# removed the redundant back-to-back s_setprio 0 / s_setprio 1 pairs in the middle of each 32-MFMA segment of every GEMM K-loop
# baseline (speedup 1.0000x reference)
; #define PG8_STAGE(bufoff, gbase, voff) do { _Pragma("unroll") for (int _i = 0; _i < 2; ++_i) \
;         __builtin_amdgcn_global_load_lds((const unsigned*)((const char*)(gbase) + (voff)[_i]), (LAS unsigned*)(lds + (bufoff) + ldsw + _i * 8192), 16, 0, 0); } while (0)
; #define PG8_LDA(dst, b, h) do { _Pragma("unroll") for (int m = 0; m < 4; ++m) _Pragma("unroll") for (int k = 0; k < 2; ++k) dst[m][k] = *(const LAS bf16x8*)(lds + PG8_SA(b, h) + aoff + m * 2048 + k * 1024); } while (0)
; #define PG8_LDB(dst, b, h) do { _Pragma("unroll") for (int n = 0; n < 2; ++n) _Pragma("unroll") for (int k = 0; k < 2; ++k) dst[n][k] = *(const LAS bf16x8*)(lds + PG8_SB(b, h) + boff + n * 2048 + k * 1024); } while (0)
; #define PG8_WAIT_V(n) asm volatile("s_waitcnt vmcnt(" #n ")" ::: "memory")
; #define PG8_WAIT_L(n) asm volatile("s_waitcnt lgkmcnt(" #n ")" ::: "memory")
; template <class Epi, class Sched>
; __device__ __forceinline__ void gemm_phase(LAS unsigned char* lds, const Gemm g, const Sched& S, const Epi& E) {
;     ...
;         for (int t = 0; t < nt; t += 2) {
;             const bool last = (t == nt - 2);
;             const char* a1 = cA + (size_t)(t + 1) * kstepA;
;             const char* a2 = last ? nA : cA + (size_t)(t + 2) * kstepA; const char* b2 = last ? nB : cB + (size_t)(t + 2) * kstep;
;             const char* a3 = a2 + kstepA; const char* b3 = b2 + kstep;
;             PG8_LDB(B0, 0, 0); PG8_LDB(B1, 0, 1); PG8_SCHED; PG8_LDA(At, 0, 0); PG8_STAGE(PG8_SA(1, 1), a1 + hA, voffA);
;             PG8_WAIT_V(8); PG8_WAIT_L(0); PG8_BAR; PG8_MMA(0, 0, At, B0); PG8_MMA(0, 1, At, B1); PG8_BAR; PG8_SCHED;
;             PG8_LDA(At, 0, 1); PG8_STAGE(PG8_SB(0, 0), b2, voffB); PG8_STAGE(PG8_SB(0, 1), b2 + hB, voffB); PG8_STAGE(PG8_SA(0, 0), a2, voffA);
;             PG8_WAIT_V(8); PG8_WAIT_L(0); PG8_BAR; PG8_MMA(1, 0, At, B0); PG8_MMA(1, 1, At, B1); PG8_BAR; PG8_SCHED;
;             PG8_LDB(B0, 1, 0); PG8_LDB(B1, 1, 1); PG8_SCHED; PG8_LDA(At, 1, 0); PG8_STAGE(PG8_SA(0, 1), a2 + hA, voffA);
;             PG8_WAIT_V(8); PG8_WAIT_L(0); PG8_BAR; PG8_MMA(0, 0, At, B0); PG8_MMA(0, 1, At, B1); PG8_BAR; PG8_SCHED;
;             PG8_LDA(At, 1, 1); PG8_STAGE(PG8_SB(1, 0), b3, voffB); PG8_STAGE(PG8_SB(1, 1), b3 + hB, voffB); PG8_STAGE(PG8_SA(1, 0), a3, voffA);
;             PG8_WAIT_V(8); PG8_WAIT_L(0); PG8_BAR; PG8_MMA(1, 0, At, B0); PG8_MMA(1, 1, At, B1); PG8_BAR; PG8_SCHED;
.LBB0_117:
	ds_read_b128 v[154:157], v150
	ds_read_b128 v[158:161], v150 offset:1024
	ds_read_b128 v[162:165], v150 offset:2048
	ds_read_b128 v[166:169], v150 offset:3072
	ds_read_b128 v[170:173], v151
	ds_read_b128 v[174:177], v151 offset:1024
	ds_read_b128 v[178:181], v151 offset:2048
	ds_read_b128 v[182:185], v151 offset:3072
	s_add_u32 s26, s24, 0xfff80080
	s_addc_u32 s27, s25, -1
	s_cmp_eq_u32 s55, 28
	s_cselect_b32 s29, s19, s27
	s_cselect_b32 s28, s46, s26
	s_cselect_b32 s27, s17, s49
	s_cselect_b32 s26, s47, s48
	v_lshl_add_u64 v[218:219], s[24:25], 0, v[140:141]
	s_add_i32 m0, s15, 0xc000
	ds_read_b128 v[186:189], v152
	ds_read_b128 v[190:193], v152 offset:1024
	ds_read_b128 v[194:197], v152 offset:2048
	ds_read_b128 v[198:201], v152 offset:3072
	ds_read_b128 v[202:205], v152 offset:4096
	ds_read_b128 v[206:209], v152 offset:5120
	ds_read_b128 v[210:213], v152 offset:6144
	ds_read_b128 v[214:217], v152 offset:7168
	global_load_lds_dwordx4 v[218:219], off
	v_lshl_add_u64 v[218:219], s[24:25], 0, v[142:143]
	s_add_i32 m0, s15, 0xe000
	s_nop 0
	global_load_lds_dwordx4 v[218:219], off
	s_waitcnt vmcnt(8)
	s_waitcnt lgkmcnt(0)
	s_barrier
	s_setprio 1
	s_waitcnt lgkmcnt(0)
	v_mfma_f32_16x16x32_bf16 v[128:131], v[154:157], v[186:189], v[128:131]
	v_mfma_f32_16x16x32_bf16 v[124:127], v[162:165], v[186:189], v[124:127]
	v_mfma_f32_16x16x32_bf16 v[112:115], v[154:157], v[194:197], v[112:115]
	v_mfma_f32_16x16x32_bf16 v[108:111], v[162:165], v[194:197], v[108:111]
	v_mfma_f32_16x16x32_bf16 v[96:99], v[154:157], v[202:205], v[96:99]
	v_mfma_f32_16x16x32_bf16 v[92:95], v[162:165], v[202:205], v[92:95]
	v_mfma_f32_16x16x32_bf16 v[80:83], v[154:157], v[210:213], v[80:83]
	v_mfma_f32_16x16x32_bf16 v[76:79], v[162:165], v[210:213], v[76:79]
	v_mfma_f32_16x16x32_bf16 v[128:131], v[158:161], v[190:193], v[128:131]
	v_mfma_f32_16x16x32_bf16 v[124:127], v[166:169], v[190:193], v[124:127]
	v_mfma_f32_16x16x32_bf16 v[112:115], v[158:161], v[198:201], v[112:115]
	v_mfma_f32_16x16x32_bf16 v[108:111], v[166:169], v[198:201], v[108:111]
	v_mfma_f32_16x16x32_bf16 v[96:99], v[158:161], v[206:209], v[96:99]
	v_mfma_f32_16x16x32_bf16 v[92:95], v[166:169], v[206:209], v[92:95]
	v_mfma_f32_16x16x32_bf16 v[80:83], v[158:161], v[214:217], v[80:83]
	v_mfma_f32_16x16x32_bf16 v[76:79], v[166:169], v[214:217], v[76:79]
	v_mfma_f32_16x16x32_bf16 v[120:123], v[170:173], v[186:189], v[120:123]
	v_mfma_f32_16x16x32_bf16 v[116:119], v[178:181], v[186:189], v[116:119]
	v_mfma_f32_16x16x32_bf16 v[104:107], v[170:173], v[194:197], v[104:107]
	v_mfma_f32_16x16x32_bf16 v[100:103], v[178:181], v[194:197], v[100:103]
	v_mfma_f32_16x16x32_bf16 v[88:91], v[170:173], v[202:205], v[88:91]
	v_mfma_f32_16x16x32_bf16 v[84:87], v[178:181], v[202:205], v[84:87]
	v_mfma_f32_16x16x32_bf16 v[72:75], v[170:173], v[210:213], v[72:75]
	v_mfma_f32_16x16x32_bf16 v[68:71], v[178:181], v[210:213], v[68:71]
	v_mfma_f32_16x16x32_bf16 v[120:123], v[174:177], v[190:193], v[120:123]
	v_mfma_f32_16x16x32_bf16 v[116:119], v[182:185], v[190:193], v[116:119]
	v_mfma_f32_16x16x32_bf16 v[104:107], v[174:177], v[198:201], v[104:107]
	v_mfma_f32_16x16x32_bf16 v[100:103], v[182:185], v[198:201], v[100:103]
	v_mfma_f32_16x16x32_bf16 v[88:91], v[174:177], v[206:209], v[88:91]
	v_mfma_f32_16x16x32_bf16 v[84:87], v[182:185], v[206:209], v[84:87]
	v_mfma_f32_16x16x32_bf16 v[72:75], v[174:177], v[214:217], v[72:75]
	v_mfma_f32_16x16x32_bf16 v[68:71], v[182:185], v[214:217], v[68:71]
	s_setprio 0
	s_barrier
	s_add_i32 s56, s43, s31
	v_lshl_add_u64 v[218:219], s[26:27], 0, v[134:135]
	s_mov_b32 m0, s56
	ds_read_b128 v[186:189], v152 offset:16384
	ds_read_b128 v[190:193], v152 offset:17408
	ds_read_b128 v[194:197], v152 offset:18432
	ds_read_b128 v[198:201], v152 offset:19456
	ds_read_b128 v[202:205], v152 offset:20480
	ds_read_b128 v[206:209], v152 offset:21504
	ds_read_b128 v[210:213], v152 offset:22528
	ds_read_b128 v[214:217], v152 offset:23552
	global_load_lds_dwordx4 v[218:219], off
	s_add_i32 m0, s56, 0x2000
	s_add_u32 s56, s26, 0x20000
	v_lshl_add_u64 v[220:221], s[26:27], 0, v[138:139]
	s_addc_u32 s57, s27, 0
	s_add_i32 s58, s44, s31
	global_load_lds_dwordx4 v[220:221], off
	v_lshl_add_u64 v[222:223], s[56:57], 0, v[134:135]
	s_mov_b32 m0, s58
	v_lshl_add_u64 v[224:225], s[28:29], 0, v[136:137]
	global_load_lds_dwordx4 v[222:223], off
	v_lshl_add_u64 v[222:223], s[56:57], 0, v[138:139]
	s_add_i32 m0, s58, 0x2000
	s_nop 0
	global_load_lds_dwordx4 v[222:223], off
	v_lshl_add_u64 v[222:223], s[28:29], 0, v[132:133]
	s_mov_b32 m0, s15
	s_nop 0
	global_load_lds_dwordx4 v[222:223], off
	s_mov_b32 m0, s36
	s_nop 0
	global_load_lds_dwordx4 v[224:225], off
	s_waitcnt vmcnt(8)
	s_waitcnt lgkmcnt(0)
	s_barrier
; #define PG8_STAGE(bufoff, gbase, voff) do { _Pragma("unroll") for (int _i = 0; _i < 2; ++_i) \
;         __builtin_amdgcn_global_load_lds((const unsigned*)((const char*)(gbase) + (voff)[_i]), (LAS unsigned*)(lds + (bufoff) + ldsw + _i * 8192), 16, 0, 0); } while (0)
; #define PG8_LDA(dst, b, h) do { _Pragma("unroll") for (int m = 0; m < 4; ++m) _Pragma("unroll") for (int k = 0; k < 2; ++k) dst[m][k] = *(const LAS bf16x8*)(lds + PG8_SA(b, h) + aoff + m * 2048 + k * 1024); } while (0)
; #define PG8_LDB(dst, b, h) do { _Pragma("unroll") for (int n = 0; n < 2; ++n) _Pragma("unroll") for (int k = 0; k < 2; ++k) dst[n][k] = *(const LAS bf16x8*)(lds + PG8_SB(b, h) + boff + n * 2048 + k * 1024); } while (0)
; #define PG8_WAIT_V(n) asm volatile("s_waitcnt vmcnt(" #n ")" ::: "memory")
; #define PG8_WAIT_L(n) asm volatile("s_waitcnt lgkmcnt(" #n ")" ::: "memory")
; template <class Epi, class Sched>
; __device__ __forceinline__ void gemm_phase(LAS unsigned char* lds, const Gemm g, const Sched& S, const Epi& E) {
;     ...
;         for (int t = 0; t < nt; t += 2) {
;             const bool last = (t == nt - 2);
;             const char* a1 = cA + (size_t)(t + 1) * kstepA;
;             const char* a2 = last ? nA : cA + (size_t)(t + 2) * kstepA; const char* b2 = last ? nB : cB + (size_t)(t + 2) * kstep;
;             const char* a3 = a2 + kstepA; const char* b3 = b2 + kstep;
;             PG8_LDB(B0, 0, 0); PG8_LDB(B1, 0, 1); PG8_SCHED; PG8_LDA(At, 0, 0); PG8_STAGE(PG8_SA(1, 1), a1 + hA, voffA);
;             PG8_WAIT_V(8); PG8_WAIT_L(0); PG8_BAR; PG8_MMA(0, 0, At, B0); PG8_MMA(0, 1, At, B1); PG8_BAR; PG8_SCHED;
;             PG8_LDA(At, 0, 1); PG8_STAGE(PG8_SB(0, 0), b2, voffB); PG8_STAGE(PG8_SB(0, 1), b2 + hB, voffB); PG8_STAGE(PG8_SA(0, 0), a2, voffA);
;             PG8_WAIT_V(8); PG8_WAIT_L(0); PG8_BAR; PG8_MMA(1, 0, At, B0); PG8_MMA(1, 1, At, B1); PG8_BAR; PG8_SCHED;
;             PG8_LDB(B0, 1, 0); PG8_LDB(B1, 1, 1); PG8_SCHED; PG8_LDA(At, 1, 0); PG8_STAGE(PG8_SA(0, 1), a2 + hA, voffA);
;             PG8_WAIT_V(8); PG8_WAIT_L(0); PG8_BAR; PG8_MMA(0, 0, At, B0); PG8_MMA(0, 1, At, B1); PG8_BAR; PG8_SCHED;
;             PG8_LDA(At, 1, 1); PG8_STAGE(PG8_SB(1, 0), b3, voffB); PG8_STAGE(PG8_SB(1, 1), b3 + hB, voffB); PG8_STAGE(PG8_SA(1, 0), a3, voffA);
;             PG8_WAIT_V(8); PG8_WAIT_L(0); PG8_BAR; PG8_MMA(1, 0, At, B0); PG8_MMA(1, 1, At, B1); PG8_BAR; PG8_SCHED;
	s_setprio 1
	s_waitcnt lgkmcnt(0)
	v_mfma_f32_16x16x32_bf16 v[64:67], v[154:157], v[186:189], v[64:67]
	v_mfma_f32_16x16x32_bf16 v[60:63], v[162:165], v[186:189], v[60:63]
	v_mfma_f32_16x16x32_bf16 v[52:55], v[154:157], v[194:197], v[52:55]
	v_mfma_f32_16x16x32_bf16 v[44:47], v[162:165], v[194:197], v[44:47]
	v_mfma_f32_16x16x32_bf16 v[36:39], v[154:157], v[202:205], v[36:39]
	v_mfma_f32_16x16x32_bf16 v[28:31], v[162:165], v[202:205], v[28:31]
	v_mfma_f32_16x16x32_bf16 v[20:23], v[154:157], v[210:213], v[20:23]
	v_mfma_f32_16x16x32_bf16 v[12:15], v[162:165], v[210:213], v[12:15]
	v_mfma_f32_16x16x32_bf16 v[64:67], v[158:161], v[190:193], v[64:67]
	v_mfma_f32_16x16x32_bf16 v[60:63], v[166:169], v[190:193], v[60:63]
	v_mfma_f32_16x16x32_bf16 v[52:55], v[158:161], v[198:201], v[52:55]
	v_mfma_f32_16x16x32_bf16 v[44:47], v[166:169], v[198:201], v[44:47]
	v_mfma_f32_16x16x32_bf16 v[36:39], v[158:161], v[206:209], v[36:39]
	v_mfma_f32_16x16x32_bf16 v[28:31], v[166:169], v[206:209], v[28:31]
	v_mfma_f32_16x16x32_bf16 v[20:23], v[158:161], v[214:217], v[20:23]
	v_mfma_f32_16x16x32_bf16 v[12:15], v[166:169], v[214:217], v[12:15]
	v_mfma_f32_16x16x32_bf16 v[56:59], v[170:173], v[186:189], v[56:59]
	v_mfma_f32_16x16x32_bf16 v[48:51], v[178:181], v[186:189], v[48:51]
	v_mfma_f32_16x16x32_bf16 v[40:43], v[170:173], v[194:197], v[40:43]
	v_mfma_f32_16x16x32_bf16 v[32:35], v[178:181], v[194:197], v[32:35]
	v_mfma_f32_16x16x32_bf16 v[24:27], v[170:173], v[202:205], v[24:27]
	v_mfma_f32_16x16x32_bf16 v[16:19], v[178:181], v[202:205], v[16:19]
	v_mfma_f32_16x16x32_bf16 v[8:11], v[170:173], v[210:213], v[8:11]
	v_mfma_f32_16x16x32_bf16 v[4:7], v[178:181], v[210:213], v[4:7]
	v_mfma_f32_16x16x32_bf16 v[56:59], v[174:177], v[190:193], v[56:59]
	v_mfma_f32_16x16x32_bf16 v[48:51], v[182:185], v[190:193], v[48:51]
	v_mfma_f32_16x16x32_bf16 v[40:43], v[174:177], v[198:201], v[40:43]
	v_mfma_f32_16x16x32_bf16 v[32:35], v[182:185], v[198:201], v[32:35]
	v_mfma_f32_16x16x32_bf16 v[24:27], v[174:177], v[206:209], v[24:27]
	v_mfma_f32_16x16x32_bf16 v[16:19], v[182:185], v[206:209], v[16:19]
	v_mfma_f32_16x16x32_bf16 v[8:11], v[174:177], v[214:217], v[8:11]
	v_mfma_f32_16x16x32_bf16 v[4:7], v[182:185], v[214:217], v[4:7]
	s_setprio 0
	s_barrier
	s_add_i32 s56, 0, 0x18000
	v_add_u32_e32 v3, s56, v148
	s_add_i32 s57, 0, 0x1c000
	ds_read_b128 v[154:157], v3
	ds_read_b128 v[158:161], v3 offset:1024
	ds_read_b128 v[162:165], v3 offset:2048
	ds_read_b128 v[166:169], v3 offset:3072
	v_add_u32_e32 v3, s57, v148
	ds_read_b128 v[170:173], v3
	ds_read_b128 v[174:177], v3 offset:1024
	ds_read_b128 v[178:181], v3 offset:2048
	ds_read_b128 v[182:185], v3 offset:3072
	s_add_u32 s28, s28, 0x80000
	s_addc_u32 s29, s29, 0
	s_mov_b32 m0, s37
	v_lshl_add_u64 v[226:227], s[28:29], 0, v[132:133]
	ds_read_b128 v[186:189], v152 offset:32768
	ds_read_b128 v[190:193], v152 offset:33792
	ds_read_b128 v[194:197], v152 offset:34816
	ds_read_b128 v[198:201], v152 offset:35840
	ds_read_b128 v[202:205], v152 offset:36864
	ds_read_b128 v[206:209], v152 offset:37888
	ds_read_b128 v[210:213], v152 offset:38912
	ds_read_b128 v[214:217], v152 offset:39936
	global_load_lds_dwordx4 v[226:227], off
	v_lshl_add_u64 v[226:227], s[28:29], 0, v[136:137]
	s_mov_b32 m0, s38
	s_nop 0
	global_load_lds_dwordx4 v[226:227], off
	s_waitcnt vmcnt(8)
	s_waitcnt lgkmcnt(0)
	s_barrier
	s_setprio 1
	s_waitcnt lgkmcnt(0)
	v_mfma_f32_16x16x32_bf16 v[128:131], v[154:157], v[186:189], v[128:131]
	v_mfma_f32_16x16x32_bf16 v[124:127], v[162:165], v[186:189], v[124:127]
	v_mfma_f32_16x16x32_bf16 v[112:115], v[154:157], v[194:197], v[112:115]
	v_mfma_f32_16x16x32_bf16 v[108:111], v[162:165], v[194:197], v[108:111]
	v_mfma_f32_16x16x32_bf16 v[96:99], v[154:157], v[202:205], v[96:99]
	v_mfma_f32_16x16x32_bf16 v[92:95], v[162:165], v[202:205], v[92:95]
	v_mfma_f32_16x16x32_bf16 v[80:83], v[154:157], v[210:213], v[80:83]
	v_mfma_f32_16x16x32_bf16 v[76:79], v[162:165], v[210:213], v[76:79]
	v_mfma_f32_16x16x32_bf16 v[128:131], v[158:161], v[190:193], v[128:131]
	v_mfma_f32_16x16x32_bf16 v[124:127], v[166:169], v[190:193], v[124:127]
	v_mfma_f32_16x16x32_bf16 v[112:115], v[158:161], v[198:201], v[112:115]
	v_mfma_f32_16x16x32_bf16 v[108:111], v[166:169], v[198:201], v[108:111]
	v_mfma_f32_16x16x32_bf16 v[96:99], v[158:161], v[206:209], v[96:99]
	v_mfma_f32_16x16x32_bf16 v[92:95], v[166:169], v[206:209], v[92:95]
	v_mfma_f32_16x16x32_bf16 v[80:83], v[158:161], v[214:217], v[80:83]
	v_mfma_f32_16x16x32_bf16 v[76:79], v[166:169], v[214:217], v[76:79]
	v_mfma_f32_16x16x32_bf16 v[120:123], v[170:173], v[186:189], v[120:123]
	v_mfma_f32_16x16x32_bf16 v[116:119], v[178:181], v[186:189], v[116:119]
	v_mfma_f32_16x16x32_bf16 v[104:107], v[170:173], v[194:197], v[104:107]
	v_mfma_f32_16x16x32_bf16 v[100:103], v[178:181], v[194:197], v[100:103]
	v_mfma_f32_16x16x32_bf16 v[88:91], v[170:173], v[202:205], v[88:91]
	v_mfma_f32_16x16x32_bf16 v[84:87], v[178:181], v[202:205], v[84:87]
	v_mfma_f32_16x16x32_bf16 v[72:75], v[170:173], v[210:213], v[72:75]
	v_mfma_f32_16x16x32_bf16 v[68:71], v[178:181], v[210:213], v[68:71]
	v_mfma_f32_16x16x32_bf16 v[120:123], v[174:177], v[190:193], v[120:123]
	v_mfma_f32_16x16x32_bf16 v[116:119], v[182:185], v[190:193], v[116:119]
	v_mfma_f32_16x16x32_bf16 v[104:107], v[174:177], v[198:201], v[104:107]
	v_mfma_f32_16x16x32_bf16 v[100:103], v[182:185], v[198:201], v[100:103]
	v_mfma_f32_16x16x32_bf16 v[88:91], v[174:177], v[206:209], v[88:91]
	v_mfma_f32_16x16x32_bf16 v[84:87], v[182:185], v[206:209], v[84:87]
	v_mfma_f32_16x16x32_bf16 v[72:75], v[174:177], v[214:217], v[72:75]
	v_mfma_f32_16x16x32_bf16 v[68:71], v[182:185], v[214:217], v[68:71]
	s_setprio 0
	s_barrier
; #define PG8_STAGE(bufoff, gbase, voff) do { _Pragma("unroll") for (int _i = 0; _i < 2; ++_i) \
;         __builtin_amdgcn_global_load_lds((const unsigned*)((const char*)(gbase) + (voff)[_i]), (LAS unsigned*)(lds + (bufoff) + ldsw + _i * 8192), 16, 0, 0); } while (0)
; #define PG8_LDA(dst, b, h) do { _Pragma("unroll") for (int m = 0; m < 4; ++m) _Pragma("unroll") for (int k = 0; k < 2; ++k) dst[m][k] = *(const LAS bf16x8*)(lds + PG8_SA(b, h) + aoff + m * 2048 + k * 1024); } while (0)
; #define PG8_LDB(dst, b, h) do { _Pragma("unroll") for (int n = 0; n < 2; ++n) _Pragma("unroll") for (int k = 0; k < 2; ++k) dst[n][k] = *(const LAS bf16x8*)(lds + PG8_SB(b, h) + boff + n * 2048 + k * 1024); } while (0)
; #define PG8_WAIT_V(n) asm volatile("s_waitcnt vmcnt(" #n ")" ::: "memory")
; template <class Epi, class Sched>
; __device__ __forceinline__ void gemm_phase(LAS unsigned char* lds, const Gemm g, const Sched& S, const Epi& E) {
;     ...
;         for (int t = 0; t < nt; t += 2) {
;             const bool last = (t == nt - 2);
;             const char* a1 = cA + (size_t)(t + 1) * kstepA;
;             const char* a2 = last ? nA : cA + (size_t)(t + 2) * kstepA; const char* b2 = last ? nB : cB + (size_t)(t + 2) * kstep;
;             const char* a3 = a2 + kstepA; const char* b3 = b2 + kstep;
;             PG8_LDB(B0, 0, 0); PG8_LDB(B1, 0, 1); PG8_SCHED; PG8_LDA(At, 0, 0); PG8_STAGE(PG8_SA(1, 1), a1 + hA, voffA);
;             PG8_WAIT_V(8); PG8_WAIT_L(0); PG8_BAR; PG8_MMA(0, 0, At, B0); PG8_MMA(0, 1, At, B1); PG8_BAR; PG8_SCHED;
;             PG8_LDA(At, 0, 1); PG8_STAGE(PG8_SB(0, 0), b2, voffB); PG8_STAGE(PG8_SB(0, 1), b2 + hB, voffB); PG8_STAGE(PG8_SA(0, 0), a2, voffA);
;             PG8_WAIT_V(8); PG8_WAIT_L(0); PG8_BAR; PG8_MMA(1, 0, At, B0); PG8_MMA(1, 1, At, B1); PG8_BAR; PG8_SCHED;
;             PG8_LDB(B0, 1, 0); PG8_LDB(B1, 1, 1); PG8_SCHED; PG8_LDA(At, 1, 0); PG8_STAGE(PG8_SA(0, 1), a2 + hA, voffA);
;             PG8_WAIT_V(8); PG8_WAIT_L(0); PG8_BAR; PG8_MMA(0, 0, At, B0); PG8_MMA(0, 1, At, B1); PG8_BAR; PG8_SCHED;
;             PG8_LDA(At, 1, 1); PG8_STAGE(PG8_SB(1, 0), b3, voffB); PG8_STAGE(PG8_SB(1, 1), b3 + hB, voffB); PG8_STAGE(PG8_SA(1, 0), a3, voffA);
;             PG8_WAIT_V(8); PG8_WAIT_L(0); PG8_BAR; PG8_MMA(1, 0, At, B0); PG8_MMA(1, 1, At, B1); PG8_BAR; PG8_SCHED;
;         }
;         if (wr == 0) PG8_BAR;
	s_add_i32 s28, s56, s31
	v_lshl_add_u64 v[218:219], v[218:219], 0, s[8:9]
	s_mov_b32 m0, s28
	ds_read_b128 v[186:189], v152 offset:49152
	ds_read_b128 v[190:193], v152 offset:50176
	ds_read_b128 v[194:197], v152 offset:51200
	ds_read_b128 v[198:201], v152 offset:52224
	ds_read_b128 v[202:205], v152 offset:53248
	ds_read_b128 v[206:209], v152 offset:54272
	ds_read_b128 v[210:213], v152 offset:55296
	ds_read_b128 v[214:217], v152 offset:56320
	global_load_lds_dwordx4 v[218:219], off
	s_add_i32 m0, s28, 0x2000
	s_add_u32 s26, s26, 0x20080
	v_lshl_add_u64 v[218:219], v[220:221], 0, s[8:9]
	s_addc_u32 s27, s27, 0
	s_add_i32 s28, s57, s31
	global_load_lds_dwordx4 v[218:219], off
	v_lshl_add_u64 v[218:219], s[26:27], 0, v[134:135]
	s_mov_b32 m0, s28
	s_nop 0
	global_load_lds_dwordx4 v[218:219], off
	v_lshl_add_u64 v[218:219], s[26:27], 0, v[138:139]
	s_add_i32 m0, s28, 0x2000
	s_nop 0
	global_load_lds_dwordx4 v[218:219], off
	v_lshl_add_u64 v[218:219], v[222:223], 0, s[8:9]
	s_mov_b32 m0, s39
	s_nop 0
	global_load_lds_dwordx4 v[218:219], off
	v_lshl_add_u64 v[218:219], v[224:225], 0, s[8:9]
	s_mov_b32 m0, s40
	s_nop 0
	global_load_lds_dwordx4 v[218:219], off
	s_waitcnt vmcnt(8)
	s_waitcnt lgkmcnt(0)
	s_barrier
	s_setprio 1
	s_waitcnt lgkmcnt(0)
	v_mfma_f32_16x16x32_bf16 v[64:67], v[154:157], v[186:189], v[64:67]
	v_mfma_f32_16x16x32_bf16 v[60:63], v[162:165], v[186:189], v[60:63]
	v_mfma_f32_16x16x32_bf16 v[52:55], v[154:157], v[194:197], v[52:55]
	v_mfma_f32_16x16x32_bf16 v[44:47], v[162:165], v[194:197], v[44:47]
	v_mfma_f32_16x16x32_bf16 v[36:39], v[154:157], v[202:205], v[36:39]
	v_mfma_f32_16x16x32_bf16 v[28:31], v[162:165], v[202:205], v[28:31]
	v_mfma_f32_16x16x32_bf16 v[20:23], v[154:157], v[210:213], v[20:23]
	v_mfma_f32_16x16x32_bf16 v[12:15], v[162:165], v[210:213], v[12:15]
	v_mfma_f32_16x16x32_bf16 v[64:67], v[158:161], v[190:193], v[64:67]
	v_mfma_f32_16x16x32_bf16 v[60:63], v[166:169], v[190:193], v[60:63]
	v_mfma_f32_16x16x32_bf16 v[52:55], v[158:161], v[198:201], v[52:55]
	v_mfma_f32_16x16x32_bf16 v[44:47], v[166:169], v[198:201], v[44:47]
	v_mfma_f32_16x16x32_bf16 v[36:39], v[158:161], v[206:209], v[36:39]
	v_mfma_f32_16x16x32_bf16 v[28:31], v[166:169], v[206:209], v[28:31]
	v_mfma_f32_16x16x32_bf16 v[20:23], v[158:161], v[214:217], v[20:23]
	v_mfma_f32_16x16x32_bf16 v[12:15], v[166:169], v[214:217], v[12:15]
	v_mfma_f32_16x16x32_bf16 v[56:59], v[170:173], v[186:189], v[56:59]
	v_mfma_f32_16x16x32_bf16 v[48:51], v[178:181], v[186:189], v[48:51]
	v_mfma_f32_16x16x32_bf16 v[40:43], v[170:173], v[194:197], v[40:43]
	v_mfma_f32_16x16x32_bf16 v[32:35], v[178:181], v[194:197], v[32:35]
	v_mfma_f32_16x16x32_bf16 v[24:27], v[170:173], v[202:205], v[24:27]
	v_mfma_f32_16x16x32_bf16 v[16:19], v[178:181], v[202:205], v[16:19]
	v_mfma_f32_16x16x32_bf16 v[8:11], v[170:173], v[210:213], v[8:11]
	v_mfma_f32_16x16x32_bf16 v[4:7], v[178:181], v[210:213], v[4:7]
	v_mfma_f32_16x16x32_bf16 v[56:59], v[174:177], v[190:193], v[56:59]
	v_mfma_f32_16x16x32_bf16 v[48:51], v[182:185], v[190:193], v[48:51]
	v_mfma_f32_16x16x32_bf16 v[40:43], v[174:177], v[198:201], v[40:43]
	v_mfma_f32_16x16x32_bf16 v[32:35], v[182:185], v[198:201], v[32:35]
	v_mfma_f32_16x16x32_bf16 v[24:27], v[174:177], v[206:209], v[24:27]
	v_mfma_f32_16x16x32_bf16 v[16:19], v[182:185], v[206:209], v[16:19]
	v_mfma_f32_16x16x32_bf16 v[8:11], v[174:177], v[214:217], v[8:11]
	v_mfma_f32_16x16x32_bf16 v[4:7], v[182:185], v[214:217], v[4:7]
	s_setprio 0
	s_barrier
	s_add_i32 s55, s55, 2
	s_add_u32 s24, s24, 0x100
	s_addc_u32 s25, s25, 0
	s_add_u32 s48, s48, 0x100
	s_addc_u32 s49, s49, 0
	s_cmp_gt_u32 s55, 29
	s_cbranch_scc0 .LBB0_117
	s_and_b64 vcc, exec, s[10:11]
	s_cbranch_vccz .LBB0_120
	s_barrier

; #define PG8_STAGE(bufoff, gbase, voff) do { _Pragma("unroll") for (int _i = 0; _i < 2; ++_i) \
;         __builtin_amdgcn_global_load_lds((const unsigned*)((const char*)(gbase) + (voff)[_i]), (LAS unsigned*)(lds + (bufoff) + ldsw + _i * 8192), 16, 0, 0); } while (0)
; #define PG8_LDA(dst, b, h) do { _Pragma("unroll") for (int m = 0; m < 4; ++m) _Pragma("unroll") for (int k = 0; k < 2; ++k) dst[m][k] = *(const LAS bf16x8*)(lds + PG8_SA(b, h) + aoff + m * 2048 + k * 1024); } while (0)
; #define PG8_LDB(dst, b, h) do { _Pragma("unroll") for (int n = 0; n < 2; ++n) _Pragma("unroll") for (int k = 0; k < 2; ++k) dst[n][k] = *(const LAS bf16x8*)(lds + PG8_SB(b, h) + boff + n * 2048 + k * 1024); } while (0)
; #define PG8_WAIT_V(n) asm volatile("s_waitcnt vmcnt(" #n ")" ::: "memory")
; #define PG8_WAIT_L(n) asm volatile("s_waitcnt lgkmcnt(" #n ")" ::: "memory")
; template <class Epi, class Sched>
; __device__ __forceinline__ void gemm_phase(LAS unsigned char* lds, const Gemm g, const Sched& S, const Epi& E) {
;     ...
;         for (int t = 0; t < nt; t += 2) {
;             const bool last = (t == nt - 2);
;             const char* a1 = cA + (size_t)(t + 1) * kstepA;
;             const char* a2 = last ? nA : cA + (size_t)(t + 2) * kstepA; const char* b2 = last ? nB : cB + (size_t)(t + 2) * kstep;
;             const char* a3 = a2 + kstepA; const char* b3 = b2 + kstep;
;             PG8_LDB(B0, 0, 0); PG8_LDB(B1, 0, 1); PG8_SCHED; PG8_LDA(At, 0, 0); PG8_STAGE(PG8_SA(1, 1), a1 + hA, voffA);
;             PG8_WAIT_V(8); PG8_WAIT_L(0); PG8_BAR; PG8_MMA(0, 0, At, B0); PG8_MMA(0, 1, At, B1); PG8_BAR; PG8_SCHED;
;             PG8_LDA(At, 0, 1); PG8_STAGE(PG8_SB(0, 0), b2, voffB); PG8_STAGE(PG8_SB(0, 1), b2 + hB, voffB); PG8_STAGE(PG8_SA(0, 0), a2, voffA);
;             PG8_WAIT_V(8); PG8_WAIT_L(0); PG8_BAR; PG8_MMA(1, 0, At, B0); PG8_MMA(1, 1, At, B1); PG8_BAR; PG8_SCHED;
;             PG8_LDB(B0, 1, 0); PG8_LDB(B1, 1, 1); PG8_SCHED; PG8_LDA(At, 1, 0); PG8_STAGE(PG8_SA(0, 1), a2 + hA, voffA);
;             PG8_WAIT_V(8); PG8_WAIT_L(0); PG8_BAR; PG8_MMA(0, 0, At, B0); PG8_MMA(0, 1, At, B1); PG8_BAR; PG8_SCHED;
;             PG8_LDA(At, 1, 1); PG8_STAGE(PG8_SB(1, 0), b3, voffB); PG8_STAGE(PG8_SB(1, 1), b3 + hB, voffB); PG8_STAGE(PG8_SA(1, 0), a3, voffA);
;             PG8_WAIT_V(8); PG8_WAIT_L(0); PG8_BAR; PG8_MMA(1, 0, At, B0); PG8_MMA(1, 1, At, B1); PG8_BAR; PG8_SCHED;
.LBB0_259:
	s_add_u32 s22, s2, 0xfff80080
	s_addc_u32 s23, s3, -1
	s_add_i32 s47, 0, 0x10000
	s_cmp_eq_u32 s46, 28
	s_cselect_b32 s25, s17, s23
	s_cselect_b32 s24, s26, s22
	s_cselect_b32 s23, s15, s29
	s_cselect_b32 s22, s27, s28
	s_add_i32 s48, 0, 0x14000
	v_add_u32_e32 v62, s47, v175
	v_add_u32_e32 v98, s48, v175
	ds_read_b128 v[42:45], v62
	ds_read_b128 v[46:49], v62 offset:1024
	ds_read_b128 v[58:61], v62 offset:2048
	ds_read_b128 v[62:65], v62 offset:3072
	ds_read_b128 v[178:181], v98
	ds_read_b128 v[182:185], v98 offset:1024
	ds_read_b128 v[186:189], v98 offset:2048
	ds_read_b128 v[190:193], v98 offset:3072
	v_lshl_add_u64 v[154:155], s[2:3], 0, v[168:169]
	s_add_i32 m0, s35, 0xc000
	ds_read_b128 v[194:197], v177
	ds_read_b128 v[198:201], v177 offset:1024
	ds_read_b128 v[202:205], v177 offset:2048
	ds_read_b128 v[206:209], v177 offset:3072
	ds_read_b128 v[210:213], v177 offset:4096
	ds_read_b128 v[220:223], v177 offset:5120
	ds_read_b128 v[224:227], v177 offset:6144
	ds_read_b128 v[228:231], v177 offset:7168
	global_load_lds_dwordx4 v[154:155], off
	v_lshl_add_u64 v[154:155], s[2:3], 0, v[170:171]
	s_add_i32 m0, s35, 0xe000
	s_nop 0
	global_load_lds_dwordx4 v[154:155], off
	s_waitcnt vmcnt(8)
	s_waitcnt lgkmcnt(0)
	s_barrier
	s_setprio 1
	s_waitcnt lgkmcnt(0)
	v_mfma_f32_16x16x32_bf16 v[144:147], v[42:45], v[194:197], v[144:147]
	v_mfma_f32_16x16x32_bf16 v[140:143], v[58:61], v[194:197], v[140:143]
	v_mfma_f32_16x16x32_bf16 v[128:131], v[42:45], v[202:205], v[128:131]
	v_mfma_f32_16x16x32_bf16 v[124:127], v[58:61], v[202:205], v[124:127]
	v_mfma_f32_16x16x32_bf16 v[112:115], v[42:45], v[210:213], v[112:115]
	v_mfma_f32_16x16x32_bf16 v[108:111], v[58:61], v[210:213], v[108:111]
	v_mfma_f32_16x16x32_bf16 v[94:97], v[42:45], v[224:227], v[94:97]
	v_mfma_f32_16x16x32_bf16 v[90:93], v[58:61], v[224:227], v[90:93]
	v_mfma_f32_16x16x32_bf16 v[144:147], v[46:49], v[198:201], v[144:147]
	v_mfma_f32_16x16x32_bf16 v[140:143], v[62:65], v[198:201], v[140:143]
	v_mfma_f32_16x16x32_bf16 v[128:131], v[46:49], v[206:209], v[128:131]
	v_mfma_f32_16x16x32_bf16 v[124:127], v[62:65], v[206:209], v[124:127]
	v_mfma_f32_16x16x32_bf16 v[112:115], v[46:49], v[220:223], v[112:115]
	v_mfma_f32_16x16x32_bf16 v[108:111], v[62:65], v[220:223], v[108:111]
	v_mfma_f32_16x16x32_bf16 v[94:97], v[46:49], v[228:231], v[94:97]
	v_mfma_f32_16x16x32_bf16 v[90:93], v[62:65], v[228:231], v[90:93]
	v_mfma_f32_16x16x32_bf16 v[136:139], v[178:181], v[194:197], v[136:139]
	v_mfma_f32_16x16x32_bf16 v[132:135], v[186:189], v[194:197], v[132:135]
	v_mfma_f32_16x16x32_bf16 v[120:123], v[178:181], v[202:205], v[120:123]
	v_mfma_f32_16x16x32_bf16 v[116:119], v[186:189], v[202:205], v[116:119]
	v_mfma_f32_16x16x32_bf16 v[104:107], v[178:181], v[210:213], v[104:107]
	v_mfma_f32_16x16x32_bf16 v[100:103], v[186:189], v[210:213], v[100:103]
	v_mfma_f32_16x16x32_bf16 v[86:89], v[178:181], v[224:227], v[86:89]
	v_mfma_f32_16x16x32_bf16 v[82:85], v[186:189], v[224:227], v[82:85]
	v_mfma_f32_16x16x32_bf16 v[136:139], v[182:185], v[198:201], v[136:139]
	v_mfma_f32_16x16x32_bf16 v[132:135], v[190:193], v[198:201], v[132:135]
	v_mfma_f32_16x16x32_bf16 v[120:123], v[182:185], v[206:209], v[120:123]
	v_mfma_f32_16x16x32_bf16 v[116:119], v[190:193], v[206:209], v[116:119]
	v_mfma_f32_16x16x32_bf16 v[104:107], v[182:185], v[220:223], v[104:107]
	v_mfma_f32_16x16x32_bf16 v[100:103], v[190:193], v[220:223], v[100:103]
	v_mfma_f32_16x16x32_bf16 v[86:89], v[182:185], v[228:231], v[86:89]
	v_mfma_f32_16x16x32_bf16 v[82:85], v[190:193], v[228:231], v[82:85]
	s_setprio 0
	s_barrier
	s_add_i32 s47, s47, s34
	v_lshl_add_u64 v[154:155], s[22:23], 0, v[162:163]
	s_mov_b32 m0, s47
	ds_read_b128 v[194:197], v177 offset:16384
	ds_read_b128 v[198:201], v177 offset:17408
	ds_read_b128 v[202:205], v177 offset:18432
	ds_read_b128 v[206:209], v177 offset:19456
	ds_read_b128 v[210:213], v177 offset:20480
	ds_read_b128 v[220:223], v177 offset:21504
	ds_read_b128 v[224:227], v177 offset:22528
	ds_read_b128 v[228:231], v177 offset:23552
	global_load_lds_dwordx4 v[154:155], off
	s_add_i32 m0, s47, 0x2000
	s_add_u32 s56, s22, 0x20000
	v_lshl_add_u64 v[156:157], s[22:23], 0, v[158:159]
	s_addc_u32 s57, s23, 0
	s_add_i32 s47, s48, s34
	global_load_lds_dwordx4 v[156:157], off
	v_lshl_add_u64 v[172:173], s[56:57], 0, v[162:163]
	s_mov_b32 m0, s47
	v_lshl_add_u64 v[232:233], s[24:25], 0, v[160:161]
	global_load_lds_dwordx4 v[172:173], off
	v_lshl_add_u64 v[172:173], s[56:57], 0, v[158:159]
	s_add_i32 m0, s47, 0x2000
	s_nop 0
	global_load_lds_dwordx4 v[172:173], off
	v_lshl_add_u64 v[172:173], s[24:25], 0, v[164:165]
	s_mov_b32 m0, s35
	s_nop 0
	global_load_lds_dwordx4 v[172:173], off
	s_mov_b32 m0, s36
	s_nop 0
	global_load_lds_dwordx4 v[232:233], off
	s_waitcnt vmcnt(8)
	s_waitcnt lgkmcnt(0)
	s_barrier
; #define PG8_STAGE(bufoff, gbase, voff) do { _Pragma("unroll") for (int _i = 0; _i < 2; ++_i) \
;         __builtin_amdgcn_global_load_lds((const unsigned*)((const char*)(gbase) + (voff)[_i]), (LAS unsigned*)(lds + (bufoff) + ldsw + _i * 8192), 16, 0, 0); } while (0)
; #define PG8_LDA(dst, b, h) do { _Pragma("unroll") for (int m = 0; m < 4; ++m) _Pragma("unroll") for (int k = 0; k < 2; ++k) dst[m][k] = *(const LAS bf16x8*)(lds + PG8_SA(b, h) + aoff + m * 2048 + k * 1024); } while (0)
; #define PG8_LDB(dst, b, h) do { _Pragma("unroll") for (int n = 0; n < 2; ++n) _Pragma("unroll") for (int k = 0; k < 2; ++k) dst[n][k] = *(const LAS bf16x8*)(lds + PG8_SB(b, h) + boff + n * 2048 + k * 1024); } while (0)
; #define PG8_WAIT_V(n) asm volatile("s_waitcnt vmcnt(" #n ")" ::: "memory")
; #define PG8_WAIT_L(n) asm volatile("s_waitcnt lgkmcnt(" #n ")" ::: "memory")
; template <class Epi, class Sched>
; __device__ __forceinline__ void gemm_phase(LAS unsigned char* lds, const Gemm g, const Sched& S, const Epi& E) {
;     ...
;         for (int t = 0; t < nt; t += 2) {
;             const bool last = (t == nt - 2);
;             const char* a1 = cA + (size_t)(t + 1) * kstepA;
;             const char* a2 = last ? nA : cA + (size_t)(t + 2) * kstepA; const char* b2 = last ? nB : cB + (size_t)(t + 2) * kstep;
;             const char* a3 = a2 + kstepA; const char* b3 = b2 + kstep;
;             PG8_LDB(B0, 0, 0); PG8_LDB(B1, 0, 1); PG8_SCHED; PG8_LDA(At, 0, 0); PG8_STAGE(PG8_SA(1, 1), a1 + hA, voffA);
;             PG8_WAIT_V(8); PG8_WAIT_L(0); PG8_BAR; PG8_MMA(0, 0, At, B0); PG8_MMA(0, 1, At, B1); PG8_BAR; PG8_SCHED;
;             PG8_LDA(At, 0, 1); PG8_STAGE(PG8_SB(0, 0), b2, voffB); PG8_STAGE(PG8_SB(0, 1), b2 + hB, voffB); PG8_STAGE(PG8_SA(0, 0), a2, voffA);
;             PG8_WAIT_V(8); PG8_WAIT_L(0); PG8_BAR; PG8_MMA(1, 0, At, B0); PG8_MMA(1, 1, At, B1); PG8_BAR; PG8_SCHED;
;             PG8_LDB(B0, 1, 0); PG8_LDB(B1, 1, 1); PG8_SCHED; PG8_LDA(At, 1, 0); PG8_STAGE(PG8_SA(0, 1), a2 + hA, voffA);
;             PG8_WAIT_V(8); PG8_WAIT_L(0); PG8_BAR; PG8_MMA(0, 0, At, B0); PG8_MMA(0, 1, At, B1); PG8_BAR; PG8_SCHED;
;             PG8_LDA(At, 1, 1); PG8_STAGE(PG8_SB(1, 0), b3, voffB); PG8_STAGE(PG8_SB(1, 1), b3 + hB, voffB); PG8_STAGE(PG8_SA(1, 0), a3, voffA);
;             PG8_WAIT_V(8); PG8_WAIT_L(0); PG8_BAR; PG8_MMA(1, 0, At, B0); PG8_MMA(1, 1, At, B1); PG8_BAR; PG8_SCHED;
	s_setprio 1
	s_waitcnt lgkmcnt(0)
	v_mfma_f32_16x16x32_bf16 v[78:81], v[42:45], v[194:197], v[78:81]
	v_mfma_f32_16x16x32_bf16 v[74:77], v[58:61], v[194:197], v[74:77]
	v_mfma_f32_16x16x32_bf16 v[54:57], v[42:45], v[202:205], v[54:57]
	v_mfma_f32_16x16x32_bf16 v[50:53], v[58:61], v[202:205], v[50:53]
	v_mfma_f32_16x16x32_bf16 v[30:33], v[42:45], v[210:213], v[30:33]
	v_mfma_f32_16x16x32_bf16 v[26:29], v[58:61], v[210:213], v[26:29]
	v_mfma_f32_16x16x32_bf16 v[14:17], v[42:45], v[224:227], v[14:17]
	v_mfma_f32_16x16x32_bf16 v[10:13], v[58:61], v[224:227], v[10:13]
	v_mfma_f32_16x16x32_bf16 v[78:81], v[46:49], v[198:201], v[78:81]
	v_mfma_f32_16x16x32_bf16 v[74:77], v[62:65], v[198:201], v[74:77]
	v_mfma_f32_16x16x32_bf16 v[54:57], v[46:49], v[206:209], v[54:57]
	v_mfma_f32_16x16x32_bf16 v[50:53], v[62:65], v[206:209], v[50:53]
	v_mfma_f32_16x16x32_bf16 v[30:33], v[46:49], v[220:223], v[30:33]
	v_mfma_f32_16x16x32_bf16 v[26:29], v[62:65], v[220:223], v[26:29]
	v_mfma_f32_16x16x32_bf16 v[14:17], v[46:49], v[228:231], v[14:17]
	v_mfma_f32_16x16x32_bf16 v[10:13], v[62:65], v[228:231], v[10:13]
	v_mfma_f32_16x16x32_bf16 v[38:41], v[178:181], v[202:205], v[38:41]
	v_mfma_f32_16x16x32_bf16 v[34:37], v[186:189], v[202:205], v[34:37]
	v_mfma_f32_16x16x32_bf16 v[22:25], v[178:181], v[210:213], v[22:25]
	v_mfma_f32_16x16x32_bf16 v[18:21], v[186:189], v[210:213], v[18:21]
	v_mfma_f32_16x16x32_bf16 v[6:9], v[178:181], v[224:227], v[6:9]
	v_mfma_f32_16x16x32_bf16 v[2:5], v[186:189], v[224:227], v[2:5]
	v_mfma_f32_16x16x32_bf16 v[42:45], v[178:181], v[194:197], v[70:73]
	v_mfma_f32_16x16x32_bf16 v[46:49], v[186:189], v[194:197], v[66:69]
	v_mfma_f32_16x16x32_bf16 v[38:41], v[182:185], v[206:209], v[38:41]
	v_mfma_f32_16x16x32_bf16 v[34:37], v[190:193], v[206:209], v[34:37]
	v_mfma_f32_16x16x32_bf16 v[22:25], v[182:185], v[220:223], v[22:25]
	v_mfma_f32_16x16x32_bf16 v[18:21], v[190:193], v[220:223], v[18:21]
	v_mfma_f32_16x16x32_bf16 v[6:9], v[182:185], v[228:231], v[6:9]
	v_mfma_f32_16x16x32_bf16 v[2:5], v[190:193], v[228:231], v[2:5]
	v_mfma_f32_16x16x32_bf16 v[42:45], v[182:185], v[198:201], v[42:45]
	v_mfma_f32_16x16x32_bf16 v[46:49], v[190:193], v[198:201], v[46:49]
	s_setprio 0
	s_barrier
	s_add_i32 s47, 0, 0x18000
	s_add_i32 s48, 0, 0x1c000
	v_add_u32_e32 v70, s47, v175
	v_add_u32_e32 v98, s48, v175
	ds_read_b128 v[58:61], v70
	ds_read_b128 v[62:65], v70 offset:1024
	ds_read_b128 v[66:69], v70 offset:2048
	ds_read_b128 v[70:73], v70 offset:3072
	ds_read_b128 v[178:181], v98
	ds_read_b128 v[182:185], v98 offset:1024
	ds_read_b128 v[186:189], v98 offset:2048
	ds_read_b128 v[190:193], v98 offset:3072
	s_add_u32 s24, s24, 0x80000
	s_addc_u32 s25, s25, 0
	s_mov_b32 m0, s37
	v_lshl_add_u64 v[234:235], s[24:25], 0, v[164:165]
	ds_read_b128 v[194:197], v177 offset:32768
	ds_read_b128 v[198:201], v177 offset:33792
	ds_read_b128 v[202:205], v177 offset:34816
	ds_read_b128 v[206:209], v177 offset:35840
	ds_read_b128 v[210:213], v177 offset:36864
	ds_read_b128 v[220:223], v177 offset:37888
	ds_read_b128 v[224:227], v177 offset:38912
	ds_read_b128 v[228:231], v177 offset:39936
	global_load_lds_dwordx4 v[234:235], off
	v_lshl_add_u64 v[234:235], s[24:25], 0, v[160:161]
	s_mov_b32 m0, s38
	s_nop 0
	global_load_lds_dwordx4 v[234:235], off
	s_waitcnt vmcnt(8)
	s_waitcnt lgkmcnt(0)
	s_barrier
	s_setprio 1
	s_waitcnt lgkmcnt(0)
	v_mfma_f32_16x16x32_bf16 v[144:147], v[58:61], v[194:197], v[144:147]
	v_mfma_f32_16x16x32_bf16 v[140:143], v[66:69], v[194:197], v[140:143]
	v_mfma_f32_16x16x32_bf16 v[128:131], v[58:61], v[202:205], v[128:131]
	v_mfma_f32_16x16x32_bf16 v[124:127], v[66:69], v[202:205], v[124:127]
	v_mfma_f32_16x16x32_bf16 v[112:115], v[58:61], v[210:213], v[112:115]
	v_mfma_f32_16x16x32_bf16 v[108:111], v[66:69], v[210:213], v[108:111]
	v_mfma_f32_16x16x32_bf16 v[94:97], v[58:61], v[224:227], v[94:97]
	v_mfma_f32_16x16x32_bf16 v[90:93], v[66:69], v[224:227], v[90:93]
	v_mfma_f32_16x16x32_bf16 v[144:147], v[62:65], v[198:201], v[144:147]
	v_mfma_f32_16x16x32_bf16 v[140:143], v[70:73], v[198:201], v[140:143]
	v_mfma_f32_16x16x32_bf16 v[128:131], v[62:65], v[206:209], v[128:131]
	v_mfma_f32_16x16x32_bf16 v[124:127], v[70:73], v[206:209], v[124:127]
	v_mfma_f32_16x16x32_bf16 v[112:115], v[62:65], v[220:223], v[112:115]
	v_mfma_f32_16x16x32_bf16 v[108:111], v[70:73], v[220:223], v[108:111]
	v_mfma_f32_16x16x32_bf16 v[94:97], v[62:65], v[228:231], v[94:97]
	v_mfma_f32_16x16x32_bf16 v[90:93], v[70:73], v[228:231], v[90:93]
	v_mfma_f32_16x16x32_bf16 v[136:139], v[178:181], v[194:197], v[136:139]
	v_mfma_f32_16x16x32_bf16 v[132:135], v[186:189], v[194:197], v[132:135]
	v_mfma_f32_16x16x32_bf16 v[120:123], v[178:181], v[202:205], v[120:123]
	v_mfma_f32_16x16x32_bf16 v[116:119], v[186:189], v[202:205], v[116:119]
	v_mfma_f32_16x16x32_bf16 v[104:107], v[178:181], v[210:213], v[104:107]
	v_mfma_f32_16x16x32_bf16 v[100:103], v[186:189], v[210:213], v[100:103]
	v_mfma_f32_16x16x32_bf16 v[86:89], v[178:181], v[224:227], v[86:89]
	v_mfma_f32_16x16x32_bf16 v[82:85], v[186:189], v[224:227], v[82:85]
	v_mfma_f32_16x16x32_bf16 v[136:139], v[182:185], v[198:201], v[136:139]
	v_mfma_f32_16x16x32_bf16 v[132:135], v[190:193], v[198:201], v[132:135]
	v_mfma_f32_16x16x32_bf16 v[120:123], v[182:185], v[206:209], v[120:123]
	v_mfma_f32_16x16x32_bf16 v[116:119], v[190:193], v[206:209], v[116:119]
	v_mfma_f32_16x16x32_bf16 v[104:107], v[182:185], v[220:223], v[104:107]
	v_mfma_f32_16x16x32_bf16 v[100:103], v[190:193], v[220:223], v[100:103]
	v_mfma_f32_16x16x32_bf16 v[86:89], v[182:185], v[228:231], v[86:89]
	v_mfma_f32_16x16x32_bf16 v[82:85], v[190:193], v[228:231], v[82:85]
	s_setprio 0
	s_barrier
; #define PG8_STAGE(bufoff, gbase, voff) do { _Pragma("unroll") for (int _i = 0; _i < 2; ++_i) \
;         __builtin_amdgcn_global_load_lds((const unsigned*)((const char*)(gbase) + (voff)[_i]), (LAS unsigned*)(lds + (bufoff) + ldsw + _i * 8192), 16, 0, 0); } while (0)
; #define PG8_LDA(dst, b, h) do { _Pragma("unroll") for (int m = 0; m < 4; ++m) _Pragma("unroll") for (int k = 0; k < 2; ++k) dst[m][k] = *(const LAS bf16x8*)(lds + PG8_SA(b, h) + aoff + m * 2048 + k * 1024); } while (0)
; #define PG8_LDB(dst, b, h) do { _Pragma("unroll") for (int n = 0; n < 2; ++n) _Pragma("unroll") for (int k = 0; k < 2; ++k) dst[n][k] = *(const LAS bf16x8*)(lds + PG8_SB(b, h) + boff + n * 2048 + k * 1024); } while (0)
; #define PG8_WAIT_V(n) asm volatile("s_waitcnt vmcnt(" #n ")" ::: "memory")
; #define PG8_BAR __builtin_amdgcn_s_barrier()
; template <class Epi, class Sched>
; __device__ __forceinline__ void gemm_phase(LAS unsigned char* lds, const Gemm g, const Sched& S, const Epi& E) {
;     ...
;         for (int t = 0; t < nt; t += 2) {
;             const bool last = (t == nt - 2);
;             const char* a1 = cA + (size_t)(t + 1) * kstepA;
;             const char* a2 = last ? nA : cA + (size_t)(t + 2) * kstepA; const char* b2 = last ? nB : cB + (size_t)(t + 2) * kstep;
;             const char* a3 = a2 + kstepA; const char* b3 = b2 + kstep;
;             PG8_LDB(B0, 0, 0); PG8_LDB(B1, 0, 1); PG8_SCHED; PG8_LDA(At, 0, 0); PG8_STAGE(PG8_SA(1, 1), a1 + hA, voffA);
;             PG8_WAIT_V(8); PG8_WAIT_L(0); PG8_BAR; PG8_MMA(0, 0, At, B0); PG8_MMA(0, 1, At, B1); PG8_BAR; PG8_SCHED;
;             PG8_LDA(At, 0, 1); PG8_STAGE(PG8_SB(0, 0), b2, voffB); PG8_STAGE(PG8_SB(0, 1), b2 + hB, voffB); PG8_STAGE(PG8_SA(0, 0), a2, voffA);
;             PG8_WAIT_V(8); PG8_WAIT_L(0); PG8_BAR; PG8_MMA(1, 0, At, B0); PG8_MMA(1, 1, At, B1); PG8_BAR; PG8_SCHED;
;             PG8_LDB(B0, 1, 0); PG8_LDB(B1, 1, 1); PG8_SCHED; PG8_LDA(At, 1, 0); PG8_STAGE(PG8_SA(0, 1), a2 + hA, voffA);
;             PG8_WAIT_V(8); PG8_WAIT_L(0); PG8_BAR; PG8_MMA(0, 0, At, B0); PG8_MMA(0, 1, At, B1); PG8_BAR; PG8_SCHED;
;             PG8_LDA(At, 1, 1); PG8_STAGE(PG8_SB(1, 0), b3, voffB); PG8_STAGE(PG8_SB(1, 1), b3 + hB, voffB); PG8_STAGE(PG8_SA(1, 0), a3, voffA);
;             PG8_WAIT_V(8); PG8_WAIT_L(0); PG8_BAR; PG8_MMA(1, 0, At, B0); PG8_MMA(1, 1, At, B1); PG8_BAR; PG8_SCHED;
;         }
	s_add_i32 s24, s47, s34
	v_lshl_add_u64 v[154:155], v[154:155], 0, s[76:77]
	s_mov_b32 m0, s24
	ds_read_b128 v[194:197], v177 offset:49152
	ds_read_b128 v[198:201], v177 offset:50176
	ds_read_b128 v[202:205], v177 offset:51200
	ds_read_b128 v[206:209], v177 offset:52224
	ds_read_b128 v[210:213], v177 offset:53248
	ds_read_b128 v[220:223], v177 offset:54272
	ds_read_b128 v[224:227], v177 offset:55296
	ds_read_b128 v[228:231], v177 offset:56320
	global_load_lds_dwordx4 v[154:155], off
	s_add_i32 m0, s24, 0x2000
	s_add_u32 s22, s22, 0x20080
	v_lshl_add_u64 v[154:155], v[156:157], 0, s[76:77]
	s_addc_u32 s23, s23, 0
	s_add_i32 s24, s48, s34
	global_load_lds_dwordx4 v[154:155], off
	v_lshl_add_u64 v[154:155], s[22:23], 0, v[162:163]
	s_mov_b32 m0, s24
	s_nop 0
	global_load_lds_dwordx4 v[154:155], off
	v_lshl_add_u64 v[154:155], s[22:23], 0, v[158:159]
	s_add_i32 m0, s24, 0x2000
	s_nop 0
	global_load_lds_dwordx4 v[154:155], off
	v_lshl_add_u64 v[154:155], v[172:173], 0, s[76:77]
	s_mov_b32 m0, s39
	s_nop 0
	global_load_lds_dwordx4 v[154:155], off
	v_lshl_add_u64 v[154:155], v[232:233], 0, s[76:77]
	s_mov_b32 m0, s40
	s_nop 0
	global_load_lds_dwordx4 v[154:155], off
	s_waitcnt vmcnt(8)
	s_waitcnt lgkmcnt(0)
	s_barrier
	s_setprio 1
	s_waitcnt lgkmcnt(0)
	v_mfma_f32_16x16x32_bf16 v[78:81], v[58:61], v[194:197], v[78:81]
	v_mfma_f32_16x16x32_bf16 v[74:77], v[66:69], v[194:197], v[74:77]
	v_mfma_f32_16x16x32_bf16 v[54:57], v[58:61], v[202:205], v[54:57]
	v_mfma_f32_16x16x32_bf16 v[50:53], v[66:69], v[202:205], v[50:53]
	v_mfma_f32_16x16x32_bf16 v[30:33], v[58:61], v[210:213], v[30:33]
	v_mfma_f32_16x16x32_bf16 v[26:29], v[66:69], v[210:213], v[26:29]
	v_mfma_f32_16x16x32_bf16 v[14:17], v[58:61], v[224:227], v[14:17]
	v_mfma_f32_16x16x32_bf16 v[10:13], v[66:69], v[224:227], v[10:13]
	v_mfma_f32_16x16x32_bf16 v[78:81], v[62:65], v[198:201], v[78:81]
	v_mfma_f32_16x16x32_bf16 v[74:77], v[70:73], v[198:201], v[74:77]
	v_mfma_f32_16x16x32_bf16 v[54:57], v[62:65], v[206:209], v[54:57]
	v_mfma_f32_16x16x32_bf16 v[50:53], v[70:73], v[206:209], v[50:53]
	v_mfma_f32_16x16x32_bf16 v[30:33], v[62:65], v[220:223], v[30:33]
	v_mfma_f32_16x16x32_bf16 v[26:29], v[70:73], v[220:223], v[26:29]
	v_mfma_f32_16x16x32_bf16 v[14:17], v[62:65], v[228:231], v[14:17]
	v_mfma_f32_16x16x32_bf16 v[10:13], v[70:73], v[228:231], v[10:13]
	v_mfma_f32_16x16x32_bf16 v[42:45], v[178:181], v[194:197], v[42:45]
	v_mfma_f32_16x16x32_bf16 v[70:73], v[182:185], v[198:201], v[42:45]
	v_mfma_f32_16x16x32_bf16 v[42:45], v[186:189], v[194:197], v[46:49]
	v_mfma_f32_16x16x32_bf16 v[38:41], v[178:181], v[202:205], v[38:41]
	v_mfma_f32_16x16x32_bf16 v[34:37], v[186:189], v[202:205], v[34:37]
	v_mfma_f32_16x16x32_bf16 v[22:25], v[178:181], v[210:213], v[22:25]
	v_mfma_f32_16x16x32_bf16 v[18:21], v[186:189], v[210:213], v[18:21]
	v_mfma_f32_16x16x32_bf16 v[6:9], v[178:181], v[224:227], v[6:9]
	v_mfma_f32_16x16x32_bf16 v[2:5], v[186:189], v[224:227], v[2:5]
	v_mfma_f32_16x16x32_bf16 v[66:69], v[190:193], v[198:201], v[42:45]
	v_mfma_f32_16x16x32_bf16 v[38:41], v[182:185], v[206:209], v[38:41]
	v_mfma_f32_16x16x32_bf16 v[34:37], v[190:193], v[206:209], v[34:37]
	v_mfma_f32_16x16x32_bf16 v[22:25], v[182:185], v[220:223], v[22:25]
	v_mfma_f32_16x16x32_bf16 v[18:21], v[190:193], v[220:223], v[18:21]
	v_mfma_f32_16x16x32_bf16 v[6:9], v[182:185], v[228:231], v[6:9]
	v_mfma_f32_16x16x32_bf16 v[2:5], v[190:193], v[228:231], v[2:5]
	s_setprio 0
	s_barrier
	s_add_i32 s46, s46, 2
	s_add_u32 s2, s2, 0x100
	s_addc_u32 s3, s3, 0
	s_add_u32 s28, s28, 0x100
	s_addc_u32 s29, s29, 0
	s_cmp_gt_u32 s46, 29
	s_cbranch_scc0 .LBB0_259
	s_and_b64 vcc, exec, s[12:13]
	s_cbranch_vccz .LBB0_262
	s_barrier

; #define PG8_STAGE(bufoff, gbase, voff) do { _Pragma("unroll") for (int _i = 0; _i < 2; ++_i) \
;         __builtin_amdgcn_global_load_lds((const unsigned*)((const char*)(gbase) + (voff)[_i]), (LAS unsigned*)(lds + (bufoff) + ldsw + _i * 8192), 16, 0, 0); } while (0)
; #define PG8_LDA(dst, b, h) do { _Pragma("unroll") for (int m = 0; m < 4; ++m) _Pragma("unroll") for (int k = 0; k < 2; ++k) dst[m][k] = *(const LAS bf16x8*)(lds + PG8_SA(b, h) + aoff + m * 2048 + k * 1024); } while (0)
; #define PG8_LDB(dst, b, h) do { _Pragma("unroll") for (int n = 0; n < 2; ++n) _Pragma("unroll") for (int k = 0; k < 2; ++k) dst[n][k] = *(const LAS bf16x8*)(lds + PG8_SB(b, h) + boff + n * 2048 + k * 1024); } while (0)
; #define PG8_WAIT_V(n) asm volatile("s_waitcnt vmcnt(" #n ")" ::: "memory")
; #define PG8_WAIT_L(n) asm volatile("s_waitcnt lgkmcnt(" #n ")" ::: "memory")
; template <class Epi, class Sched>
; __device__ __forceinline__ void gemm_phase(LAS unsigned char* lds, const Gemm g, const Sched& S, const Epi& E) {
;     ...
;         for (int t = 0; t < nt; t += 2) {
;             const bool last = (t == nt - 2);
;             const char* a1 = cA + (size_t)(t + 1) * kstepA;
;             const char* a2 = last ? nA : cA + (size_t)(t + 2) * kstepA; const char* b2 = last ? nB : cB + (size_t)(t + 2) * kstep;
;             const char* a3 = a2 + kstepA; const char* b3 = b2 + kstep;
;             PG8_LDB(B0, 0, 0); PG8_LDB(B1, 0, 1); PG8_SCHED; PG8_LDA(At, 0, 0); PG8_STAGE(PG8_SA(1, 1), a1 + hA, voffA);
;             PG8_WAIT_V(8); PG8_WAIT_L(0); PG8_BAR; PG8_MMA(0, 0, At, B0); PG8_MMA(0, 1, At, B1); PG8_BAR; PG8_SCHED;
;             PG8_LDA(At, 0, 1); PG8_STAGE(PG8_SB(0, 0), b2, voffB); PG8_STAGE(PG8_SB(0, 1), b2 + hB, voffB); PG8_STAGE(PG8_SA(0, 0), a2, voffA);
;             PG8_WAIT_V(8); PG8_WAIT_L(0); PG8_BAR; PG8_MMA(1, 0, At, B0); PG8_MMA(1, 1, At, B1); PG8_BAR; PG8_SCHED;
;             PG8_LDB(B0, 1, 0); PG8_LDB(B1, 1, 1); PG8_SCHED; PG8_LDA(At, 1, 0); PG8_STAGE(PG8_SA(0, 1), a2 + hA, voffA);
;             PG8_WAIT_V(8); PG8_WAIT_L(0); PG8_BAR; PG8_MMA(0, 0, At, B0); PG8_MMA(0, 1, At, B1); PG8_BAR; PG8_SCHED;
;             PG8_LDA(At, 1, 1); PG8_STAGE(PG8_SB(1, 0), b3, voffB); PG8_STAGE(PG8_SB(1, 1), b3 + hB, voffB); PG8_STAGE(PG8_SA(1, 0), a3, voffA);
;             PG8_WAIT_V(8); PG8_WAIT_L(0); PG8_BAR; PG8_MMA(1, 0, At, B0); PG8_MMA(1, 1, At, B1); PG8_BAR; PG8_SCHED;
.LBB0_412:
	s_add_u32 s12, s16, 0x100
	s_addc_u32 s13, s17, 0
	s_add_i32 s20, 0, 0x10000
	v_add_u32_e32 v83, s20, v81
	ds_read_b128 v[84:87], v83
	ds_read_b128 v[88:91], v83 offset:1024
	ds_read_b128 v[92:95], v83 offset:2048
	ds_read_b128 v[100:103], v83 offset:3072
	s_cmp_eq_u32 s42, 4
	s_cselect_b32 s19, s5, s13
	s_cselect_b32 s18, s4, s12
	s_cselect_b32 s15, s38, s41
	s_cselect_b32 s14, s39, s40
	v_lshl_add_u64 v[96:97], s[16:17], 0, v[76:77]
	s_add_i32 m0, s22, 0xc000
	ds_read_b128 v[104:107], v82
	ds_read_b128 v[108:111], v82 offset:1024
	ds_read_b128 v[112:115], v82 offset:2048
	ds_read_b128 v[116:119], v82 offset:3072
	ds_read_b128 v[120:123], v82 offset:4096
	ds_read_b128 v[124:127], v82 offset:5120
	ds_read_b128 v[128:131], v82 offset:6144
	ds_read_b128 v[132:135], v82 offset:7168
	global_load_lds_dwordx4 v[96:97], off
	v_lshl_add_u64 v[96:97], s[16:17], 0, v[78:79]
	s_add_i32 m0, s22, 0xe000
	s_nop 0
	global_load_lds_dwordx4 v[96:97], off
	s_waitcnt vmcnt(8)
	s_waitcnt lgkmcnt(0)
	s_barrier
	s_setprio 1
	s_waitcnt lgkmcnt(0)
	v_mfma_f32_16x16x32_bf16 v[62:65], v[84:87], v[104:107], v[62:65]
	v_mfma_f32_16x16x32_bf16 v[58:61], v[92:95], v[104:107], v[58:61]
	v_mfma_f32_16x16x32_bf16 v[54:57], v[84:87], v[112:115], v[54:57]
	v_mfma_f32_16x16x32_bf16 v[50:53], v[92:95], v[112:115], v[50:53]
	v_mfma_f32_16x16x32_bf16 v[46:49], v[84:87], v[120:123], v[46:49]
	v_mfma_f32_16x16x32_bf16 v[42:45], v[92:95], v[120:123], v[42:45]
	v_mfma_f32_16x16x32_bf16 v[38:41], v[84:87], v[128:131], v[38:41]
	v_mfma_f32_16x16x32_bf16 v[34:37], v[92:95], v[128:131], v[34:37]
	v_mfma_f32_16x16x32_bf16 v[62:65], v[88:91], v[108:111], v[62:65]
	v_mfma_f32_16x16x32_bf16 v[58:61], v[100:103], v[108:111], v[58:61]
	v_mfma_f32_16x16x32_bf16 v[54:57], v[88:91], v[116:119], v[54:57]
	v_mfma_f32_16x16x32_bf16 v[50:53], v[100:103], v[116:119], v[50:53]
	v_mfma_f32_16x16x32_bf16 v[46:49], v[88:91], v[124:127], v[46:49]
	v_mfma_f32_16x16x32_bf16 v[42:45], v[100:103], v[124:127], v[42:45]
	v_mfma_f32_16x16x32_bf16 v[38:41], v[88:91], v[132:135], v[38:41]
	v_mfma_f32_16x16x32_bf16 v[34:37], v[100:103], v[132:135], v[34:37]
	s_setprio 0
	s_barrier
	s_add_i32 s16, s20, s10
	v_lshl_add_u64 v[96:97], s[14:15], 0, v[70:71]
	s_mov_b32 m0, s16
	ds_read_b128 v[104:107], v82 offset:16384
	ds_read_b128 v[108:111], v82 offset:17408
	ds_read_b128 v[112:115], v82 offset:18432
	ds_read_b128 v[116:119], v82 offset:19456
	ds_read_b128 v[120:123], v82 offset:20480
	ds_read_b128 v[124:127], v82 offset:21504
	ds_read_b128 v[128:131], v82 offset:22528
	ds_read_b128 v[132:135], v82 offset:23552
	global_load_lds_dwordx4 v[96:97], off
	s_add_i32 m0, s16, 0x2000
	s_add_u32 s16, s14, 0x20000
	v_lshl_add_u64 v[136:137], s[14:15], 0, v[66:67]
	s_addc_u32 s17, s15, 0
	global_load_lds_dwordx4 v[136:137], off
	v_lshl_add_u64 v[138:139], s[16:17], 0, v[70:71]
	s_mov_b32 m0, s23
	v_lshl_add_u64 v[140:141], s[18:19], 0, v[68:69]
	global_load_lds_dwordx4 v[138:139], off
	v_lshl_add_u64 v[138:139], s[16:17], 0, v[66:67]
	s_mov_b32 m0, s24
	s_nop 0
	global_load_lds_dwordx4 v[138:139], off
	v_lshl_add_u64 v[138:139], s[18:19], 0, v[72:73]
	s_mov_b32 m0, s22
	s_nop 0
	global_load_lds_dwordx4 v[138:139], off
	s_mov_b32 m0, s25
	s_nop 0
	global_load_lds_dwordx4 v[140:141], off
	s_waitcnt vmcnt(8)
	s_waitcnt lgkmcnt(0)
	s_barrier
	s_setprio 1
	s_waitcnt lgkmcnt(0)
	v_mfma_f32_16x16x32_bf16 v[30:33], v[84:87], v[104:107], v[30:33]
	v_mfma_f32_16x16x32_bf16 v[26:29], v[92:95], v[104:107], v[26:29]
	v_mfma_f32_16x16x32_bf16 v[22:25], v[84:87], v[112:115], v[22:25]
	v_mfma_f32_16x16x32_bf16 v[18:21], v[92:95], v[112:115], v[18:21]
	v_mfma_f32_16x16x32_bf16 v[14:17], v[84:87], v[120:123], v[14:17]
	v_mfma_f32_16x16x32_bf16 v[10:13], v[92:95], v[120:123], v[10:13]
	v_mfma_f32_16x16x32_bf16 v[6:9], v[84:87], v[128:131], v[6:9]
	v_mfma_f32_16x16x32_bf16 v[2:5], v[92:95], v[128:131], v[2:5]
	v_mfma_f32_16x16x32_bf16 v[30:33], v[88:91], v[108:111], v[30:33]
	v_mfma_f32_16x16x32_bf16 v[26:29], v[100:103], v[108:111], v[26:29]
	v_mfma_f32_16x16x32_bf16 v[22:25], v[88:91], v[116:119], v[22:25]
	v_mfma_f32_16x16x32_bf16 v[18:21], v[100:103], v[116:119], v[18:21]
	v_mfma_f32_16x16x32_bf16 v[14:17], v[88:91], v[124:127], v[14:17]
	v_mfma_f32_16x16x32_bf16 v[10:13], v[100:103], v[124:127], v[10:13]
	v_mfma_f32_16x16x32_bf16 v[6:9], v[88:91], v[132:135], v[6:9]
	v_mfma_f32_16x16x32_bf16 v[2:5], v[100:103], v[132:135], v[2:5]
	s_setprio 0
	s_barrier
; #define PG8_STAGE(bufoff, gbase, voff) do { _Pragma("unroll") for (int _i = 0; _i < 2; ++_i) \
;         __builtin_amdgcn_global_load_lds((const unsigned*)((const char*)(gbase) + (voff)[_i]), (LAS unsigned*)(lds + (bufoff) + ldsw + _i * 8192), 16, 0, 0); } while (0)
; #define PG8_LDA(dst, b, h) do { _Pragma("unroll") for (int m = 0; m < 4; ++m) _Pragma("unroll") for (int k = 0; k < 2; ++k) dst[m][k] = *(const LAS bf16x8*)(lds + PG8_SA(b, h) + aoff + m * 2048 + k * 1024); } while (0)
; #define PG8_LDB(dst, b, h) do { _Pragma("unroll") for (int n = 0; n < 2; ++n) _Pragma("unroll") for (int k = 0; k < 2; ++k) dst[n][k] = *(const LAS bf16x8*)(lds + PG8_SB(b, h) + boff + n * 2048 + k * 1024); } while (0)
; #define PG8_MMA(ai, bj, At, Bt) do { __builtin_amdgcn_s_setprio(1); _Pragma("unroll") for (int m = 0; m < 4; ++m) _Pragma("unroll") for (int n = 0; n < 2; ++n) _Pragma("unroll") for (int k = 0; k < 2; ++k) \
;         acc[ai][bj][m][n] = __builtin_amdgcn_mfma_f32_16x16x32_bf16(Bt[n][k], At[m][k], acc[ai][bj][m][n], 0, 0, 0); __builtin_amdgcn_s_setprio(0); } while (0)
; #define PG8_WAIT_V(n) asm volatile("s_waitcnt vmcnt(" #n ")" ::: "memory")
; #define PG8_WAIT_L(n) asm volatile("s_waitcnt lgkmcnt(" #n ")" ::: "memory")
; #define PG8_BAR __builtin_amdgcn_s_barrier()
; #define PG8_SCHED __builtin_amdgcn_sched_barrier(0)
; template <class Epi, class Sched>
; __device__ __forceinline__ void gemm_phase(LAS unsigned char* lds, const Gemm g, const Sched& S, const Epi& E) {
;     ...
;             PG8_LDB(B0, 1, 0); PG8_LDB(B1, 1, 1); PG8_SCHED; PG8_LDA(At, 1, 0); PG8_STAGE(PG8_SA(0, 1), a2 + hA, voffA);
;             PG8_WAIT_V(8); PG8_WAIT_L(0); PG8_BAR; PG8_MMA(0, 0, At, B0); PG8_MMA(0, 1, At, B1); PG8_BAR; PG8_SCHED;
;             PG8_LDA(At, 1, 1); PG8_STAGE(PG8_SB(1, 0), b3, voffB); PG8_STAGE(PG8_SB(1, 1), b3 + hB, voffB); PG8_STAGE(PG8_SA(1, 0), a3, voffA);
;             PG8_WAIT_V(8); PG8_WAIT_L(0); PG8_BAR; PG8_MMA(1, 0, At, B0); PG8_MMA(1, 1, At, B1); PG8_BAR; PG8_SCHED;
;         }
;         if (wr == 0) PG8_BAR;
	s_add_i32 s21, 0, 0x18000
	v_add_u32_e32 v83, s21, v81
	ds_read_b128 v[84:87], v83
	ds_read_b128 v[88:91], v83 offset:1024
	ds_read_b128 v[92:95], v83 offset:2048
	ds_read_b128 v[100:103], v83 offset:3072
	s_add_u32 s16, s18, 0x28000
	s_addc_u32 s17, s19, 0
	s_mov_b32 m0, s26
	v_lshl_add_u64 v[142:143], s[16:17], 0, v[72:73]
	ds_read_b128 v[104:107], v82 offset:32768
	ds_read_b128 v[108:111], v82 offset:33792
	ds_read_b128 v[112:115], v82 offset:34816
	ds_read_b128 v[116:119], v82 offset:35840
	ds_read_b128 v[120:123], v82 offset:36864
	ds_read_b128 v[124:127], v82 offset:37888
	ds_read_b128 v[128:131], v82 offset:38912
	ds_read_b128 v[132:135], v82 offset:39936
	global_load_lds_dwordx4 v[142:143], off
	v_lshl_add_u64 v[142:143], s[16:17], 0, v[68:69]
	s_mov_b32 m0, s27
	s_nop 0
	global_load_lds_dwordx4 v[142:143], off
	s_waitcnt vmcnt(8)
	s_waitcnt lgkmcnt(0)
	s_barrier
	s_setprio 1
	s_waitcnt lgkmcnt(0)
	v_mfma_f32_16x16x32_bf16 v[62:65], v[84:87], v[104:107], v[62:65]
	v_mfma_f32_16x16x32_bf16 v[58:61], v[92:95], v[104:107], v[58:61]
	v_mfma_f32_16x16x32_bf16 v[54:57], v[84:87], v[112:115], v[54:57]
	v_mfma_f32_16x16x32_bf16 v[50:53], v[92:95], v[112:115], v[50:53]
	v_mfma_f32_16x16x32_bf16 v[46:49], v[84:87], v[120:123], v[46:49]
	v_mfma_f32_16x16x32_bf16 v[42:45], v[92:95], v[120:123], v[42:45]
	v_mfma_f32_16x16x32_bf16 v[38:41], v[84:87], v[128:131], v[38:41]
	v_mfma_f32_16x16x32_bf16 v[34:37], v[92:95], v[128:131], v[34:37]
	v_mfma_f32_16x16x32_bf16 v[62:65], v[88:91], v[108:111], v[62:65]
	v_mfma_f32_16x16x32_bf16 v[58:61], v[100:103], v[108:111], v[58:61]
	v_mfma_f32_16x16x32_bf16 v[54:57], v[88:91], v[116:119], v[54:57]
	v_mfma_f32_16x16x32_bf16 v[50:53], v[100:103], v[116:119], v[50:53]
	v_mfma_f32_16x16x32_bf16 v[46:49], v[88:91], v[124:127], v[46:49]
	v_mfma_f32_16x16x32_bf16 v[42:45], v[100:103], v[124:127], v[42:45]
	v_mfma_f32_16x16x32_bf16 v[38:41], v[88:91], v[132:135], v[38:41]
	v_mfma_f32_16x16x32_bf16 v[34:37], v[100:103], v[132:135], v[34:37]
	s_setprio 0
	s_barrier
	s_add_i32 s16, s21, s10
	v_lshl_add_u64 v[96:97], v[96:97], 0, s[76:77]
	s_mov_b32 m0, s16
	ds_read_b128 v[104:107], v82 offset:49152
	ds_read_b128 v[108:111], v82 offset:50176
	ds_read_b128 v[112:115], v82 offset:51200
	ds_read_b128 v[116:119], v82 offset:52224
	ds_read_b128 v[120:123], v82 offset:53248
	ds_read_b128 v[124:127], v82 offset:54272
	ds_read_b128 v[128:131], v82 offset:55296
	ds_read_b128 v[132:135], v82 offset:56320
	global_load_lds_dwordx4 v[96:97], off
	s_add_i32 m0, s16, 0x2000
	s_add_u32 s14, s14, 0x20080
	v_lshl_add_u64 v[96:97], v[136:137], 0, s[76:77]
	s_addc_u32 s15, s15, 0
	global_load_lds_dwordx4 v[96:97], off
	v_lshl_add_u64 v[96:97], s[14:15], 0, v[70:71]
	s_mov_b32 m0, s30
	s_nop 0
	global_load_lds_dwordx4 v[96:97], off
	v_lshl_add_u64 v[96:97], s[14:15], 0, v[66:67]
	s_mov_b32 m0, s31
	s_nop 0
	global_load_lds_dwordx4 v[96:97], off
	v_lshl_add_u64 v[96:97], v[138:139], 0, s[76:77]
	s_mov_b32 m0, s28
	s_nop 0
	global_load_lds_dwordx4 v[96:97], off
	v_lshl_add_u64 v[96:97], v[140:141], 0, s[76:77]
	s_mov_b32 m0, s29
	s_nop 0
	global_load_lds_dwordx4 v[96:97], off
	s_waitcnt vmcnt(8)
	s_waitcnt lgkmcnt(0)
	s_barrier
	s_setprio 1
	s_waitcnt lgkmcnt(0)
	v_mfma_f32_16x16x32_bf16 v[30:33], v[84:87], v[104:107], v[30:33]
	v_mfma_f32_16x16x32_bf16 v[26:29], v[92:95], v[104:107], v[26:29]
	v_mfma_f32_16x16x32_bf16 v[22:25], v[84:87], v[112:115], v[22:25]
	v_mfma_f32_16x16x32_bf16 v[18:21], v[92:95], v[112:115], v[18:21]
	v_mfma_f32_16x16x32_bf16 v[14:17], v[84:87], v[120:123], v[14:17]
	v_mfma_f32_16x16x32_bf16 v[10:13], v[92:95], v[120:123], v[10:13]
	v_mfma_f32_16x16x32_bf16 v[6:9], v[84:87], v[128:131], v[6:9]
	v_mfma_f32_16x16x32_bf16 v[2:5], v[92:95], v[128:131], v[2:5]
	v_mfma_f32_16x16x32_bf16 v[30:33], v[88:91], v[108:111], v[30:33]
	v_mfma_f32_16x16x32_bf16 v[26:29], v[100:103], v[108:111], v[26:29]
	v_mfma_f32_16x16x32_bf16 v[22:25], v[88:91], v[116:119], v[22:25]
	v_mfma_f32_16x16x32_bf16 v[18:21], v[100:103], v[116:119], v[18:21]
	v_mfma_f32_16x16x32_bf16 v[14:17], v[88:91], v[124:127], v[14:17]
	v_mfma_f32_16x16x32_bf16 v[10:13], v[100:103], v[124:127], v[10:13]
	v_mfma_f32_16x16x32_bf16 v[6:9], v[88:91], v[132:135], v[6:9]
	v_mfma_f32_16x16x32_bf16 v[2:5], v[100:103], v[132:135], v[2:5]
	s_setprio 0
	s_barrier
	s_add_i32 s42, s42, 2
	s_add_u32 s40, s40, 0x100
	s_addc_u32 s41, s41, 0
	s_cmp_gt_u32 s42, 5
	s_mov_b64 s[16:17], s[12:13]
	s_cbranch_scc0 .LBB0_412
	s_and_b64 vcc, exec, s[2:3]
	s_cbranch_vccz .LBB0_415
	s_barrier

; #define PG8_STAGE(bufoff, gbase, voff) do { _Pragma("unroll") for (int _i = 0; _i < 2; ++_i) \
;         __builtin_amdgcn_global_load_lds((const unsigned*)((const char*)(gbase) + (voff)[_i]), (LAS unsigned*)(lds + (bufoff) + ldsw + _i * 8192), 16, 0, 0); } while (0)
; #define PG8_LDA(dst, b, h) do { _Pragma("unroll") for (int m = 0; m < 4; ++m) _Pragma("unroll") for (int k = 0; k < 2; ++k) dst[m][k] = *(const LAS bf16x8*)(lds + PG8_SA(b, h) + aoff + m * 2048 + k * 1024); } while (0)
; #define PG8_LDB(dst, b, h) do { _Pragma("unroll") for (int n = 0; n < 2; ++n) _Pragma("unroll") for (int k = 0; k < 2; ++k) dst[n][k] = *(const LAS bf16x8*)(lds + PG8_SB(b, h) + boff + n * 2048 + k * 1024); } while (0)
; #define PG8_MMA(ai, bj, At, Bt) do { __builtin_amdgcn_s_setprio(1); _Pragma("unroll") for (int m = 0; m < 4; ++m) _Pragma("unroll") for (int n = 0; n < 2; ++n) _Pragma("unroll") for (int k = 0; k < 2; ++k) \
;         acc[ai][bj][m][n] = __builtin_amdgcn_mfma_f32_16x16x32_bf16(Bt[n][k], At[m][k], acc[ai][bj][m][n], 0, 0, 0); __builtin_amdgcn_s_setprio(0); } while (0)
; #define PG8_WAIT_V(n) asm volatile("s_waitcnt vmcnt(" #n ")" ::: "memory")
; #define PG8_WAIT_L(n) asm volatile("s_waitcnt lgkmcnt(" #n ")" ::: "memory")
; #define PG8_BAR __builtin_amdgcn_s_barrier()
; #define PG8_SCHED __builtin_amdgcn_sched_barrier(0)
; template <class Epi, class Sched>
; __device__ __forceinline__ void gemm_phase(LAS unsigned char* lds, const Gemm g, const Sched& S, const Epi& E) {
;     ...
;         for (int t = 0; t < nt; t += 2) {
;             const bool last = (t == nt - 2);
;             const char* a1 = cA + (size_t)(t + 1) * kstepA;
;             const char* a2 = last ? nA : cA + (size_t)(t + 2) * kstepA; const char* b2 = last ? nB : cB + (size_t)(t + 2) * kstep;
;             const char* a3 = a2 + kstepA; const char* b3 = b2 + kstep;
;             PG8_LDB(B0, 0, 0); PG8_LDB(B1, 0, 1); PG8_SCHED; PG8_LDA(At, 0, 0); PG8_STAGE(PG8_SA(1, 1), a1 + hA, voffA);
;             PG8_WAIT_V(8); PG8_WAIT_L(0); PG8_BAR; PG8_MMA(0, 0, At, B0); PG8_MMA(0, 1, At, B1); PG8_BAR; PG8_SCHED;
;             PG8_LDA(At, 0, 1); PG8_STAGE(PG8_SB(0, 0), b2, voffB); PG8_STAGE(PG8_SB(0, 1), b2 + hB, voffB); PG8_STAGE(PG8_SA(0, 0), a2, voffA);
;             PG8_WAIT_V(8); PG8_WAIT_L(0); PG8_BAR; PG8_MMA(1, 0, At, B0); PG8_MMA(1, 1, At, B1); PG8_BAR; PG8_SCHED;
.LBB0_433:
	s_add_u32 s2, s14, 0x100
	s_addc_u32 s3, s15, 0
	s_cmp_eq_u32 s35, 6
	s_cselect_b32 s17, s7, s3
	s_cselect_b32 s16, s6, s2
	v_add_u32_e32 v98, s20, v173
	s_cselect_b32 s13, s9, s34
	s_cselect_b32 s12, s8, s31
	s_add_i32 s36, 0, 0x14000
	ds_read_b128 v[74:77], v98
	ds_read_b128 v[78:81], v98 offset:1024
	ds_read_b128 v[166:169], v98 offset:2048
	ds_read_b128 v[176:179], v98 offset:3072
	v_add_u32_e32 v98, s36, v173
	ds_read_b128 v[180:183], v98
	ds_read_b128 v[184:187], v98 offset:1024
	ds_read_b128 v[188:191], v98 offset:2048
	ds_read_b128 v[192:195], v98 offset:3072
	v_lshl_add_u64 v[154:155], s[14:15], 0, v[160:161]
	s_add_i32 m0, s19, 0xc000
	ds_read_b128 v[196:199], v175
	ds_read_b128 v[200:203], v175 offset:1024
	ds_read_b128 v[204:207], v175 offset:2048
	ds_read_b128 v[208:211], v175 offset:3072
	ds_read_b128 v[220:223], v175 offset:4096
	ds_read_b128 v[224:227], v175 offset:5120
	ds_read_b128 v[228:231], v175 offset:6144
	ds_read_b128 v[232:235], v175 offset:7168
	global_load_lds_dwordx4 v[154:155], off
	v_lshl_add_u64 v[154:155], s[14:15], 0, v[162:163]
	s_add_i32 m0, s19, 0xe000
	s_nop 0
	global_load_lds_dwordx4 v[154:155], off
	s_waitcnt vmcnt(8)
	s_waitcnt lgkmcnt(0)
	s_barrier
	s_setprio 1
	s_waitcnt lgkmcnt(0)
	v_mfma_f32_16x16x32_bf16 v[136:139], v[74:77], v[196:199], v[136:139]
	v_mfma_f32_16x16x32_bf16 v[132:135], v[166:169], v[196:199], v[132:135]
	v_mfma_f32_16x16x32_bf16 v[128:131], v[74:77], v[204:207], v[128:131]
	v_mfma_f32_16x16x32_bf16 v[124:127], v[166:169], v[204:207], v[124:127]
	v_mfma_f32_16x16x32_bf16 v[120:123], v[74:77], v[220:223], v[120:123]
	v_mfma_f32_16x16x32_bf16 v[116:119], v[166:169], v[220:223], v[116:119]
	v_mfma_f32_16x16x32_bf16 v[112:115], v[74:77], v[228:231], v[112:115]
	v_mfma_f32_16x16x32_bf16 v[108:111], v[166:169], v[228:231], v[108:111]
	v_mfma_f32_16x16x32_bf16 v[136:139], v[78:81], v[200:203], v[136:139]
	v_mfma_f32_16x16x32_bf16 v[132:135], v[176:179], v[200:203], v[132:135]
	v_mfma_f32_16x16x32_bf16 v[128:131], v[78:81], v[208:211], v[128:131]
	v_mfma_f32_16x16x32_bf16 v[124:127], v[176:179], v[208:211], v[124:127]
	v_mfma_f32_16x16x32_bf16 v[120:123], v[78:81], v[224:227], v[120:123]
	v_mfma_f32_16x16x32_bf16 v[116:119], v[176:179], v[224:227], v[116:119]
	v_mfma_f32_16x16x32_bf16 v[112:115], v[78:81], v[232:235], v[112:115]
	v_mfma_f32_16x16x32_bf16 v[108:111], v[176:179], v[232:235], v[108:111]
	v_mfma_f32_16x16x32_bf16 v[70:73], v[180:183], v[196:199], v[70:73]
	v_mfma_f32_16x16x32_bf16 v[66:69], v[188:191], v[196:199], v[66:69]
	v_mfma_f32_16x16x32_bf16 v[54:57], v[180:183], v[204:207], v[54:57]
	v_mfma_f32_16x16x32_bf16 v[50:53], v[188:191], v[204:207], v[50:53]
	v_mfma_f32_16x16x32_bf16 v[46:49], v[180:183], v[220:223], v[46:49]
	v_mfma_f32_16x16x32_bf16 v[42:45], v[188:191], v[220:223], v[42:45]
	v_mfma_f32_16x16x32_bf16 v[38:41], v[180:183], v[228:231], v[38:41]
	v_mfma_f32_16x16x32_bf16 v[34:37], v[188:191], v[228:231], v[34:37]
	v_mfma_f32_16x16x32_bf16 v[70:73], v[184:187], v[200:203], v[70:73]
	v_mfma_f32_16x16x32_bf16 v[66:69], v[192:195], v[200:203], v[66:69]
	v_mfma_f32_16x16x32_bf16 v[54:57], v[184:187], v[208:211], v[54:57]
	v_mfma_f32_16x16x32_bf16 v[50:53], v[192:195], v[208:211], v[50:53]
	v_mfma_f32_16x16x32_bf16 v[46:49], v[184:187], v[224:227], v[46:49]
	v_mfma_f32_16x16x32_bf16 v[42:45], v[192:195], v[224:227], v[42:45]
	v_mfma_f32_16x16x32_bf16 v[38:41], v[184:187], v[232:235], v[38:41]
	v_mfma_f32_16x16x32_bf16 v[34:37], v[192:195], v[232:235], v[34:37]
	s_setprio 0
	s_barrier
	s_add_i32 s14, s20, s18
	v_lshl_add_u64 v[154:155], s[12:13], 0, v[144:145]
	s_mov_b32 m0, s14
	ds_read_b128 v[196:199], v175 offset:16384
	ds_read_b128 v[200:203], v175 offset:17408
	ds_read_b128 v[204:207], v175 offset:18432
	ds_read_b128 v[208:211], v175 offset:19456
	ds_read_b128 v[220:223], v175 offset:20480
	ds_read_b128 v[224:227], v175 offset:21504
	ds_read_b128 v[228:231], v175 offset:22528
	ds_read_b128 v[232:235], v175 offset:23552
	global_load_lds_dwordx4 v[154:155], off
	s_add_i32 m0, s14, 0x2000
	s_add_u32 s14, s12, 0xa000
	v_lshl_add_u64 v[156:157], s[12:13], 0, v[140:141]
	s_addc_u32 s15, s13, 0
	s_add_i32 s36, s36, s18
	global_load_lds_dwordx4 v[156:157], off
	v_lshl_add_u64 v[170:171], s[14:15], 0, v[144:145]
	s_mov_b32 m0, s36
	v_lshl_add_u64 v[212:213], s[16:17], 0, v[142:143]
	global_load_lds_dwordx4 v[170:171], off
	v_lshl_add_u64 v[170:171], s[14:15], 0, v[140:141]
	s_add_i32 m0, s36, 0x2000
	s_nop 0
	global_load_lds_dwordx4 v[170:171], off
	v_lshl_add_u64 v[170:171], s[16:17], 0, v[146:147]
	s_mov_b32 m0, s19
	s_nop 0
	global_load_lds_dwordx4 v[170:171], off
	s_mov_b32 m0, s22
	s_nop 0
	global_load_lds_dwordx4 v[212:213], off
	s_waitcnt vmcnt(8)
	s_waitcnt lgkmcnt(0)
	s_barrier
; #define PG8_STAGE(bufoff, gbase, voff) do { _Pragma("unroll") for (int _i = 0; _i < 2; ++_i) \
;         __builtin_amdgcn_global_load_lds((const unsigned*)((const char*)(gbase) + (voff)[_i]), (LAS unsigned*)(lds + (bufoff) + ldsw + _i * 8192), 16, 0, 0); } while (0)
; #define PG8_LDA(dst, b, h) do { _Pragma("unroll") for (int m = 0; m < 4; ++m) _Pragma("unroll") for (int k = 0; k < 2; ++k) dst[m][k] = *(const LAS bf16x8*)(lds + PG8_SA(b, h) + aoff + m * 2048 + k * 1024); } while (0)
; #define PG8_LDB(dst, b, h) do { _Pragma("unroll") for (int n = 0; n < 2; ++n) _Pragma("unroll") for (int k = 0; k < 2; ++k) dst[n][k] = *(const LAS bf16x8*)(lds + PG8_SB(b, h) + boff + n * 2048 + k * 1024); } while (0)
; #define PG8_MMA(ai, bj, At, Bt) do { __builtin_amdgcn_s_setprio(1); _Pragma("unroll") for (int m = 0; m < 4; ++m) _Pragma("unroll") for (int n = 0; n < 2; ++n) _Pragma("unroll") for (int k = 0; k < 2; ++k) \
;         acc[ai][bj][m][n] = __builtin_amdgcn_mfma_f32_16x16x32_bf16(Bt[n][k], At[m][k], acc[ai][bj][m][n], 0, 0, 0); __builtin_amdgcn_s_setprio(0); } while (0)
; #define PG8_WAIT_V(n) asm volatile("s_waitcnt vmcnt(" #n ")" ::: "memory")
; #define PG8_WAIT_L(n) asm volatile("s_waitcnt lgkmcnt(" #n ")" ::: "memory")
; #define PG8_BAR __builtin_amdgcn_s_barrier()
; #define PG8_SCHED __builtin_amdgcn_sched_barrier(0)
; template <class Epi, class Sched>
; __device__ __forceinline__ void gemm_phase(LAS unsigned char* lds, const Gemm g, const Sched& S, const Epi& E) {
;     ...
;             PG8_WAIT_V(8); PG8_WAIT_L(0); PG8_BAR; PG8_MMA(1, 0, At, B0); PG8_MMA(1, 1, At, B1); PG8_BAR; PG8_SCHED;
;             PG8_LDB(B0, 1, 0); PG8_LDB(B1, 1, 1); PG8_SCHED; PG8_LDA(At, 1, 0); PG8_STAGE(PG8_SA(0, 1), a2 + hA, voffA);
;             PG8_WAIT_V(8); PG8_WAIT_L(0); PG8_BAR; PG8_MMA(0, 0, At, B0); PG8_MMA(0, 1, At, B1); PG8_BAR; PG8_SCHED;
;             PG8_LDA(At, 1, 1); PG8_STAGE(PG8_SB(1, 0), b3, voffB); PG8_STAGE(PG8_SB(1, 1), b3 + hB, voffB); PG8_STAGE(PG8_SA(1, 0), a3, voffA);
;             PG8_WAIT_V(8); PG8_WAIT_L(0); PG8_BAR; PG8_MMA(1, 0, At, B0); PG8_MMA(1, 1, At, B1); PG8_BAR; PG8_SCHED;
	s_setprio 1
	s_waitcnt lgkmcnt(0)
	v_mfma_f32_16x16x32_bf16 v[104:107], v[74:77], v[196:199], v[104:107]
	v_mfma_f32_16x16x32_bf16 v[100:103], v[166:169], v[196:199], v[100:103]
	v_mfma_f32_16x16x32_bf16 v[94:97], v[74:77], v[204:207], v[94:97]
	v_mfma_f32_16x16x32_bf16 v[90:93], v[166:169], v[204:207], v[90:93]
	v_mfma_f32_16x16x32_bf16 v[86:89], v[74:77], v[220:223], v[86:89]
	v_mfma_f32_16x16x32_bf16 v[82:85], v[166:169], v[220:223], v[82:85]
	v_mfma_f32_16x16x32_bf16 v[62:65], v[74:77], v[228:231], v[62:65]
	v_mfma_f32_16x16x32_bf16 v[58:61], v[166:169], v[228:231], v[58:61]
	v_mfma_f32_16x16x32_bf16 v[104:107], v[78:81], v[200:203], v[104:107]
	v_mfma_f32_16x16x32_bf16 v[100:103], v[176:179], v[200:203], v[100:103]
	v_mfma_f32_16x16x32_bf16 v[94:97], v[78:81], v[208:211], v[94:97]
	v_mfma_f32_16x16x32_bf16 v[90:93], v[176:179], v[208:211], v[90:93]
	v_mfma_f32_16x16x32_bf16 v[86:89], v[78:81], v[224:227], v[86:89]
	v_mfma_f32_16x16x32_bf16 v[82:85], v[176:179], v[224:227], v[82:85]
	v_mfma_f32_16x16x32_bf16 v[62:65], v[78:81], v[232:235], v[62:65]
	v_mfma_f32_16x16x32_bf16 v[58:61], v[176:179], v[232:235], v[58:61]
	v_mfma_f32_16x16x32_bf16 v[30:33], v[180:183], v[196:199], v[30:33]
	v_mfma_f32_16x16x32_bf16 v[26:29], v[188:191], v[196:199], v[26:29]
	v_mfma_f32_16x16x32_bf16 v[22:25], v[180:183], v[204:207], v[22:25]
	v_mfma_f32_16x16x32_bf16 v[18:21], v[188:191], v[204:207], v[18:21]
	v_mfma_f32_16x16x32_bf16 v[14:17], v[180:183], v[220:223], v[14:17]
	v_mfma_f32_16x16x32_bf16 v[10:13], v[188:191], v[220:223], v[10:13]
	v_mfma_f32_16x16x32_bf16 v[6:9], v[180:183], v[228:231], v[6:9]
	v_mfma_f32_16x16x32_bf16 v[2:5], v[188:191], v[228:231], v[2:5]
	v_mfma_f32_16x16x32_bf16 v[30:33], v[184:187], v[200:203], v[30:33]
	v_mfma_f32_16x16x32_bf16 v[26:29], v[192:195], v[200:203], v[26:29]
	v_mfma_f32_16x16x32_bf16 v[22:25], v[184:187], v[208:211], v[22:25]
	v_mfma_f32_16x16x32_bf16 v[18:21], v[192:195], v[208:211], v[18:21]
	v_mfma_f32_16x16x32_bf16 v[14:17], v[184:187], v[224:227], v[14:17]
	v_mfma_f32_16x16x32_bf16 v[10:13], v[192:195], v[224:227], v[10:13]
	v_mfma_f32_16x16x32_bf16 v[6:9], v[184:187], v[232:235], v[6:9]
	v_mfma_f32_16x16x32_bf16 v[2:5], v[192:195], v[232:235], v[2:5]
	s_setprio 0
	s_barrier
	v_add_u32_e32 v98, s21, v173
	s_add_i32 s36, 0, 0x1c000
	ds_read_b128 v[74:77], v98
	ds_read_b128 v[78:81], v98 offset:1024
	ds_read_b128 v[166:169], v98 offset:2048
	ds_read_b128 v[176:179], v98 offset:3072
	v_add_u32_e32 v98, s36, v173
	ds_read_b128 v[180:183], v98
	ds_read_b128 v[184:187], v98 offset:1024
	ds_read_b128 v[188:191], v98 offset:2048
	ds_read_b128 v[192:195], v98 offset:3072
	s_add_u32 s14, s16, 0x28000
	s_addc_u32 s15, s17, 0
	s_mov_b32 m0, s23
	v_lshl_add_u64 v[236:237], s[14:15], 0, v[146:147]
	ds_read_b128 v[196:199], v175 offset:32768
	ds_read_b128 v[200:203], v175 offset:33792
	ds_read_b128 v[204:207], v175 offset:34816
	ds_read_b128 v[208:211], v175 offset:35840
	ds_read_b128 v[220:223], v175 offset:36864
	ds_read_b128 v[224:227], v175 offset:37888
	ds_read_b128 v[228:231], v175 offset:38912
	ds_read_b128 v[232:235], v175 offset:39936
	global_load_lds_dwordx4 v[236:237], off
	v_lshl_add_u64 v[236:237], s[14:15], 0, v[142:143]
	s_mov_b32 m0, s24
	s_nop 0
	global_load_lds_dwordx4 v[236:237], off
	s_waitcnt vmcnt(8)
	s_waitcnt lgkmcnt(0)
	s_barrier
	s_setprio 1
	s_waitcnt lgkmcnt(0)
	v_mfma_f32_16x16x32_bf16 v[136:139], v[74:77], v[196:199], v[136:139]
	v_mfma_f32_16x16x32_bf16 v[132:135], v[166:169], v[196:199], v[132:135]
	v_mfma_f32_16x16x32_bf16 v[128:131], v[74:77], v[204:207], v[128:131]
	v_mfma_f32_16x16x32_bf16 v[124:127], v[166:169], v[204:207], v[124:127]
	v_mfma_f32_16x16x32_bf16 v[120:123], v[74:77], v[220:223], v[120:123]
	v_mfma_f32_16x16x32_bf16 v[116:119], v[166:169], v[220:223], v[116:119]
	v_mfma_f32_16x16x32_bf16 v[112:115], v[74:77], v[228:231], v[112:115]
	v_mfma_f32_16x16x32_bf16 v[108:111], v[166:169], v[228:231], v[108:111]
	v_mfma_f32_16x16x32_bf16 v[136:139], v[78:81], v[200:203], v[136:139]
	v_mfma_f32_16x16x32_bf16 v[132:135], v[176:179], v[200:203], v[132:135]
	v_mfma_f32_16x16x32_bf16 v[128:131], v[78:81], v[208:211], v[128:131]
	v_mfma_f32_16x16x32_bf16 v[124:127], v[176:179], v[208:211], v[124:127]
	v_mfma_f32_16x16x32_bf16 v[120:123], v[78:81], v[224:227], v[120:123]
	v_mfma_f32_16x16x32_bf16 v[116:119], v[176:179], v[224:227], v[116:119]
	v_mfma_f32_16x16x32_bf16 v[112:115], v[78:81], v[232:235], v[112:115]
	v_mfma_f32_16x16x32_bf16 v[108:111], v[176:179], v[232:235], v[108:111]
	v_mfma_f32_16x16x32_bf16 v[70:73], v[180:183], v[196:199], v[70:73]
	v_mfma_f32_16x16x32_bf16 v[66:69], v[188:191], v[196:199], v[66:69]
	v_mfma_f32_16x16x32_bf16 v[54:57], v[180:183], v[204:207], v[54:57]
	v_mfma_f32_16x16x32_bf16 v[50:53], v[188:191], v[204:207], v[50:53]
	v_mfma_f32_16x16x32_bf16 v[46:49], v[180:183], v[220:223], v[46:49]
	v_mfma_f32_16x16x32_bf16 v[42:45], v[188:191], v[220:223], v[42:45]
	v_mfma_f32_16x16x32_bf16 v[38:41], v[180:183], v[228:231], v[38:41]
	v_mfma_f32_16x16x32_bf16 v[34:37], v[188:191], v[228:231], v[34:37]
	v_mfma_f32_16x16x32_bf16 v[70:73], v[184:187], v[200:203], v[70:73]
	v_mfma_f32_16x16x32_bf16 v[66:69], v[192:195], v[200:203], v[66:69]
	v_mfma_f32_16x16x32_bf16 v[54:57], v[184:187], v[208:211], v[54:57]
	v_mfma_f32_16x16x32_bf16 v[50:53], v[192:195], v[208:211], v[50:53]
	v_mfma_f32_16x16x32_bf16 v[46:49], v[184:187], v[224:227], v[46:49]
	v_mfma_f32_16x16x32_bf16 v[42:45], v[192:195], v[224:227], v[42:45]
	v_mfma_f32_16x16x32_bf16 v[38:41], v[184:187], v[232:235], v[38:41]
	v_mfma_f32_16x16x32_bf16 v[34:37], v[192:195], v[232:235], v[34:37]
	s_setprio 0
	s_barrier
; #define PG8_STAGE(bufoff, gbase, voff) do { _Pragma("unroll") for (int _i = 0; _i < 2; ++_i) \
;         __builtin_amdgcn_global_load_lds((const unsigned*)((const char*)(gbase) + (voff)[_i]), (LAS unsigned*)(lds + (bufoff) + ldsw + _i * 8192), 16, 0, 0); } while (0)
; #define PG8_LDA(dst, b, h) do { _Pragma("unroll") for (int m = 0; m < 4; ++m) _Pragma("unroll") for (int k = 0; k < 2; ++k) dst[m][k] = *(const LAS bf16x8*)(lds + PG8_SA(b, h) + aoff + m * 2048 + k * 1024); } while (0)
; #define PG8_MMA(ai, bj, At, Bt) do { __builtin_amdgcn_s_setprio(1); _Pragma("unroll") for (int m = 0; m < 4; ++m) _Pragma("unroll") for (int n = 0; n < 2; ++n) _Pragma("unroll") for (int k = 0; k < 2; ++k) \
;         acc[ai][bj][m][n] = __builtin_amdgcn_mfma_f32_16x16x32_bf16(Bt[n][k], At[m][k], acc[ai][bj][m][n], 0, 0, 0); __builtin_amdgcn_s_setprio(0); } while (0)
; #define PG8_WAIT_V(n) asm volatile("s_waitcnt vmcnt(" #n ")" ::: "memory")
; #define PG8_WAIT_L(n) asm volatile("s_waitcnt lgkmcnt(" #n ")" ::: "memory")
; #define PG8_BAR __builtin_amdgcn_s_barrier()
; #define PG8_SCHED __builtin_amdgcn_sched_barrier(0)
; template <class Epi, class Sched>
; __device__ __forceinline__ void gemm_phase(LAS unsigned char* lds, const Gemm g, const Sched& S, const Epi& E) {
;     ...
;             PG8_LDA(At, 1, 1); PG8_STAGE(PG8_SB(1, 0), b3, voffB); PG8_STAGE(PG8_SB(1, 1), b3 + hB, voffB); PG8_STAGE(PG8_SA(1, 0), a3, voffA);
;             PG8_WAIT_V(8); PG8_WAIT_L(0); PG8_BAR; PG8_MMA(1, 0, At, B0); PG8_MMA(1, 1, At, B1); PG8_BAR; PG8_SCHED;
;         }
;         if (wr == 0) PG8_BAR;
	s_add_i32 s14, s21, s18
	v_lshl_add_u64 v[154:155], v[154:155], 0, s[76:77]
	s_mov_b32 m0, s14
	ds_read_b128 v[196:199], v175 offset:49152
	ds_read_b128 v[200:203], v175 offset:50176
	ds_read_b128 v[204:207], v175 offset:51200
	ds_read_b128 v[208:211], v175 offset:52224
	ds_read_b128 v[220:223], v175 offset:53248
	ds_read_b128 v[224:227], v175 offset:54272
	ds_read_b128 v[228:231], v175 offset:55296
	ds_read_b128 v[232:235], v175 offset:56320
	global_load_lds_dwordx4 v[154:155], off
	s_add_i32 m0, s14, 0x2000
	s_add_u32 s12, s12, 0xa080
	v_lshl_add_u64 v[154:155], v[156:157], 0, s[76:77]
	s_addc_u32 s13, s13, 0
	s_add_i32 s14, s36, s18
	global_load_lds_dwordx4 v[154:155], off
	v_lshl_add_u64 v[154:155], s[12:13], 0, v[144:145]
	s_mov_b32 m0, s14
	s_nop 0
	global_load_lds_dwordx4 v[154:155], off
	v_lshl_add_u64 v[154:155], s[12:13], 0, v[140:141]
	s_add_i32 m0, s14, 0x2000
	s_nop 0
	global_load_lds_dwordx4 v[154:155], off
	v_lshl_add_u64 v[154:155], v[170:171], 0, s[76:77]
	s_mov_b32 m0, s25
	s_nop 0
	global_load_lds_dwordx4 v[154:155], off
	v_lshl_add_u64 v[154:155], v[212:213], 0, s[76:77]
	s_mov_b32 m0, s26
	s_nop 0
	global_load_lds_dwordx4 v[154:155], off
	s_waitcnt vmcnt(8)
	s_waitcnt lgkmcnt(0)
	s_barrier
	s_setprio 1
	s_waitcnt lgkmcnt(0)
	v_mfma_f32_16x16x32_bf16 v[104:107], v[74:77], v[196:199], v[104:107]
	v_mfma_f32_16x16x32_bf16 v[100:103], v[166:169], v[196:199], v[100:103]
	v_mfma_f32_16x16x32_bf16 v[94:97], v[74:77], v[204:207], v[94:97]
	v_mfma_f32_16x16x32_bf16 v[90:93], v[166:169], v[204:207], v[90:93]
	v_mfma_f32_16x16x32_bf16 v[86:89], v[74:77], v[220:223], v[86:89]
	v_mfma_f32_16x16x32_bf16 v[82:85], v[166:169], v[220:223], v[82:85]
	v_mfma_f32_16x16x32_bf16 v[62:65], v[74:77], v[228:231], v[62:65]
	v_mfma_f32_16x16x32_bf16 v[58:61], v[166:169], v[228:231], v[58:61]
	v_mfma_f32_16x16x32_bf16 v[104:107], v[78:81], v[200:203], v[104:107]
	v_mfma_f32_16x16x32_bf16 v[100:103], v[176:179], v[200:203], v[100:103]
	v_mfma_f32_16x16x32_bf16 v[94:97], v[78:81], v[208:211], v[94:97]
	v_mfma_f32_16x16x32_bf16 v[90:93], v[176:179], v[208:211], v[90:93]
	v_mfma_f32_16x16x32_bf16 v[86:89], v[78:81], v[224:227], v[86:89]
	v_mfma_f32_16x16x32_bf16 v[82:85], v[176:179], v[224:227], v[82:85]
	v_mfma_f32_16x16x32_bf16 v[62:65], v[78:81], v[232:235], v[62:65]
	v_mfma_f32_16x16x32_bf16 v[58:61], v[176:179], v[232:235], v[58:61]
	v_mfma_f32_16x16x32_bf16 v[30:33], v[180:183], v[196:199], v[30:33]
	v_mfma_f32_16x16x32_bf16 v[26:29], v[188:191], v[196:199], v[26:29]
	v_mfma_f32_16x16x32_bf16 v[22:25], v[180:183], v[204:207], v[22:25]
	v_mfma_f32_16x16x32_bf16 v[18:21], v[188:191], v[204:207], v[18:21]
	v_mfma_f32_16x16x32_bf16 v[14:17], v[180:183], v[220:223], v[14:17]
	v_mfma_f32_16x16x32_bf16 v[10:13], v[188:191], v[220:223], v[10:13]
	v_mfma_f32_16x16x32_bf16 v[6:9], v[180:183], v[228:231], v[6:9]
	v_mfma_f32_16x16x32_bf16 v[2:5], v[188:191], v[228:231], v[2:5]
	v_mfma_f32_16x16x32_bf16 v[30:33], v[184:187], v[200:203], v[30:33]
	v_mfma_f32_16x16x32_bf16 v[26:29], v[192:195], v[200:203], v[26:29]
	v_mfma_f32_16x16x32_bf16 v[22:25], v[184:187], v[208:211], v[22:25]
	v_mfma_f32_16x16x32_bf16 v[18:21], v[192:195], v[208:211], v[18:21]
	v_mfma_f32_16x16x32_bf16 v[14:17], v[184:187], v[224:227], v[14:17]
	v_mfma_f32_16x16x32_bf16 v[10:13], v[192:195], v[224:227], v[10:13]
	v_mfma_f32_16x16x32_bf16 v[6:9], v[184:187], v[232:235], v[6:9]
	v_mfma_f32_16x16x32_bf16 v[2:5], v[192:195], v[232:235], v[2:5]
	s_setprio 0
	s_barrier
	s_add_i32 s35, s35, 2
	s_add_u32 s31, s31, 0x100
	s_addc_u32 s34, s34, 0
	s_cmp_gt_u32 s35, 7
	s_mov_b64 s[14:15], s[2:3]
	s_cbranch_scc0 .LBB0_433
	s_and_b64 vcc, exec, s[4:5]
	s_cbranch_vccz .LBB0_436
	s_barrier

; #define PG8_STAGE(bufoff, gbase, voff) do { _Pragma("unroll") for (int _i = 0; _i < 2; ++_i) \
;         __builtin_amdgcn_global_load_lds((const unsigned*)((const char*)(gbase) + (voff)[_i]), (LAS unsigned*)(lds + (bufoff) + ldsw + _i * 8192), 16, 0, 0); } while (0)
; #define PG8_LDA(dst, b, h) do { _Pragma("unroll") for (int m = 0; m < 4; ++m) _Pragma("unroll") for (int k = 0; k < 2; ++k) dst[m][k] = *(const LAS bf16x8*)(lds + PG8_SA(b, h) + aoff + m * 2048 + k * 1024); } while (0)
; #define PG8_LDB(dst, b, h) do { _Pragma("unroll") for (int n = 0; n < 2; ++n) _Pragma("unroll") for (int k = 0; k < 2; ++k) dst[n][k] = *(const LAS bf16x8*)(lds + PG8_SB(b, h) + boff + n * 2048 + k * 1024); } while (0)
; #define PG8_MMA(ai, bj, At, Bt) do { __builtin_amdgcn_s_setprio(1); _Pragma("unroll") for (int m = 0; m < 4; ++m) _Pragma("unroll") for (int n = 0; n < 2; ++n) _Pragma("unroll") for (int k = 0; k < 2; ++k) \
;         acc[ai][bj][m][n] = __builtin_amdgcn_mfma_f32_16x16x32_bf16(Bt[n][k], At[m][k], acc[ai][bj][m][n], 0, 0, 0); __builtin_amdgcn_s_setprio(0); } while (0)
; #define PG8_WAIT_V(n) asm volatile("s_waitcnt vmcnt(" #n ")" ::: "memory")
; #define PG8_WAIT_L(n) asm volatile("s_waitcnt lgkmcnt(" #n ")" ::: "memory")
; #define PG8_BAR __builtin_amdgcn_s_barrier()
; #define PG8_SCHED __builtin_amdgcn_sched_barrier(0)
; template <class Epi, class Sched>
; __device__ __forceinline__ void gemm_phase(LAS unsigned char* lds, const Gemm g, const Sched& S, const Epi& E) {
;     ...
;         for (int t = 0; t < nt; t += 2) {
;             const bool last = (t == nt - 2);
;             const char* a1 = cA + (size_t)(t + 1) * kstepA;
;             const char* a2 = last ? nA : cA + (size_t)(t + 2) * kstepA; const char* b2 = last ? nB : cB + (size_t)(t + 2) * kstep;
;             const char* a3 = a2 + kstepA; const char* b3 = b2 + kstep;
;             PG8_LDB(B0, 0, 0); PG8_LDB(B1, 0, 1); PG8_SCHED; PG8_LDA(At, 0, 0); PG8_STAGE(PG8_SA(1, 1), a1 + hA, voffA);
;             PG8_WAIT_V(8); PG8_WAIT_L(0); PG8_BAR; PG8_MMA(0, 0, At, B0); PG8_MMA(0, 1, At, B1); PG8_BAR; PG8_SCHED;
;             PG8_LDA(At, 0, 1); PG8_STAGE(PG8_SB(0, 0), b2, voffB); PG8_STAGE(PG8_SB(0, 1), b2 + hB, voffB); PG8_STAGE(PG8_SA(0, 0), a2, voffA);
;             PG8_WAIT_V(8); PG8_WAIT_L(0); PG8_BAR; PG8_MMA(1, 0, At, B0); PG8_MMA(1, 1, At, B1); PG8_BAR; PG8_SCHED;
.LBB0_640:
	s_add_u32 s18, s16, 0xfffe0080
	s_addc_u32 s19, s17, -1
	s_add_i32 s40, 0, 0x10000
	s_cmp_eq_u32 s39, 4
	s_cselect_b32 s21, s9, s19
	s_cselect_b32 s20, s35, s18
	v_add_u32_e32 v98, s40, v147
	s_cselect_b32 s19, s7, s38
	s_cselect_b32 s18, s36, s37
	s_add_i32 s42, 0, 0x14000
	ds_read_b128 v[154:157], v98
	ds_read_b128 v[160:163], v98 offset:1024
	ds_read_b128 v[164:167], v98 offset:2048
	ds_read_b128 v[168:171], v98 offset:3072
	v_add_u32_e32 v98, s42, v147
	ds_read_b128 v[172:175], v98
	ds_read_b128 v[176:179], v98 offset:1024
	ds_read_b128 v[180:183], v98 offset:2048
	ds_read_b128 v[184:187], v98 offset:3072
	v_lshl_add_u64 v[144:145], s[16:17], 0, v[140:141]
	s_add_i32 m0, s25, 0xc000
	ds_read_b128 v[188:191], v159
	ds_read_b128 v[192:195], v159 offset:1024
	ds_read_b128 v[196:199], v159 offset:2048
	ds_read_b128 v[200:203], v159 offset:3072
	ds_read_b128 v[204:207], v159 offset:4096
	ds_read_b128 v[208:211], v159 offset:5120
	ds_read_b128 v[220:223], v159 offset:6144
	ds_read_b128 v[224:227], v159 offset:7168
	global_load_lds_dwordx4 v[144:145], off
	v_lshl_add_u64 v[144:145], s[16:17], 0, v[142:143]
	s_add_i32 m0, s25, 0xe000
	s_nop 0
	global_load_lds_dwordx4 v[144:145], off
	s_waitcnt vmcnt(8)
	s_waitcnt lgkmcnt(0)
	s_barrier
	s_setprio 1
	s_waitcnt lgkmcnt(0)
	v_mfma_f32_16x16x32_bf16 v[124:127], v[154:157], v[188:191], v[124:127]
	v_mfma_f32_16x16x32_bf16 v[116:119], v[164:167], v[188:191], v[116:119]
	v_mfma_f32_16x16x32_bf16 v[108:111], v[154:157], v[196:199], v[108:111]
	v_mfma_f32_16x16x32_bf16 v[100:103], v[164:167], v[196:199], v[100:103]
	v_mfma_f32_16x16x32_bf16 v[90:93], v[154:157], v[204:207], v[90:93]
	v_mfma_f32_16x16x32_bf16 v[82:85], v[164:167], v[204:207], v[82:85]
	v_mfma_f32_16x16x32_bf16 v[74:77], v[154:157], v[220:223], v[74:77]
	v_mfma_f32_16x16x32_bf16 v[66:69], v[164:167], v[220:223], v[66:69]
	v_mfma_f32_16x16x32_bf16 v[124:127], v[160:163], v[192:195], v[124:127]
	v_mfma_f32_16x16x32_bf16 v[116:119], v[168:171], v[192:195], v[116:119]
	v_mfma_f32_16x16x32_bf16 v[108:111], v[160:163], v[200:203], v[108:111]
	v_mfma_f32_16x16x32_bf16 v[100:103], v[168:171], v[200:203], v[100:103]
	v_mfma_f32_16x16x32_bf16 v[90:93], v[160:163], v[208:211], v[90:93]
	v_mfma_f32_16x16x32_bf16 v[82:85], v[168:171], v[208:211], v[82:85]
	v_mfma_f32_16x16x32_bf16 v[74:77], v[160:163], v[224:227], v[74:77]
	v_mfma_f32_16x16x32_bf16 v[66:69], v[168:171], v[224:227], v[66:69]
	v_mfma_f32_16x16x32_bf16 v[128:131], v[172:175], v[188:191], v[128:131]
	v_mfma_f32_16x16x32_bf16 v[120:123], v[180:183], v[188:191], v[120:123]
	v_mfma_f32_16x16x32_bf16 v[112:115], v[172:175], v[196:199], v[112:115]
	v_mfma_f32_16x16x32_bf16 v[104:107], v[180:183], v[196:199], v[104:107]
	v_mfma_f32_16x16x32_bf16 v[94:97], v[172:175], v[204:207], v[94:97]
	v_mfma_f32_16x16x32_bf16 v[86:89], v[180:183], v[204:207], v[86:89]
	v_mfma_f32_16x16x32_bf16 v[78:81], v[172:175], v[220:223], v[78:81]
	v_mfma_f32_16x16x32_bf16 v[70:73], v[180:183], v[220:223], v[70:73]
	v_mfma_f32_16x16x32_bf16 v[128:131], v[176:179], v[192:195], v[128:131]
	v_mfma_f32_16x16x32_bf16 v[120:123], v[184:187], v[192:195], v[120:123]
	v_mfma_f32_16x16x32_bf16 v[112:115], v[176:179], v[200:203], v[112:115]
	v_mfma_f32_16x16x32_bf16 v[104:107], v[184:187], v[200:203], v[104:107]
	v_mfma_f32_16x16x32_bf16 v[94:97], v[176:179], v[208:211], v[94:97]
	v_mfma_f32_16x16x32_bf16 v[86:89], v[184:187], v[208:211], v[86:89]
	v_mfma_f32_16x16x32_bf16 v[78:81], v[176:179], v[224:227], v[78:81]
	v_mfma_f32_16x16x32_bf16 v[70:73], v[184:187], v[224:227], v[70:73]
	s_setprio 0
	s_barrier
	s_add_i32 s40, s40, s24
	v_lshl_add_u64 v[144:145], s[18:19], 0, v[136:137]
	s_mov_b32 m0, s40
	ds_read_b128 v[188:191], v159 offset:16384
	ds_read_b128 v[192:195], v159 offset:17408
	ds_read_b128 v[196:199], v159 offset:18432
	ds_read_b128 v[200:203], v159 offset:19456
	ds_read_b128 v[204:207], v159 offset:20480
	ds_read_b128 v[208:211], v159 offset:21504
	ds_read_b128 v[220:223], v159 offset:22528
	ds_read_b128 v[224:227], v159 offset:23552
	global_load_lds_dwordx4 v[144:145], off
	s_add_i32 m0, s40, 0x2000
	s_add_u32 s40, s18, 0x8000
	v_lshl_add_u64 v[212:213], s[18:19], 0, v[132:133]
	s_addc_u32 s41, s19, 0
	s_add_i32 s42, s42, s24
	global_load_lds_dwordx4 v[212:213], off
	v_lshl_add_u64 v[228:229], s[40:41], 0, v[136:137]
	s_mov_b32 m0, s42
	v_lshl_add_u64 v[230:231], s[20:21], 0, v[134:135]
	global_load_lds_dwordx4 v[228:229], off
	v_lshl_add_u64 v[228:229], s[40:41], 0, v[132:133]
	s_add_i32 m0, s42, 0x2000
	s_nop 0
	global_load_lds_dwordx4 v[228:229], off
	v_lshl_add_u64 v[228:229], s[20:21], 0, v[138:139]
	s_mov_b32 m0, s25
	s_nop 0
	global_load_lds_dwordx4 v[228:229], off
	s_mov_b32 m0, s26
	s_nop 0
	global_load_lds_dwordx4 v[230:231], off
	s_waitcnt vmcnt(8)
	s_waitcnt lgkmcnt(0)
	s_barrier
; #define PG8_STAGE(bufoff, gbase, voff) do { _Pragma("unroll") for (int _i = 0; _i < 2; ++_i) \
;         __builtin_amdgcn_global_load_lds((const unsigned*)((const char*)(gbase) + (voff)[_i]), (LAS unsigned*)(lds + (bufoff) + ldsw + _i * 8192), 16, 0, 0); } while (0)
; #define PG8_LDA(dst, b, h) do { _Pragma("unroll") for (int m = 0; m < 4; ++m) _Pragma("unroll") for (int k = 0; k < 2; ++k) dst[m][k] = *(const LAS bf16x8*)(lds + PG8_SA(b, h) + aoff + m * 2048 + k * 1024); } while (0)
; #define PG8_LDB(dst, b, h) do { _Pragma("unroll") for (int n = 0; n < 2; ++n) _Pragma("unroll") for (int k = 0; k < 2; ++k) dst[n][k] = *(const LAS bf16x8*)(lds + PG8_SB(b, h) + boff + n * 2048 + k * 1024); } while (0)
; #define PG8_MMA(ai, bj, At, Bt) do { __builtin_amdgcn_s_setprio(1); _Pragma("unroll") for (int m = 0; m < 4; ++m) _Pragma("unroll") for (int n = 0; n < 2; ++n) _Pragma("unroll") for (int k = 0; k < 2; ++k) \
;         acc[ai][bj][m][n] = __builtin_amdgcn_mfma_f32_16x16x32_bf16(Bt[n][k], At[m][k], acc[ai][bj][m][n], 0, 0, 0); __builtin_amdgcn_s_setprio(0); } while (0)
; #define PG8_WAIT_V(n) asm volatile("s_waitcnt vmcnt(" #n ")" ::: "memory")
; #define PG8_WAIT_L(n) asm volatile("s_waitcnt lgkmcnt(" #n ")" ::: "memory")
; #define PG8_BAR __builtin_amdgcn_s_barrier()
; #define PG8_SCHED __builtin_amdgcn_sched_barrier(0)
; template <class Epi, class Sched>
; __device__ __forceinline__ void gemm_phase(LAS unsigned char* lds, const Gemm g, const Sched& S, const Epi& E) {
;     ...
;             PG8_WAIT_V(8); PG8_WAIT_L(0); PG8_BAR; PG8_MMA(1, 0, At, B0); PG8_MMA(1, 1, At, B1); PG8_BAR; PG8_SCHED;
;             PG8_LDB(B0, 1, 0); PG8_LDB(B1, 1, 1); PG8_SCHED; PG8_LDA(At, 1, 0); PG8_STAGE(PG8_SA(0, 1), a2 + hA, voffA);
;             PG8_WAIT_V(8); PG8_WAIT_L(0); PG8_BAR; PG8_MMA(0, 0, At, B0); PG8_MMA(0, 1, At, B1); PG8_BAR; PG8_SCHED;
;             PG8_LDA(At, 1, 1); PG8_STAGE(PG8_SB(1, 0), b3, voffB); PG8_STAGE(PG8_SB(1, 1), b3 + hB, voffB); PG8_STAGE(PG8_SA(1, 0), a3, voffA);
;             PG8_WAIT_V(8); PG8_WAIT_L(0); PG8_BAR; PG8_MMA(1, 0, At, B0); PG8_MMA(1, 1, At, B1); PG8_BAR; PG8_SCHED;
	s_setprio 1
	s_waitcnt lgkmcnt(0)
	v_mfma_f32_16x16x32_bf16 v[58:61], v[154:157], v[188:191], v[58:61]
	v_mfma_f32_16x16x32_bf16 v[50:53], v[164:167], v[188:191], v[50:53]
	v_mfma_f32_16x16x32_bf16 v[42:45], v[154:157], v[196:199], v[42:45]
	v_mfma_f32_16x16x32_bf16 v[34:37], v[164:167], v[196:199], v[34:37]
	v_mfma_f32_16x16x32_bf16 v[26:29], v[154:157], v[204:207], v[26:29]
	v_mfma_f32_16x16x32_bf16 v[18:21], v[164:167], v[204:207], v[18:21]
	v_mfma_f32_16x16x32_bf16 v[10:13], v[154:157], v[220:223], v[10:13]
	v_mfma_f32_16x16x32_bf16 v[6:9], v[164:167], v[220:223], v[6:9]
	v_mfma_f32_16x16x32_bf16 v[58:61], v[160:163], v[192:195], v[58:61]
	v_mfma_f32_16x16x32_bf16 v[50:53], v[168:171], v[192:195], v[50:53]
	v_mfma_f32_16x16x32_bf16 v[42:45], v[160:163], v[200:203], v[42:45]
	v_mfma_f32_16x16x32_bf16 v[34:37], v[168:171], v[200:203], v[34:37]
	v_mfma_f32_16x16x32_bf16 v[26:29], v[160:163], v[208:211], v[26:29]
	v_mfma_f32_16x16x32_bf16 v[18:21], v[168:171], v[208:211], v[18:21]
	v_mfma_f32_16x16x32_bf16 v[10:13], v[160:163], v[224:227], v[10:13]
	v_mfma_f32_16x16x32_bf16 v[6:9], v[168:171], v[224:227], v[6:9]
	v_mfma_f32_16x16x32_bf16 v[62:65], v[172:175], v[188:191], v[62:65]
	v_mfma_f32_16x16x32_bf16 v[54:57], v[180:183], v[188:191], v[54:57]
	v_mfma_f32_16x16x32_bf16 v[46:49], v[172:175], v[196:199], v[46:49]
	v_mfma_f32_16x16x32_bf16 v[38:41], v[180:183], v[196:199], v[38:41]
	v_mfma_f32_16x16x32_bf16 v[30:33], v[172:175], v[204:207], v[30:33]
	v_mfma_f32_16x16x32_bf16 v[22:25], v[180:183], v[204:207], v[22:25]
	v_mfma_f32_16x16x32_bf16 v[14:17], v[172:175], v[220:223], v[14:17]
	v_mfma_f32_16x16x32_bf16 v[2:5], v[180:183], v[220:223], v[2:5]
	v_mfma_f32_16x16x32_bf16 v[62:65], v[176:179], v[192:195], v[62:65]
	v_mfma_f32_16x16x32_bf16 v[54:57], v[184:187], v[192:195], v[54:57]
	v_mfma_f32_16x16x32_bf16 v[46:49], v[176:179], v[200:203], v[46:49]
	v_mfma_f32_16x16x32_bf16 v[38:41], v[184:187], v[200:203], v[38:41]
	v_mfma_f32_16x16x32_bf16 v[30:33], v[176:179], v[208:211], v[30:33]
	v_mfma_f32_16x16x32_bf16 v[22:25], v[184:187], v[208:211], v[22:25]
	v_mfma_f32_16x16x32_bf16 v[14:17], v[176:179], v[224:227], v[14:17]
	v_mfma_f32_16x16x32_bf16 v[2:5], v[184:187], v[224:227], v[2:5]
	s_setprio 0
	s_barrier
	s_add_i32 s40, 0, 0x18000
	v_add_u32_e32 v98, s40, v147
	s_add_i32 s41, 0, 0x1c000
	ds_read_b128 v[154:157], v98
	ds_read_b128 v[160:163], v98 offset:1024
	ds_read_b128 v[164:167], v98 offset:2048
	ds_read_b128 v[168:171], v98 offset:3072
	v_add_u32_e32 v98, s41, v147
	ds_read_b128 v[172:175], v98
	ds_read_b128 v[176:179], v98 offset:1024
	ds_read_b128 v[180:183], v98 offset:2048
	ds_read_b128 v[184:187], v98 offset:3072
	s_add_u32 s20, s20, 0x20000
	s_addc_u32 s21, s21, 0
	s_mov_b32 m0, s27
	v_lshl_add_u64 v[232:233], s[20:21], 0, v[138:139]
	ds_read_b128 v[188:191], v159 offset:32768
	ds_read_b128 v[192:195], v159 offset:33792
	ds_read_b128 v[196:199], v159 offset:34816
	ds_read_b128 v[200:203], v159 offset:35840
	ds_read_b128 v[204:207], v159 offset:36864
	ds_read_b128 v[208:211], v159 offset:37888
	ds_read_b128 v[220:223], v159 offset:38912
	ds_read_b128 v[224:227], v159 offset:39936
	global_load_lds_dwordx4 v[232:233], off
	v_lshl_add_u64 v[232:233], s[20:21], 0, v[134:135]
	s_mov_b32 m0, s28
	s_nop 0
	global_load_lds_dwordx4 v[232:233], off
	s_waitcnt vmcnt(8)
	s_waitcnt lgkmcnt(0)
	s_barrier
	s_setprio 1
	s_waitcnt lgkmcnt(0)
	v_mfma_f32_16x16x32_bf16 v[124:127], v[154:157], v[188:191], v[124:127]
	v_mfma_f32_16x16x32_bf16 v[116:119], v[164:167], v[188:191], v[116:119]
	v_mfma_f32_16x16x32_bf16 v[108:111], v[154:157], v[196:199], v[108:111]
	v_mfma_f32_16x16x32_bf16 v[100:103], v[164:167], v[196:199], v[100:103]
	v_mfma_f32_16x16x32_bf16 v[90:93], v[154:157], v[204:207], v[90:93]
	v_mfma_f32_16x16x32_bf16 v[82:85], v[164:167], v[204:207], v[82:85]
	v_mfma_f32_16x16x32_bf16 v[74:77], v[154:157], v[220:223], v[74:77]
	v_mfma_f32_16x16x32_bf16 v[66:69], v[164:167], v[220:223], v[66:69]
	v_mfma_f32_16x16x32_bf16 v[124:127], v[160:163], v[192:195], v[124:127]
	v_mfma_f32_16x16x32_bf16 v[116:119], v[168:171], v[192:195], v[116:119]
	v_mfma_f32_16x16x32_bf16 v[108:111], v[160:163], v[200:203], v[108:111]
	v_mfma_f32_16x16x32_bf16 v[100:103], v[168:171], v[200:203], v[100:103]
	v_mfma_f32_16x16x32_bf16 v[90:93], v[160:163], v[208:211], v[90:93]
	v_mfma_f32_16x16x32_bf16 v[82:85], v[168:171], v[208:211], v[82:85]
	v_mfma_f32_16x16x32_bf16 v[74:77], v[160:163], v[224:227], v[74:77]
	v_mfma_f32_16x16x32_bf16 v[66:69], v[168:171], v[224:227], v[66:69]
	v_mfma_f32_16x16x32_bf16 v[128:131], v[172:175], v[188:191], v[128:131]
	v_mfma_f32_16x16x32_bf16 v[120:123], v[180:183], v[188:191], v[120:123]
	v_mfma_f32_16x16x32_bf16 v[112:115], v[172:175], v[196:199], v[112:115]
	v_mfma_f32_16x16x32_bf16 v[104:107], v[180:183], v[196:199], v[104:107]
	v_mfma_f32_16x16x32_bf16 v[94:97], v[172:175], v[204:207], v[94:97]
	v_mfma_f32_16x16x32_bf16 v[86:89], v[180:183], v[204:207], v[86:89]
	v_mfma_f32_16x16x32_bf16 v[78:81], v[172:175], v[220:223], v[78:81]
	v_mfma_f32_16x16x32_bf16 v[70:73], v[180:183], v[220:223], v[70:73]
	v_mfma_f32_16x16x32_bf16 v[128:131], v[176:179], v[192:195], v[128:131]
	v_mfma_f32_16x16x32_bf16 v[120:123], v[184:187], v[192:195], v[120:123]
	v_mfma_f32_16x16x32_bf16 v[112:115], v[176:179], v[200:203], v[112:115]
	v_mfma_f32_16x16x32_bf16 v[104:107], v[184:187], v[200:203], v[104:107]
	v_mfma_f32_16x16x32_bf16 v[94:97], v[176:179], v[208:211], v[94:97]
	v_mfma_f32_16x16x32_bf16 v[86:89], v[184:187], v[208:211], v[86:89]
	v_mfma_f32_16x16x32_bf16 v[78:81], v[176:179], v[224:227], v[78:81]
	v_mfma_f32_16x16x32_bf16 v[70:73], v[184:187], v[224:227], v[70:73]
	s_setprio 0
	s_barrier
; #define PG8_STAGE(bufoff, gbase, voff) do { _Pragma("unroll") for (int _i = 0; _i < 2; ++_i) \
;         __builtin_amdgcn_global_load_lds((const unsigned*)((const char*)(gbase) + (voff)[_i]), (LAS unsigned*)(lds + (bufoff) + ldsw + _i * 8192), 16, 0, 0); } while (0)
; #define PG8_LDA(dst, b, h) do { _Pragma("unroll") for (int m = 0; m < 4; ++m) _Pragma("unroll") for (int k = 0; k < 2; ++k) dst[m][k] = *(const LAS bf16x8*)(lds + PG8_SA(b, h) + aoff + m * 2048 + k * 1024); } while (0)
; #define PG8_MMA(ai, bj, At, Bt) do { __builtin_amdgcn_s_setprio(1); _Pragma("unroll") for (int m = 0; m < 4; ++m) _Pragma("unroll") for (int n = 0; n < 2; ++n) _Pragma("unroll") for (int k = 0; k < 2; ++k) \
;         acc[ai][bj][m][n] = __builtin_amdgcn_mfma_f32_16x16x32_bf16(Bt[n][k], At[m][k], acc[ai][bj][m][n], 0, 0, 0); __builtin_amdgcn_s_setprio(0); } while (0)
; #define PG8_WAIT_V(n) asm volatile("s_waitcnt vmcnt(" #n ")" ::: "memory")
; #define PG8_WAIT_L(n) asm volatile("s_waitcnt lgkmcnt(" #n ")" ::: "memory")
; #define PG8_BAR __builtin_amdgcn_s_barrier()
; #define PG8_SCHED __builtin_amdgcn_sched_barrier(0)
; template <class Epi, class Sched>
; __device__ __forceinline__ void gemm_phase(LAS unsigned char* lds, const Gemm g, const Sched& S, const Epi& E) {
;     ...
;             PG8_LDA(At, 1, 1); PG8_STAGE(PG8_SB(1, 0), b3, voffB); PG8_STAGE(PG8_SB(1, 1), b3 + hB, voffB); PG8_STAGE(PG8_SA(1, 0), a3, voffA);
;             PG8_WAIT_V(8); PG8_WAIT_L(0); PG8_BAR; PG8_MMA(1, 0, At, B0); PG8_MMA(1, 1, At, B1); PG8_BAR; PG8_SCHED;
;         }
;         if (wr == 0) PG8_BAR;
	s_add_i32 s20, s40, s24
	v_lshl_add_u64 v[144:145], v[144:145], 0, s[76:77]
	s_mov_b32 m0, s20
	ds_read_b128 v[188:191], v159 offset:49152
	ds_read_b128 v[192:195], v159 offset:50176
	ds_read_b128 v[196:199], v159 offset:51200
	ds_read_b128 v[200:203], v159 offset:52224
	ds_read_b128 v[204:207], v159 offset:53248
	ds_read_b128 v[208:211], v159 offset:54272
	ds_read_b128 v[220:223], v159 offset:55296
	ds_read_b128 v[224:227], v159 offset:56320
	global_load_lds_dwordx4 v[144:145], off
	s_add_i32 m0, s20, 0x2000
	s_add_u32 s18, s18, 0x8080
	v_lshl_add_u64 v[144:145], v[212:213], 0, s[76:77]
	s_addc_u32 s19, s19, 0
	s_add_i32 s20, s41, s24
	global_load_lds_dwordx4 v[144:145], off
	v_lshl_add_u64 v[144:145], s[18:19], 0, v[136:137]
	s_mov_b32 m0, s20
	s_nop 0
	global_load_lds_dwordx4 v[144:145], off
	v_lshl_add_u64 v[144:145], s[18:19], 0, v[132:133]
	s_add_i32 m0, s20, 0x2000
	s_nop 0
	global_load_lds_dwordx4 v[144:145], off
	v_lshl_add_u64 v[144:145], v[228:229], 0, s[76:77]
	s_mov_b32 m0, s29
	s_nop 0
	global_load_lds_dwordx4 v[144:145], off
	v_lshl_add_u64 v[144:145], v[230:231], 0, s[76:77]
	s_mov_b32 m0, s30
	s_nop 0
	global_load_lds_dwordx4 v[144:145], off
	s_waitcnt vmcnt(8)
	s_waitcnt lgkmcnt(0)
	s_barrier
	s_setprio 1
	s_waitcnt lgkmcnt(0)
	v_mfma_f32_16x16x32_bf16 v[58:61], v[154:157], v[188:191], v[58:61]
	v_mfma_f32_16x16x32_bf16 v[50:53], v[164:167], v[188:191], v[50:53]
	v_mfma_f32_16x16x32_bf16 v[42:45], v[154:157], v[196:199], v[42:45]
	v_mfma_f32_16x16x32_bf16 v[34:37], v[164:167], v[196:199], v[34:37]
	v_mfma_f32_16x16x32_bf16 v[26:29], v[154:157], v[204:207], v[26:29]
	v_mfma_f32_16x16x32_bf16 v[18:21], v[164:167], v[204:207], v[18:21]
	v_mfma_f32_16x16x32_bf16 v[10:13], v[154:157], v[220:223], v[10:13]
	v_mfma_f32_16x16x32_bf16 v[6:9], v[164:167], v[220:223], v[6:9]
	v_mfma_f32_16x16x32_bf16 v[58:61], v[160:163], v[192:195], v[58:61]
	v_mfma_f32_16x16x32_bf16 v[50:53], v[168:171], v[192:195], v[50:53]
	v_mfma_f32_16x16x32_bf16 v[42:45], v[160:163], v[200:203], v[42:45]
	v_mfma_f32_16x16x32_bf16 v[34:37], v[168:171], v[200:203], v[34:37]
	v_mfma_f32_16x16x32_bf16 v[26:29], v[160:163], v[208:211], v[26:29]
	v_mfma_f32_16x16x32_bf16 v[18:21], v[168:171], v[208:211], v[18:21]
	v_mfma_f32_16x16x32_bf16 v[10:13], v[160:163], v[224:227], v[10:13]
	v_mfma_f32_16x16x32_bf16 v[6:9], v[168:171], v[224:227], v[6:9]
	v_mfma_f32_16x16x32_bf16 v[62:65], v[172:175], v[188:191], v[62:65]
	v_mfma_f32_16x16x32_bf16 v[54:57], v[180:183], v[188:191], v[54:57]
	v_mfma_f32_16x16x32_bf16 v[46:49], v[172:175], v[196:199], v[46:49]
	v_mfma_f32_16x16x32_bf16 v[38:41], v[180:183], v[196:199], v[38:41]
	v_mfma_f32_16x16x32_bf16 v[30:33], v[172:175], v[204:207], v[30:33]
	v_mfma_f32_16x16x32_bf16 v[22:25], v[180:183], v[204:207], v[22:25]
	v_mfma_f32_16x16x32_bf16 v[14:17], v[172:175], v[220:223], v[14:17]
	v_mfma_f32_16x16x32_bf16 v[2:5], v[180:183], v[220:223], v[2:5]
	v_mfma_f32_16x16x32_bf16 v[62:65], v[176:179], v[192:195], v[62:65]
	v_mfma_f32_16x16x32_bf16 v[54:57], v[184:187], v[192:195], v[54:57]
	v_mfma_f32_16x16x32_bf16 v[46:49], v[176:179], v[200:203], v[46:49]
	v_mfma_f32_16x16x32_bf16 v[38:41], v[184:187], v[200:203], v[38:41]
	v_mfma_f32_16x16x32_bf16 v[30:33], v[176:179], v[208:211], v[30:33]
	v_mfma_f32_16x16x32_bf16 v[22:25], v[184:187], v[208:211], v[22:25]
	v_mfma_f32_16x16x32_bf16 v[14:17], v[176:179], v[224:227], v[14:17]
	v_mfma_f32_16x16x32_bf16 v[2:5], v[184:187], v[224:227], v[2:5]
	s_setprio 0
	s_barrier
	s_add_i32 s39, s39, 2
	s_add_u32 s16, s16, 0x100
	s_addc_u32 s17, s17, 0
	s_add_u32 s37, s37, 0x100
	s_addc_u32 s38, s38, 0
	s_cmp_gt_u32 s39, 5
	s_cbranch_scc0 .LBB0_640
	s_and_b64 vcc, exec, s[4:5]
	s_cbranch_vccz .LBB0_643
	s_barrier

; #define PG8_STAGE(bufoff, gbase, voff) do { _Pragma("unroll") for (int _i = 0; _i < 2; ++_i) \
;         __builtin_amdgcn_global_load_lds((const unsigned*)((const char*)(gbase) + (voff)[_i]), (LAS unsigned*)(lds + (bufoff) + ldsw + _i * 8192), 16, 0, 0); } while (0)
; #define PG8_LDA(dst, b, h) do { _Pragma("unroll") for (int m = 0; m < 4; ++m) _Pragma("unroll") for (int k = 0; k < 2; ++k) dst[m][k] = *(const LAS bf16x8*)(lds + PG8_SA(b, h) + aoff + m * 2048 + k * 1024); } while (0)
; #define PG8_LDB(dst, b, h) do { _Pragma("unroll") for (int n = 0; n < 2; ++n) _Pragma("unroll") for (int k = 0; k < 2; ++k) dst[n][k] = *(const LAS bf16x8*)(lds + PG8_SB(b, h) + boff + n * 2048 + k * 1024); } while (0)
; #define PG8_MMA(ai, bj, At, Bt) do { __builtin_amdgcn_s_setprio(1); _Pragma("unroll") for (int m = 0; m < 4; ++m) _Pragma("unroll") for (int n = 0; n < 2; ++n) _Pragma("unroll") for (int k = 0; k < 2; ++k) \
;         acc[ai][bj][m][n] = __builtin_amdgcn_mfma_f32_16x16x32_bf16(Bt[n][k], At[m][k], acc[ai][bj][m][n], 0, 0, 0); __builtin_amdgcn_s_setprio(0); } while (0)
; #define PG8_WAIT_V(n) asm volatile("s_waitcnt vmcnt(" #n ")" ::: "memory")
; #define PG8_WAIT_L(n) asm volatile("s_waitcnt lgkmcnt(" #n ")" ::: "memory")
; #define PG8_BAR __builtin_amdgcn_s_barrier()
; #define PG8_SCHED __builtin_amdgcn_sched_barrier(0)
; template <class Epi, class Sched>
; __device__ __forceinline__ void gemm_phase(LAS unsigned char* lds, const Gemm g, const Sched& S, const Epi& E) {
;     ...
;         for (int t = 0; t < nt; t += 2) {
;             const bool last = (t == nt - 2);
;             const char* a1 = cA + (size_t)(t + 1) * kstepA;
;             const char* a2 = last ? nA : cA + (size_t)(t + 2) * kstepA; const char* b2 = last ? nB : cB + (size_t)(t + 2) * kstep;
;             const char* a3 = a2 + kstepA; const char* b3 = b2 + kstep;
;             PG8_LDB(B0, 0, 0); PG8_LDB(B1, 0, 1); PG8_SCHED; PG8_LDA(At, 0, 0); PG8_STAGE(PG8_SA(1, 1), a1 + hA, voffA);
;             PG8_WAIT_V(8); PG8_WAIT_L(0); PG8_BAR; PG8_MMA(0, 0, At, B0); PG8_MMA(0, 1, At, B1); PG8_BAR; PG8_SCHED;
;             PG8_LDA(At, 0, 1); PG8_STAGE(PG8_SB(0, 0), b2, voffB); PG8_STAGE(PG8_SB(0, 1), b2 + hB, voffB); PG8_STAGE(PG8_SA(0, 0), a2, voffA);
;             PG8_WAIT_V(8); PG8_WAIT_L(0); PG8_BAR; PG8_MMA(1, 0, At, B0); PG8_MMA(1, 1, At, B1); PG8_BAR; PG8_SCHED;
.LBB0_708:
	s_add_i32 s48, s20, 2
	s_add_u32 s21, s2, 0xfff80080
	s_addc_u32 s22, s3, -1
	s_add_i32 s50, 0, 0x10000
	s_cmp_eq_u32 s43, s20
	s_cselect_b32 s23, s13, s22
	s_cselect_b32 s22, s15, s21
	v_add_u32_e32 v98, s50, v178
	s_cselect_b32 s21, s9, s47
	s_cselect_b32 s20, s42, s46
	s_add_i32 s52, 0, 0x14000
	ds_read_b128 v[154:157], v98
	ds_read_b128 v[160:163], v98 offset:1024
	ds_read_b128 v[164:167], v98 offset:2048
	ds_read_b128 v[168:171], v98 offset:3072
	v_add_u32_e32 v98, s52, v178
	ds_read_b128 v[172:175], v98
	ds_read_b128 v[180:183], v98 offset:1024
	ds_read_b128 v[184:187], v98 offset:2048
	ds_read_b128 v[188:191], v98 offset:3072
	v_lshl_add_u64 v[100:101], s[2:3], 0, v[146:147]
	s_add_i32 m0, s29, 0xc000
	ds_read_b128 v[192:195], v179
	ds_read_b128 v[196:199], v179 offset:1024
	ds_read_b128 v[200:203], v179 offset:2048
	ds_read_b128 v[204:207], v179 offset:3072
	ds_read_b128 v[208:211], v179 offset:4096
	ds_read_b128 v[220:223], v179 offset:5120
	ds_read_b128 v[224:227], v179 offset:6144
	ds_read_b128 v[228:231], v179 offset:7168
	global_load_lds_dwordx4 v[100:101], off
	v_lshl_add_u64 v[100:101], s[2:3], 0, v[158:159]
	s_add_i32 m0, s29, 0xe000
	s_nop 0
	global_load_lds_dwordx4 v[100:101], off
	s_waitcnt vmcnt(8)
	s_waitcnt lgkmcnt(0)
	s_barrier
	s_setprio 1
	s_waitcnt lgkmcnt(0)
	v_mfma_f32_16x16x32_bf16 v[130:133], v[154:157], v[192:195], v[130:133]
	v_mfma_f32_16x16x32_bf16 v[126:129], v[164:167], v[192:195], v[126:129]
	v_mfma_f32_16x16x32_bf16 v[122:125], v[154:157], v[200:203], v[122:125]
	v_mfma_f32_16x16x32_bf16 v[118:121], v[164:167], v[200:203], v[118:121]
	v_mfma_f32_16x16x32_bf16 v[114:117], v[154:157], v[208:211], v[114:117]
	v_mfma_f32_16x16x32_bf16 v[110:113], v[164:167], v[208:211], v[110:113]
	v_mfma_f32_16x16x32_bf16 v[106:109], v[154:157], v[224:227], v[106:109]
	v_mfma_f32_16x16x32_bf16 v[100:103], v[164:167], v[224:227], v[102:105]
	v_mfma_f32_16x16x32_bf16 v[130:133], v[160:163], v[196:199], v[130:133]
	v_mfma_f32_16x16x32_bf16 v[126:129], v[168:171], v[196:199], v[126:129]
	v_mfma_f32_16x16x32_bf16 v[122:125], v[160:163], v[204:207], v[122:125]
	v_mfma_f32_16x16x32_bf16 v[118:121], v[168:171], v[204:207], v[118:121]
	v_mfma_f32_16x16x32_bf16 v[114:117], v[160:163], v[220:223], v[114:117]
	v_mfma_f32_16x16x32_bf16 v[110:113], v[168:171], v[220:223], v[110:113]
	v_mfma_f32_16x16x32_bf16 v[106:109], v[160:163], v[228:231], v[106:109]
	v_mfma_f32_16x16x32_bf16 v[100:103], v[168:171], v[228:231], v[100:103]
	v_mfma_f32_16x16x32_bf16 v[94:97], v[172:175], v[192:195], v[94:97]
	v_mfma_f32_16x16x32_bf16 v[90:93], v[184:187], v[192:195], v[90:93]
	v_mfma_f32_16x16x32_bf16 v[86:89], v[172:175], v[200:203], v[86:89]
	v_mfma_f32_16x16x32_bf16 v[82:85], v[184:187], v[200:203], v[82:85]
	v_mfma_f32_16x16x32_bf16 v[78:81], v[172:175], v[208:211], v[78:81]
	v_mfma_f32_16x16x32_bf16 v[74:77], v[184:187], v[208:211], v[74:77]
	v_mfma_f32_16x16x32_bf16 v[70:73], v[172:175], v[224:227], v[70:73]
	v_mfma_f32_16x16x32_bf16 v[66:69], v[184:187], v[224:227], v[66:69]
	v_mfma_f32_16x16x32_bf16 v[94:97], v[180:183], v[196:199], v[94:97]
	v_mfma_f32_16x16x32_bf16 v[90:93], v[188:191], v[196:199], v[90:93]
	v_mfma_f32_16x16x32_bf16 v[86:89], v[180:183], v[204:207], v[86:89]
	v_mfma_f32_16x16x32_bf16 v[82:85], v[188:191], v[204:207], v[82:85]
	v_mfma_f32_16x16x32_bf16 v[78:81], v[180:183], v[220:223], v[78:81]
	v_mfma_f32_16x16x32_bf16 v[74:77], v[188:191], v[220:223], v[74:77]
	v_mfma_f32_16x16x32_bf16 v[70:73], v[180:183], v[228:231], v[70:73]
	v_mfma_f32_16x16x32_bf16 v[66:69], v[188:191], v[228:231], v[66:69]
	s_setprio 0
	s_barrier
	s_add_i32 s50, s50, s28
	v_lshl_add_u64 v[176:177], s[20:21], 0, v[138:139]
	s_mov_b32 m0, s50
	ds_read_b128 v[192:195], v179 offset:16384
	ds_read_b128 v[196:199], v179 offset:17408
	ds_read_b128 v[200:203], v179 offset:18432
	ds_read_b128 v[204:207], v179 offset:19456
	ds_read_b128 v[208:211], v179 offset:20480
	ds_read_b128 v[220:223], v179 offset:21504
	ds_read_b128 v[224:227], v179 offset:22528
	ds_read_b128 v[228:231], v179 offset:23552
	global_load_lds_dwordx4 v[176:177], off
	s_add_i32 m0, s50, 0x2000
	s_add_u32 s56, s20, 0x20000
	v_lshl_add_u64 v[212:213], s[20:21], 0, v[134:135]
	s_addc_u32 s57, s21, 0
	s_add_i32 s50, s52, s28
	global_load_lds_dwordx4 v[212:213], off
	v_lshl_add_u64 v[104:105], s[56:57], 0, v[138:139]
	s_mov_b32 m0, s50
	v_lshl_add_u64 v[232:233], s[22:23], 0, v[140:141]
	global_load_lds_dwordx4 v[104:105], off
	v_lshl_add_u64 v[104:105], s[56:57], 0, v[134:135]
	s_add_i32 m0, s50, 0x2000
	v_lshl_add_u64 v[234:235], s[22:23], 0, v[136:137]
	global_load_lds_dwordx4 v[104:105], off
	s_mov_b32 m0, s29
	s_nop 0
	global_load_lds_dwordx4 v[232:233], off
	s_mov_b32 m0, s30
	s_nop 0
	global_load_lds_dwordx4 v[234:235], off
	s_waitcnt vmcnt(8)
	s_waitcnt lgkmcnt(0)
	s_barrier
; #define PG8_STAGE(bufoff, gbase, voff) do { _Pragma("unroll") for (int _i = 0; _i < 2; ++_i) \
;         __builtin_amdgcn_global_load_lds((const unsigned*)((const char*)(gbase) + (voff)[_i]), (LAS unsigned*)(lds + (bufoff) + ldsw + _i * 8192), 16, 0, 0); } while (0)
; #define PG8_LDA(dst, b, h) do { _Pragma("unroll") for (int m = 0; m < 4; ++m) _Pragma("unroll") for (int k = 0; k < 2; ++k) dst[m][k] = *(const LAS bf16x8*)(lds + PG8_SA(b, h) + aoff + m * 2048 + k * 1024); } while (0)
; #define PG8_LDB(dst, b, h) do { _Pragma("unroll") for (int n = 0; n < 2; ++n) _Pragma("unroll") for (int k = 0; k < 2; ++k) dst[n][k] = *(const LAS bf16x8*)(lds + PG8_SB(b, h) + boff + n * 2048 + k * 1024); } while (0)
; #define PG8_MMA(ai, bj, At, Bt) do { __builtin_amdgcn_s_setprio(1); _Pragma("unroll") for (int m = 0; m < 4; ++m) _Pragma("unroll") for (int n = 0; n < 2; ++n) _Pragma("unroll") for (int k = 0; k < 2; ++k) \
;         acc[ai][bj][m][n] = __builtin_amdgcn_mfma_f32_16x16x32_bf16(Bt[n][k], At[m][k], acc[ai][bj][m][n], 0, 0, 0); __builtin_amdgcn_s_setprio(0); } while (0)
; #define PG8_WAIT_V(n) asm volatile("s_waitcnt vmcnt(" #n ")" ::: "memory")
; #define PG8_WAIT_L(n) asm volatile("s_waitcnt lgkmcnt(" #n ")" ::: "memory")
; #define PG8_BAR __builtin_amdgcn_s_barrier()
; #define PG8_SCHED __builtin_amdgcn_sched_barrier(0)
; template <class Epi, class Sched>
; __device__ __forceinline__ void gemm_phase(LAS unsigned char* lds, const Gemm g, const Sched& S, const Epi& E) {
;     ...
;             PG8_WAIT_V(8); PG8_WAIT_L(0); PG8_BAR; PG8_MMA(1, 0, At, B0); PG8_MMA(1, 1, At, B1); PG8_BAR; PG8_SCHED;
;             PG8_LDB(B0, 1, 0); PG8_LDB(B1, 1, 1); PG8_SCHED; PG8_LDA(At, 1, 0); PG8_STAGE(PG8_SA(0, 1), a2 + hA, voffA);
;             PG8_WAIT_V(8); PG8_WAIT_L(0); PG8_BAR; PG8_MMA(0, 0, At, B0); PG8_MMA(0, 1, At, B1); PG8_BAR; PG8_SCHED;
;             PG8_LDA(At, 1, 1); PG8_STAGE(PG8_SB(1, 0), b3, voffB); PG8_STAGE(PG8_SB(1, 1), b3 + hB, voffB); PG8_STAGE(PG8_SA(1, 0), a3, voffA);
;             PG8_WAIT_V(8); PG8_WAIT_L(0); PG8_BAR; PG8_MMA(1, 0, At, B0); PG8_MMA(1, 1, At, B1); PG8_BAR; PG8_SCHED;
	s_setprio 1
	s_waitcnt lgkmcnt(0)
	v_mfma_f32_16x16x32_bf16 v[62:65], v[154:157], v[192:195], v[62:65]
	v_mfma_f32_16x16x32_bf16 v[58:61], v[164:167], v[192:195], v[58:61]
	v_mfma_f32_16x16x32_bf16 v[54:57], v[154:157], v[200:203], v[54:57]
	v_mfma_f32_16x16x32_bf16 v[50:53], v[164:167], v[200:203], v[50:53]
	v_mfma_f32_16x16x32_bf16 v[46:49], v[154:157], v[208:211], v[46:49]
	v_mfma_f32_16x16x32_bf16 v[42:45], v[164:167], v[208:211], v[42:45]
	v_mfma_f32_16x16x32_bf16 v[38:41], v[154:157], v[224:227], v[38:41]
	v_mfma_f32_16x16x32_bf16 v[34:37], v[164:167], v[224:227], v[34:37]
	v_mfma_f32_16x16x32_bf16 v[62:65], v[160:163], v[196:199], v[62:65]
	v_mfma_f32_16x16x32_bf16 v[58:61], v[168:171], v[196:199], v[58:61]
	v_mfma_f32_16x16x32_bf16 v[54:57], v[160:163], v[204:207], v[54:57]
	v_mfma_f32_16x16x32_bf16 v[50:53], v[168:171], v[204:207], v[50:53]
	v_mfma_f32_16x16x32_bf16 v[46:49], v[160:163], v[220:223], v[46:49]
	v_mfma_f32_16x16x32_bf16 v[42:45], v[168:171], v[220:223], v[42:45]
	v_mfma_f32_16x16x32_bf16 v[38:41], v[160:163], v[228:231], v[38:41]
	v_mfma_f32_16x16x32_bf16 v[34:37], v[168:171], v[228:231], v[34:37]
	v_mfma_f32_16x16x32_bf16 v[30:33], v[172:175], v[192:195], v[30:33]
	v_mfma_f32_16x16x32_bf16 v[26:29], v[184:187], v[192:195], v[26:29]
	v_mfma_f32_16x16x32_bf16 v[22:25], v[172:175], v[200:203], v[22:25]
	v_mfma_f32_16x16x32_bf16 v[18:21], v[184:187], v[200:203], v[18:21]
	v_mfma_f32_16x16x32_bf16 v[14:17], v[172:175], v[208:211], v[14:17]
	v_mfma_f32_16x16x32_bf16 v[10:13], v[184:187], v[208:211], v[10:13]
	v_mfma_f32_16x16x32_bf16 v[6:9], v[172:175], v[224:227], v[6:9]
	v_mfma_f32_16x16x32_bf16 v[2:5], v[184:187], v[224:227], v[2:5]
	v_mfma_f32_16x16x32_bf16 v[30:33], v[180:183], v[196:199], v[30:33]
	v_mfma_f32_16x16x32_bf16 v[26:29], v[188:191], v[196:199], v[26:29]
	v_mfma_f32_16x16x32_bf16 v[22:25], v[180:183], v[204:207], v[22:25]
	v_mfma_f32_16x16x32_bf16 v[18:21], v[188:191], v[204:207], v[18:21]
	v_mfma_f32_16x16x32_bf16 v[14:17], v[180:183], v[220:223], v[14:17]
	v_mfma_f32_16x16x32_bf16 v[10:13], v[188:191], v[220:223], v[10:13]
	v_mfma_f32_16x16x32_bf16 v[6:9], v[180:183], v[228:231], v[6:9]
	v_mfma_f32_16x16x32_bf16 v[2:5], v[188:191], v[228:231], v[2:5]
	s_setprio 0
	s_barrier
	s_add_i32 s50, 0, 0x18000
	v_add_u32_e32 v98, s50, v178
	s_add_i32 s52, 0, 0x1c000
	ds_read_b128 v[154:157], v98
	ds_read_b128 v[160:163], v98 offset:1024
	ds_read_b128 v[164:167], v98 offset:2048
	ds_read_b128 v[168:171], v98 offset:3072
	v_add_u32_e32 v98, s52, v178
	ds_read_b128 v[172:175], v98
	ds_read_b128 v[180:183], v98 offset:1024
	ds_read_b128 v[184:187], v98 offset:2048
	ds_read_b128 v[188:191], v98 offset:3072
	s_add_u32 s22, s22, 0x80000
	s_addc_u32 s23, s23, 0
	s_mov_b32 m0, s31
	v_lshl_add_u64 v[104:105], s[22:23], 0, v[140:141]
	ds_read_b128 v[192:195], v179 offset:32768
	ds_read_b128 v[196:199], v179 offset:33792
	ds_read_b128 v[200:203], v179 offset:34816
	ds_read_b128 v[204:207], v179 offset:35840
	ds_read_b128 v[208:211], v179 offset:36864
	ds_read_b128 v[220:223], v179 offset:37888
	ds_read_b128 v[224:227], v179 offset:38912
	ds_read_b128 v[228:231], v179 offset:39936
	global_load_lds_dwordx4 v[104:105], off
	v_lshl_add_u64 v[104:105], s[22:23], 0, v[136:137]
	s_mov_b32 m0, s34
	s_nop 0
	global_load_lds_dwordx4 v[104:105], off
	s_waitcnt vmcnt(8)
	s_waitcnt lgkmcnt(0)
	s_barrier
	s_setprio 1
	s_waitcnt lgkmcnt(0)
	v_mfma_f32_16x16x32_bf16 v[130:133], v[154:157], v[192:195], v[130:133]
	v_mfma_f32_16x16x32_bf16 v[126:129], v[164:167], v[192:195], v[126:129]
	v_mfma_f32_16x16x32_bf16 v[122:125], v[154:157], v[200:203], v[122:125]
	v_mfma_f32_16x16x32_bf16 v[118:121], v[164:167], v[200:203], v[118:121]
	v_mfma_f32_16x16x32_bf16 v[114:117], v[154:157], v[208:211], v[114:117]
	v_mfma_f32_16x16x32_bf16 v[110:113], v[164:167], v[208:211], v[110:113]
	v_mfma_f32_16x16x32_bf16 v[104:107], v[154:157], v[224:227], v[106:109]
	v_mfma_f32_16x16x32_bf16 v[100:103], v[164:167], v[224:227], v[100:103]
	v_mfma_f32_16x16x32_bf16 v[130:133], v[160:163], v[196:199], v[130:133]
	v_mfma_f32_16x16x32_bf16 v[126:129], v[168:171], v[196:199], v[126:129]
	v_mfma_f32_16x16x32_bf16 v[122:125], v[160:163], v[204:207], v[122:125]
	v_mfma_f32_16x16x32_bf16 v[118:121], v[168:171], v[204:207], v[118:121]
	v_mfma_f32_16x16x32_bf16 v[114:117], v[160:163], v[220:223], v[114:117]
	v_mfma_f32_16x16x32_bf16 v[110:113], v[168:171], v[220:223], v[110:113]
	v_mfma_f32_16x16x32_bf16 v[106:109], v[160:163], v[228:231], v[104:107]
	v_mfma_f32_16x16x32_bf16 v[102:105], v[168:171], v[228:231], v[100:103]
	v_mfma_f32_16x16x32_bf16 v[94:97], v[172:175], v[192:195], v[94:97]
	v_mfma_f32_16x16x32_bf16 v[90:93], v[184:187], v[192:195], v[90:93]
	v_mfma_f32_16x16x32_bf16 v[86:89], v[172:175], v[200:203], v[86:89]
	v_mfma_f32_16x16x32_bf16 v[82:85], v[184:187], v[200:203], v[82:85]
	v_mfma_f32_16x16x32_bf16 v[78:81], v[172:175], v[208:211], v[78:81]
	v_mfma_f32_16x16x32_bf16 v[74:77], v[184:187], v[208:211], v[74:77]
	v_mfma_f32_16x16x32_bf16 v[70:73], v[172:175], v[224:227], v[70:73]
	v_mfma_f32_16x16x32_bf16 v[66:69], v[184:187], v[224:227], v[66:69]
	v_mfma_f32_16x16x32_bf16 v[94:97], v[180:183], v[196:199], v[94:97]
	v_mfma_f32_16x16x32_bf16 v[90:93], v[188:191], v[196:199], v[90:93]
	v_mfma_f32_16x16x32_bf16 v[86:89], v[180:183], v[204:207], v[86:89]
	v_mfma_f32_16x16x32_bf16 v[82:85], v[188:191], v[204:207], v[82:85]
	v_mfma_f32_16x16x32_bf16 v[78:81], v[180:183], v[220:223], v[78:81]
	v_mfma_f32_16x16x32_bf16 v[74:77], v[188:191], v[220:223], v[74:77]
	v_mfma_f32_16x16x32_bf16 v[70:73], v[180:183], v[228:231], v[70:73]
	v_mfma_f32_16x16x32_bf16 v[66:69], v[188:191], v[228:231], v[66:69]
	s_setprio 0
	s_barrier
; #define PG8_STAGE(bufoff, gbase, voff) do { _Pragma("unroll") for (int _i = 0; _i < 2; ++_i) \
;         __builtin_amdgcn_global_load_lds((const unsigned*)((const char*)(gbase) + (voff)[_i]), (LAS unsigned*)(lds + (bufoff) + ldsw + _i * 8192), 16, 0, 0); } while (0)
; #define PG8_LDA(dst, b, h) do { _Pragma("unroll") for (int m = 0; m < 4; ++m) _Pragma("unroll") for (int k = 0; k < 2; ++k) dst[m][k] = *(const LAS bf16x8*)(lds + PG8_SA(b, h) + aoff + m * 2048 + k * 1024); } while (0)
; #define PG8_MMA(ai, bj, At, Bt) do { __builtin_amdgcn_s_setprio(1); _Pragma("unroll") for (int m = 0; m < 4; ++m) _Pragma("unroll") for (int n = 0; n < 2; ++n) _Pragma("unroll") for (int k = 0; k < 2; ++k) \
;         acc[ai][bj][m][n] = __builtin_amdgcn_mfma_f32_16x16x32_bf16(Bt[n][k], At[m][k], acc[ai][bj][m][n], 0, 0, 0); __builtin_amdgcn_s_setprio(0); } while (0)
; #define PG8_WAIT_V(n) asm volatile("s_waitcnt vmcnt(" #n ")" ::: "memory")
; #define PG8_WAIT_L(n) asm volatile("s_waitcnt lgkmcnt(" #n ")" ::: "memory")
; #define PG8_BAR __builtin_amdgcn_s_barrier()
; #define PG8_SCHED __builtin_amdgcn_sched_barrier(0)
; template <class Epi, class Sched>
; __device__ __forceinline__ void gemm_phase(LAS unsigned char* lds, const Gemm g, const Sched& S, const Epi& E) {
;     ...
;             PG8_LDA(At, 1, 1); PG8_STAGE(PG8_SB(1, 0), b3, voffB); PG8_STAGE(PG8_SB(1, 1), b3 + hB, voffB); PG8_STAGE(PG8_SA(1, 0), a3, voffA);
;             PG8_WAIT_V(8); PG8_WAIT_L(0); PG8_BAR; PG8_MMA(1, 0, At, B0); PG8_MMA(1, 1, At, B1); PG8_BAR; PG8_SCHED;
;         }
;         if (wr == 0) PG8_BAR;
	s_add_i32 s22, s50, s28
	v_lshl_add_u64 v[100:101], v[176:177], 0, s[76:77]
	s_mov_b32 m0, s22
	ds_read_b128 v[192:195], v179 offset:49152
	ds_read_b128 v[196:199], v179 offset:50176
	ds_read_b128 v[200:203], v179 offset:51200
	ds_read_b128 v[204:207], v179 offset:52224
	ds_read_b128 v[208:211], v179 offset:53248
	ds_read_b128 v[220:223], v179 offset:54272
	ds_read_b128 v[224:227], v179 offset:55296
	ds_read_b128 v[228:231], v179 offset:56320
	global_load_lds_dwordx4 v[100:101], off
	s_add_i32 m0, s22, 0x2000
	s_add_u32 s20, s20, 0x20080
	v_lshl_add_u64 v[100:101], v[212:213], 0, s[76:77]
	s_addc_u32 s21, s21, 0
	s_add_i32 s22, s52, s28
	global_load_lds_dwordx4 v[100:101], off
	v_lshl_add_u64 v[100:101], s[20:21], 0, v[138:139]
	s_mov_b32 m0, s22
	s_nop 0
	global_load_lds_dwordx4 v[100:101], off
	v_lshl_add_u64 v[100:101], s[20:21], 0, v[134:135]
	s_add_i32 m0, s22, 0x2000
	s_nop 0
	global_load_lds_dwordx4 v[100:101], off
	v_lshl_add_u64 v[100:101], v[232:233], 0, s[76:77]
	s_mov_b32 m0, s35
	s_nop 0
	global_load_lds_dwordx4 v[100:101], off
	v_lshl_add_u64 v[100:101], v[234:235], 0, s[76:77]
	s_mov_b32 m0, s36
	s_nop 0
	global_load_lds_dwordx4 v[100:101], off
	s_waitcnt vmcnt(8)
	s_waitcnt lgkmcnt(0)
	s_barrier
	s_setprio 1
	s_waitcnt lgkmcnt(0)
	v_mfma_f32_16x16x32_bf16 v[62:65], v[154:157], v[192:195], v[62:65]
	v_mfma_f32_16x16x32_bf16 v[58:61], v[164:167], v[192:195], v[58:61]
	v_mfma_f32_16x16x32_bf16 v[54:57], v[154:157], v[200:203], v[54:57]
	v_mfma_f32_16x16x32_bf16 v[50:53], v[164:167], v[200:203], v[50:53]
	v_mfma_f32_16x16x32_bf16 v[46:49], v[154:157], v[208:211], v[46:49]
	v_mfma_f32_16x16x32_bf16 v[42:45], v[164:167], v[208:211], v[42:45]
	v_mfma_f32_16x16x32_bf16 v[38:41], v[154:157], v[224:227], v[38:41]
	v_mfma_f32_16x16x32_bf16 v[34:37], v[164:167], v[224:227], v[34:37]
	v_mfma_f32_16x16x32_bf16 v[62:65], v[160:163], v[196:199], v[62:65]
	v_mfma_f32_16x16x32_bf16 v[58:61], v[168:171], v[196:199], v[58:61]
	v_mfma_f32_16x16x32_bf16 v[54:57], v[160:163], v[204:207], v[54:57]
	v_mfma_f32_16x16x32_bf16 v[50:53], v[168:171], v[204:207], v[50:53]
	v_mfma_f32_16x16x32_bf16 v[46:49], v[160:163], v[220:223], v[46:49]
	v_mfma_f32_16x16x32_bf16 v[42:45], v[168:171], v[220:223], v[42:45]
	v_mfma_f32_16x16x32_bf16 v[38:41], v[160:163], v[228:231], v[38:41]
	v_mfma_f32_16x16x32_bf16 v[34:37], v[168:171], v[228:231], v[34:37]
	v_mfma_f32_16x16x32_bf16 v[30:33], v[172:175], v[192:195], v[30:33]
	v_mfma_f32_16x16x32_bf16 v[26:29], v[184:187], v[192:195], v[26:29]
	v_mfma_f32_16x16x32_bf16 v[22:25], v[172:175], v[200:203], v[22:25]
	v_mfma_f32_16x16x32_bf16 v[18:21], v[184:187], v[200:203], v[18:21]
	v_mfma_f32_16x16x32_bf16 v[14:17], v[172:175], v[208:211], v[14:17]
	v_mfma_f32_16x16x32_bf16 v[10:13], v[184:187], v[208:211], v[10:13]
	v_mfma_f32_16x16x32_bf16 v[6:9], v[172:175], v[224:227], v[6:9]
	v_mfma_f32_16x16x32_bf16 v[2:5], v[184:187], v[224:227], v[2:5]
	v_mfma_f32_16x16x32_bf16 v[30:33], v[180:183], v[196:199], v[30:33]
	v_mfma_f32_16x16x32_bf16 v[26:29], v[188:191], v[196:199], v[26:29]
	v_mfma_f32_16x16x32_bf16 v[22:25], v[180:183], v[204:207], v[22:25]
	v_mfma_f32_16x16x32_bf16 v[18:21], v[188:191], v[204:207], v[18:21]
	v_mfma_f32_16x16x32_bf16 v[14:17], v[180:183], v[220:223], v[14:17]
	v_mfma_f32_16x16x32_bf16 v[10:13], v[188:191], v[220:223], v[10:13]
	v_mfma_f32_16x16x32_bf16 v[6:9], v[180:183], v[228:231], v[6:9]
	v_mfma_f32_16x16x32_bf16 v[2:5], v[188:191], v[228:231], v[2:5]
	s_setprio 0
	s_barrier
	s_add_u32 s2, s2, 0x100
	s_addc_u32 s3, s3, 0
	s_add_u32 s46, s46, 0x100
	s_addc_u32 s47, s47, 0
	s_cmp_ge_i32 s48, s24
	s_mov_b32 s20, s48
	s_cbranch_scc0 .LBB0_708
	s_and_b64 vcc, exec, s[6:7]
	s_cbranch_vccz .LBB0_711
	s_barrier

; #define PG8_STAGE(bufoff, gbase, voff) do { _Pragma("unroll") for (int _i = 0; _i < 2; ++_i) \
;         __builtin_amdgcn_global_load_lds((const unsigned*)((const char*)(gbase) + (voff)[_i]), (LAS unsigned*)(lds + (bufoff) + ldsw + _i * 8192), 16, 0, 0); } while (0)
; #define PG8_LDA(dst, b, h) do { _Pragma("unroll") for (int m = 0; m < 4; ++m) _Pragma("unroll") for (int k = 0; k < 2; ++k) dst[m][k] = *(const LAS bf16x8*)(lds + PG8_SA(b, h) + aoff + m * 2048 + k * 1024); } while (0)
; #define PG8_LDB(dst, b, h) do { _Pragma("unroll") for (int n = 0; n < 2; ++n) _Pragma("unroll") for (int k = 0; k < 2; ++k) dst[n][k] = *(const LAS bf16x8*)(lds + PG8_SB(b, h) + boff + n * 2048 + k * 1024); } while (0)
; #define PG8_MMA(ai, bj, At, Bt) do { __builtin_amdgcn_s_setprio(1); _Pragma("unroll") for (int m = 0; m < 4; ++m) _Pragma("unroll") for (int n = 0; n < 2; ++n) _Pragma("unroll") for (int k = 0; k < 2; ++k) \
;         acc[ai][bj][m][n] = __builtin_amdgcn_mfma_f32_16x16x32_bf16(Bt[n][k], At[m][k], acc[ai][bj][m][n], 0, 0, 0); __builtin_amdgcn_s_setprio(0); } while (0)
; #define PG8_WAIT_V(n) asm volatile("s_waitcnt vmcnt(" #n ")" ::: "memory")
; #define PG8_WAIT_L(n) asm volatile("s_waitcnt lgkmcnt(" #n ")" ::: "memory")
; #define PG8_BAR __builtin_amdgcn_s_barrier()
; #define PG8_SCHED __builtin_amdgcn_sched_barrier(0)
; template <class Epi, class Sched>
; __device__ __forceinline__ void gemm_phase(LAS unsigned char* lds, const Gemm g, const Sched& S, const Epi& E) {
;     ...
;         for (int t = 0; t < nt; t += 2) {
;             const bool last = (t == nt - 2);
;             const char* a1 = cA + (size_t)(t + 1) * kstepA;
;             const char* a2 = last ? nA : cA + (size_t)(t + 2) * kstepA; const char* b2 = last ? nB : cB + (size_t)(t + 2) * kstep;
;             const char* a3 = a2 + kstepA; const char* b3 = b2 + kstep;
;             PG8_LDB(B0, 0, 0); PG8_LDB(B1, 0, 1); PG8_SCHED; PG8_LDA(At, 0, 0); PG8_STAGE(PG8_SA(1, 1), a1 + hA, voffA);
;             PG8_WAIT_V(8); PG8_WAIT_L(0); PG8_BAR; PG8_MMA(0, 0, At, B0); PG8_MMA(0, 1, At, B1); PG8_BAR; PG8_SCHED;
;             PG8_LDA(At, 0, 1); PG8_STAGE(PG8_SB(0, 0), b2, voffB); PG8_STAGE(PG8_SB(0, 1), b2 + hB, voffB); PG8_STAGE(PG8_SA(0, 0), a2, voffA);
;             PG8_WAIT_V(8); PG8_WAIT_L(0); PG8_BAR; PG8_MMA(1, 0, At, B0); PG8_MMA(1, 1, At, B1); PG8_BAR; PG8_SCHED;
.LBB0_842:
	s_add_u32 s2, s24, 0x200
	s_addc_u32 s3, s25, 0
	s_add_i32 s55, 0, 0x10000
	s_cmp_eq_u32 s52, 28
	s_cselect_b32 s29, s19, s3
	s_cselect_b32 s28, s46, s2
	v_add_u32_e32 v98, s55, v212
	s_cselect_b32 s27, s17, s50
	s_cselect_b32 s26, s47, s48
	s_add_i32 s56, 0, 0x14000
	ds_read_b128 v[132:135], v98
	ds_read_b128 v[136:139], v98 offset:1024
	ds_read_b128 v[154:157], v98 offset:2048
	ds_read_b128 v[164:167], v98 offset:3072
	v_add_u32_e32 v98, s56, v212
	ds_read_b128 v[168:171], v98
	ds_read_b128 v[172:175], v98 offset:1024
	ds_read_b128 v[176:179], v98 offset:2048
	ds_read_b128 v[180:183], v98 offset:3072
	v_lshl_add_u64 v[226:227], s[24:25], 0, v[160:161]
	s_add_i32 m0, s35, 0xc000
	ds_read_b128 v[184:187], v221
	ds_read_b128 v[188:191], v221 offset:1024
	ds_read_b128 v[192:195], v221 offset:2048
	ds_read_b128 v[196:199], v221 offset:3072
	ds_read_b128 v[200:203], v221 offset:4096
	ds_read_b128 v[204:207], v221 offset:5120
	ds_read_b128 v[208:211], v221 offset:6144
	ds_read_b128 v[222:225], v221 offset:7168
	global_load_lds_dwordx4 v[226:227], off
	v_lshl_add_u64 v[226:227], s[24:25], 0, v[162:163]
	s_add_i32 m0, s35, 0xe000
	s_nop 0
	global_load_lds_dwordx4 v[226:227], off
	s_waitcnt vmcnt(8)
	s_waitcnt lgkmcnt(0)
	s_barrier
	s_setprio 1
	s_waitcnt lgkmcnt(0)
	v_mfma_f32_16x16x32_bf16 v[128:131], v[132:135], v[184:187], v[128:131]
	v_mfma_f32_16x16x32_bf16 v[124:127], v[154:157], v[184:187], v[124:127]
	v_mfma_f32_16x16x32_bf16 v[112:115], v[132:135], v[192:195], v[112:115]
	v_mfma_f32_16x16x32_bf16 v[108:111], v[154:157], v[192:195], v[108:111]
	v_mfma_f32_16x16x32_bf16 v[94:97], v[132:135], v[200:203], v[94:97]
	v_mfma_f32_16x16x32_bf16 v[90:93], v[154:157], v[200:203], v[90:93]
	v_mfma_f32_16x16x32_bf16 v[78:81], v[132:135], v[208:211], v[78:81]
	v_mfma_f32_16x16x32_bf16 v[74:77], v[154:157], v[208:211], v[74:77]
	v_mfma_f32_16x16x32_bf16 v[128:131], v[136:139], v[188:191], v[128:131]
	v_mfma_f32_16x16x32_bf16 v[124:127], v[164:167], v[188:191], v[124:127]
	v_mfma_f32_16x16x32_bf16 v[112:115], v[136:139], v[196:199], v[112:115]
	v_mfma_f32_16x16x32_bf16 v[108:111], v[164:167], v[196:199], v[108:111]
	v_mfma_f32_16x16x32_bf16 v[94:97], v[136:139], v[204:207], v[94:97]
	v_mfma_f32_16x16x32_bf16 v[90:93], v[164:167], v[204:207], v[90:93]
	v_mfma_f32_16x16x32_bf16 v[78:81], v[136:139], v[222:225], v[78:81]
	v_mfma_f32_16x16x32_bf16 v[74:77], v[164:167], v[222:225], v[74:77]
	v_mfma_f32_16x16x32_bf16 v[120:123], v[168:171], v[184:187], v[120:123]
	v_mfma_f32_16x16x32_bf16 v[116:119], v[176:179], v[184:187], v[116:119]
	v_mfma_f32_16x16x32_bf16 v[104:107], v[168:171], v[192:195], v[104:107]
	v_mfma_f32_16x16x32_bf16 v[100:103], v[176:179], v[192:195], v[100:103]
	v_mfma_f32_16x16x32_bf16 v[86:89], v[168:171], v[200:203], v[86:89]
	v_mfma_f32_16x16x32_bf16 v[82:85], v[176:179], v[200:203], v[82:85]
	v_mfma_f32_16x16x32_bf16 v[70:73], v[168:171], v[208:211], v[70:73]
	v_mfma_f32_16x16x32_bf16 v[66:69], v[176:179], v[208:211], v[66:69]
	v_mfma_f32_16x16x32_bf16 v[120:123], v[172:175], v[188:191], v[120:123]
	v_mfma_f32_16x16x32_bf16 v[116:119], v[180:183], v[188:191], v[116:119]
	v_mfma_f32_16x16x32_bf16 v[104:107], v[172:175], v[196:199], v[104:107]
	v_mfma_f32_16x16x32_bf16 v[100:103], v[180:183], v[196:199], v[100:103]
	v_mfma_f32_16x16x32_bf16 v[86:89], v[172:175], v[204:207], v[86:89]
	v_mfma_f32_16x16x32_bf16 v[82:85], v[180:183], v[204:207], v[82:85]
	v_mfma_f32_16x16x32_bf16 v[70:73], v[172:175], v[222:225], v[70:73]
	v_mfma_f32_16x16x32_bf16 v[66:69], v[180:183], v[222:225], v[66:69]
	s_setprio 0
	s_barrier
	s_add_i32 s24, s55, s34
	v_lshl_add_u64 v[226:227], s[26:27], 0, v[144:145]
	s_mov_b32 m0, s24
	ds_read_b128 v[184:187], v221 offset:16384
	ds_read_b128 v[188:191], v221 offset:17408
	ds_read_b128 v[192:195], v221 offset:18432
	ds_read_b128 v[196:199], v221 offset:19456
	ds_read_b128 v[200:203], v221 offset:20480
	ds_read_b128 v[204:207], v221 offset:21504
	ds_read_b128 v[208:211], v221 offset:22528
	ds_read_b128 v[222:225], v221 offset:23552
	global_load_lds_dwordx4 v[226:227], off
	s_add_i32 m0, s24, 0x2000
	s_add_u32 s24, s26, 0x20000
	v_lshl_add_u64 v[228:229], s[26:27], 0, v[140:141]
	s_addc_u32 s25, s27, 0
	s_add_i32 s55, s56, s34
	global_load_lds_dwordx4 v[228:229], off
	v_lshl_add_u64 v[230:231], s[24:25], 0, v[144:145]
	s_mov_b32 m0, s55
	v_lshl_add_u64 v[232:233], s[28:29], 0, v[142:143]
	global_load_lds_dwordx4 v[230:231], off
	v_lshl_add_u64 v[230:231], s[24:25], 0, v[140:141]
	s_add_i32 m0, s55, 0x2000
	s_nop 0
	global_load_lds_dwordx4 v[230:231], off
	v_lshl_add_u64 v[230:231], s[28:29], 0, v[146:147]
	s_mov_b32 m0, s35
	s_nop 0
	global_load_lds_dwordx4 v[230:231], off
	s_mov_b32 m0, s36
	s_nop 0
	global_load_lds_dwordx4 v[232:233], off
	s_waitcnt vmcnt(8)
	s_waitcnt lgkmcnt(0)
	s_barrier
; #define PG8_STAGE(bufoff, gbase, voff) do { _Pragma("unroll") for (int _i = 0; _i < 2; ++_i) \
;         __builtin_amdgcn_global_load_lds((const unsigned*)((const char*)(gbase) + (voff)[_i]), (LAS unsigned*)(lds + (bufoff) + ldsw + _i * 8192), 16, 0, 0); } while (0)
; #define PG8_LDA(dst, b, h) do { _Pragma("unroll") for (int m = 0; m < 4; ++m) _Pragma("unroll") for (int k = 0; k < 2; ++k) dst[m][k] = *(const LAS bf16x8*)(lds + PG8_SA(b, h) + aoff + m * 2048 + k * 1024); } while (0)
; #define PG8_LDB(dst, b, h) do { _Pragma("unroll") for (int n = 0; n < 2; ++n) _Pragma("unroll") for (int k = 0; k < 2; ++k) dst[n][k] = *(const LAS bf16x8*)(lds + PG8_SB(b, h) + boff + n * 2048 + k * 1024); } while (0)
; #define PG8_MMA(ai, bj, At, Bt) do { __builtin_amdgcn_s_setprio(1); _Pragma("unroll") for (int m = 0; m < 4; ++m) _Pragma("unroll") for (int n = 0; n < 2; ++n) _Pragma("unroll") for (int k = 0; k < 2; ++k) \
;         acc[ai][bj][m][n] = __builtin_amdgcn_mfma_f32_16x16x32_bf16(Bt[n][k], At[m][k], acc[ai][bj][m][n], 0, 0, 0); __builtin_amdgcn_s_setprio(0); } while (0)
; #define PG8_WAIT_V(n) asm volatile("s_waitcnt vmcnt(" #n ")" ::: "memory")
; #define PG8_WAIT_L(n) asm volatile("s_waitcnt lgkmcnt(" #n ")" ::: "memory")
; #define PG8_BAR __builtin_amdgcn_s_barrier()
; #define PG8_SCHED __builtin_amdgcn_sched_barrier(0)
; template <class Epi, class Sched>
; __device__ __forceinline__ void gemm_phase(LAS unsigned char* lds, const Gemm g, const Sched& S, const Epi& E) {
;     ...
;             PG8_WAIT_V(8); PG8_WAIT_L(0); PG8_BAR; PG8_MMA(1, 0, At, B0); PG8_MMA(1, 1, At, B1); PG8_BAR; PG8_SCHED;
;             PG8_LDB(B0, 1, 0); PG8_LDB(B1, 1, 1); PG8_SCHED; PG8_LDA(At, 1, 0); PG8_STAGE(PG8_SA(0, 1), a2 + hA, voffA);
;             PG8_WAIT_V(8); PG8_WAIT_L(0); PG8_BAR; PG8_MMA(0, 0, At, B0); PG8_MMA(0, 1, At, B1); PG8_BAR; PG8_SCHED;
;             PG8_LDA(At, 1, 1); PG8_STAGE(PG8_SB(1, 0), b3, voffB); PG8_STAGE(PG8_SB(1, 1), b3 + hB, voffB); PG8_STAGE(PG8_SA(1, 0), a3, voffA);
;             PG8_WAIT_V(8); PG8_WAIT_L(0); PG8_BAR; PG8_MMA(1, 0, At, B0); PG8_MMA(1, 1, At, B1); PG8_BAR; PG8_SCHED;
	s_setprio 1
	s_waitcnt lgkmcnt(0)
	v_mfma_f32_16x16x32_bf16 v[62:65], v[132:135], v[184:187], v[62:65]
	v_mfma_f32_16x16x32_bf16 v[58:61], v[154:157], v[184:187], v[58:61]
	v_mfma_f32_16x16x32_bf16 v[46:49], v[132:135], v[192:195], v[46:49]
	v_mfma_f32_16x16x32_bf16 v[42:45], v[154:157], v[192:195], v[42:45]
	v_mfma_f32_16x16x32_bf16 v[30:33], v[132:135], v[200:203], v[30:33]
	v_mfma_f32_16x16x32_bf16 v[26:29], v[154:157], v[200:203], v[26:29]
	v_mfma_f32_16x16x32_bf16 v[14:17], v[132:135], v[208:211], v[14:17]
	v_mfma_f32_16x16x32_bf16 v[10:13], v[154:157], v[208:211], v[10:13]
	v_mfma_f32_16x16x32_bf16 v[62:65], v[136:139], v[188:191], v[62:65]
	v_mfma_f32_16x16x32_bf16 v[58:61], v[164:167], v[188:191], v[58:61]
	v_mfma_f32_16x16x32_bf16 v[46:49], v[136:139], v[196:199], v[46:49]
	v_mfma_f32_16x16x32_bf16 v[42:45], v[164:167], v[196:199], v[42:45]
	v_mfma_f32_16x16x32_bf16 v[30:33], v[136:139], v[204:207], v[30:33]
	v_mfma_f32_16x16x32_bf16 v[26:29], v[164:167], v[204:207], v[26:29]
	v_mfma_f32_16x16x32_bf16 v[14:17], v[136:139], v[222:225], v[14:17]
	v_mfma_f32_16x16x32_bf16 v[10:13], v[164:167], v[222:225], v[10:13]
	v_mfma_f32_16x16x32_bf16 v[54:57], v[168:171], v[184:187], v[54:57]
	v_mfma_f32_16x16x32_bf16 v[50:53], v[176:179], v[184:187], v[50:53]
	v_mfma_f32_16x16x32_bf16 v[38:41], v[168:171], v[192:195], v[38:41]
	v_mfma_f32_16x16x32_bf16 v[34:37], v[176:179], v[192:195], v[34:37]
	v_mfma_f32_16x16x32_bf16 v[22:25], v[168:171], v[200:203], v[22:25]
	v_mfma_f32_16x16x32_bf16 v[18:21], v[176:179], v[200:203], v[18:21]
	v_mfma_f32_16x16x32_bf16 v[6:9], v[168:171], v[208:211], v[6:9]
	v_mfma_f32_16x16x32_bf16 v[2:5], v[176:179], v[208:211], v[2:5]
	v_mfma_f32_16x16x32_bf16 v[54:57], v[172:175], v[188:191], v[54:57]
	v_mfma_f32_16x16x32_bf16 v[50:53], v[180:183], v[188:191], v[50:53]
	v_mfma_f32_16x16x32_bf16 v[38:41], v[172:175], v[196:199], v[38:41]
	v_mfma_f32_16x16x32_bf16 v[34:37], v[180:183], v[196:199], v[34:37]
	v_mfma_f32_16x16x32_bf16 v[22:25], v[172:175], v[204:207], v[22:25]
	v_mfma_f32_16x16x32_bf16 v[18:21], v[180:183], v[204:207], v[18:21]
	v_mfma_f32_16x16x32_bf16 v[6:9], v[172:175], v[222:225], v[6:9]
	v_mfma_f32_16x16x32_bf16 v[2:5], v[180:183], v[222:225], v[2:5]
	s_setprio 0
	s_barrier
	s_add_i32 s55, 0, 0x18000
	v_add_u32_e32 v98, s55, v212
	s_add_i32 s56, 0, 0x1c000
	ds_read_b128 v[132:135], v98
	ds_read_b128 v[136:139], v98 offset:1024
	ds_read_b128 v[154:157], v98 offset:2048
	ds_read_b128 v[164:167], v98 offset:3072
	v_add_u32_e32 v98, s56, v212
	ds_read_b128 v[168:171], v98
	ds_read_b128 v[172:175], v98 offset:1024
	ds_read_b128 v[176:179], v98 offset:2048
	ds_read_b128 v[180:183], v98 offset:3072
	s_add_u32 s24, s28, 0x80000
	s_addc_u32 s25, s29, 0
	s_mov_b32 m0, s37
	v_lshl_add_u64 v[234:235], s[24:25], 0, v[146:147]
	ds_read_b128 v[184:187], v221 offset:32768
	ds_read_b128 v[188:191], v221 offset:33792
	ds_read_b128 v[192:195], v221 offset:34816
	ds_read_b128 v[196:199], v221 offset:35840
	ds_read_b128 v[200:203], v221 offset:36864
	ds_read_b128 v[204:207], v221 offset:37888
	ds_read_b128 v[208:211], v221 offset:38912
	ds_read_b128 v[222:225], v221 offset:39936
	global_load_lds_dwordx4 v[234:235], off
	v_lshl_add_u64 v[234:235], s[24:25], 0, v[142:143]
	s_mov_b32 m0, s38
	s_nop 0
	global_load_lds_dwordx4 v[234:235], off
	s_waitcnt vmcnt(8)
	s_waitcnt lgkmcnt(0)
	s_barrier
	s_setprio 1
	s_waitcnt lgkmcnt(0)
	v_mfma_f32_16x16x32_bf16 v[128:131], v[132:135], v[184:187], v[128:131]
	v_mfma_f32_16x16x32_bf16 v[124:127], v[154:157], v[184:187], v[124:127]
	v_mfma_f32_16x16x32_bf16 v[112:115], v[132:135], v[192:195], v[112:115]
	v_mfma_f32_16x16x32_bf16 v[108:111], v[154:157], v[192:195], v[108:111]
	v_mfma_f32_16x16x32_bf16 v[94:97], v[132:135], v[200:203], v[94:97]
	v_mfma_f32_16x16x32_bf16 v[90:93], v[154:157], v[200:203], v[90:93]
	v_mfma_f32_16x16x32_bf16 v[78:81], v[132:135], v[208:211], v[78:81]
	v_mfma_f32_16x16x32_bf16 v[74:77], v[154:157], v[208:211], v[74:77]
	v_mfma_f32_16x16x32_bf16 v[128:131], v[136:139], v[188:191], v[128:131]
	v_mfma_f32_16x16x32_bf16 v[124:127], v[164:167], v[188:191], v[124:127]
	v_mfma_f32_16x16x32_bf16 v[112:115], v[136:139], v[196:199], v[112:115]
	v_mfma_f32_16x16x32_bf16 v[108:111], v[164:167], v[196:199], v[108:111]
	v_mfma_f32_16x16x32_bf16 v[94:97], v[136:139], v[204:207], v[94:97]
	v_mfma_f32_16x16x32_bf16 v[90:93], v[164:167], v[204:207], v[90:93]
	v_mfma_f32_16x16x32_bf16 v[78:81], v[136:139], v[222:225], v[78:81]
	v_mfma_f32_16x16x32_bf16 v[74:77], v[164:167], v[222:225], v[74:77]
	v_mfma_f32_16x16x32_bf16 v[120:123], v[168:171], v[184:187], v[120:123]
	v_mfma_f32_16x16x32_bf16 v[116:119], v[176:179], v[184:187], v[116:119]
	v_mfma_f32_16x16x32_bf16 v[104:107], v[168:171], v[192:195], v[104:107]
	v_mfma_f32_16x16x32_bf16 v[100:103], v[176:179], v[192:195], v[100:103]
	v_mfma_f32_16x16x32_bf16 v[86:89], v[168:171], v[200:203], v[86:89]
	v_mfma_f32_16x16x32_bf16 v[82:85], v[176:179], v[200:203], v[82:85]
	v_mfma_f32_16x16x32_bf16 v[70:73], v[168:171], v[208:211], v[70:73]
	v_mfma_f32_16x16x32_bf16 v[66:69], v[176:179], v[208:211], v[66:69]
	v_mfma_f32_16x16x32_bf16 v[120:123], v[172:175], v[188:191], v[120:123]
	v_mfma_f32_16x16x32_bf16 v[116:119], v[180:183], v[188:191], v[116:119]
	v_mfma_f32_16x16x32_bf16 v[104:107], v[172:175], v[196:199], v[104:107]
	v_mfma_f32_16x16x32_bf16 v[100:103], v[180:183], v[196:199], v[100:103]
	v_mfma_f32_16x16x32_bf16 v[86:89], v[172:175], v[204:207], v[86:89]
	v_mfma_f32_16x16x32_bf16 v[82:85], v[180:183], v[204:207], v[82:85]
	v_mfma_f32_16x16x32_bf16 v[70:73], v[172:175], v[222:225], v[70:73]
	v_mfma_f32_16x16x32_bf16 v[66:69], v[180:183], v[222:225], v[66:69]
	s_setprio 0
	s_barrier
; #define PG8_STAGE(bufoff, gbase, voff) do { _Pragma("unroll") for (int _i = 0; _i < 2; ++_i) \
;         __builtin_amdgcn_global_load_lds((const unsigned*)((const char*)(gbase) + (voff)[_i]), (LAS unsigned*)(lds + (bufoff) + ldsw + _i * 8192), 16, 0, 0); } while (0)
; #define PG8_LDA(dst, b, h) do { _Pragma("unroll") for (int m = 0; m < 4; ++m) _Pragma("unroll") for (int k = 0; k < 2; ++k) dst[m][k] = *(const LAS bf16x8*)(lds + PG8_SA(b, h) + aoff + m * 2048 + k * 1024); } while (0)
; #define PG8_MMA(ai, bj, At, Bt) do { __builtin_amdgcn_s_setprio(1); _Pragma("unroll") for (int m = 0; m < 4; ++m) _Pragma("unroll") for (int n = 0; n < 2; ++n) _Pragma("unroll") for (int k = 0; k < 2; ++k) \
;         acc[ai][bj][m][n] = __builtin_amdgcn_mfma_f32_16x16x32_bf16(Bt[n][k], At[m][k], acc[ai][bj][m][n], 0, 0, 0); __builtin_amdgcn_s_setprio(0); } while (0)
; #define PG8_WAIT_V(n) asm volatile("s_waitcnt vmcnt(" #n ")" ::: "memory")
; #define PG8_WAIT_L(n) asm volatile("s_waitcnt lgkmcnt(" #n ")" ::: "memory")
; #define PG8_BAR __builtin_amdgcn_s_barrier()
; #define PG8_SCHED __builtin_amdgcn_sched_barrier(0)
; template <class Epi, class Sched>
; __device__ __forceinline__ void gemm_phase(LAS unsigned char* lds, const Gemm g, const Sched& S, const Epi& E) {
;     ...
;             PG8_LDA(At, 1, 1); PG8_STAGE(PG8_SB(1, 0), b3, voffB); PG8_STAGE(PG8_SB(1, 1), b3 + hB, voffB); PG8_STAGE(PG8_SA(1, 0), a3, voffA);
;             PG8_WAIT_V(8); PG8_WAIT_L(0); PG8_BAR; PG8_MMA(1, 0, At, B0); PG8_MMA(1, 1, At, B1); PG8_BAR; PG8_SCHED;
;         }
;         if (wr == 0) PG8_BAR;
	s_add_i32 s24, s55, s34
	v_lshl_add_u64 v[226:227], v[226:227], 0, s[76:77]
	s_mov_b32 m0, s24
	ds_read_b128 v[184:187], v221 offset:49152
	ds_read_b128 v[188:191], v221 offset:50176
	ds_read_b128 v[192:195], v221 offset:51200
	ds_read_b128 v[196:199], v221 offset:52224
	ds_read_b128 v[200:203], v221 offset:53248
	ds_read_b128 v[204:207], v221 offset:54272
	ds_read_b128 v[208:211], v221 offset:55296
	ds_read_b128 v[222:225], v221 offset:56320
	global_load_lds_dwordx4 v[226:227], off
	s_add_i32 m0, s24, 0x2000
	s_add_u32 s24, s26, 0x20080
	v_lshl_add_u64 v[226:227], v[228:229], 0, s[76:77]
	s_addc_u32 s25, s27, 0
	s_add_i32 s26, s56, s34
	global_load_lds_dwordx4 v[226:227], off
	v_lshl_add_u64 v[226:227], s[24:25], 0, v[144:145]
	s_mov_b32 m0, s26
	s_nop 0
	global_load_lds_dwordx4 v[226:227], off
	v_lshl_add_u64 v[226:227], s[24:25], 0, v[140:141]
	s_add_i32 m0, s26, 0x2000
	s_nop 0
	global_load_lds_dwordx4 v[226:227], off
	v_lshl_add_u64 v[226:227], v[230:231], 0, s[96:97]
	s_mov_b32 m0, s41
	s_nop 0
	global_load_lds_dwordx4 v[226:227], off
	v_lshl_add_u64 v[226:227], v[232:233], 0, s[96:97]
	s_mov_b32 m0, s42
	s_nop 0
	global_load_lds_dwordx4 v[226:227], off
	s_waitcnt vmcnt(8)
	s_waitcnt lgkmcnt(0)
	s_barrier
	s_setprio 1
	s_waitcnt lgkmcnt(0)
	v_mfma_f32_16x16x32_bf16 v[62:65], v[132:135], v[184:187], v[62:65]
	v_mfma_f32_16x16x32_bf16 v[58:61], v[154:157], v[184:187], v[58:61]
	v_mfma_f32_16x16x32_bf16 v[46:49], v[132:135], v[192:195], v[46:49]
	v_mfma_f32_16x16x32_bf16 v[42:45], v[154:157], v[192:195], v[42:45]
	v_mfma_f32_16x16x32_bf16 v[30:33], v[132:135], v[200:203], v[30:33]
	v_mfma_f32_16x16x32_bf16 v[26:29], v[154:157], v[200:203], v[26:29]
	v_mfma_f32_16x16x32_bf16 v[14:17], v[132:135], v[208:211], v[14:17]
	v_mfma_f32_16x16x32_bf16 v[10:13], v[154:157], v[208:211], v[10:13]
	v_mfma_f32_16x16x32_bf16 v[62:65], v[136:139], v[188:191], v[62:65]
	v_mfma_f32_16x16x32_bf16 v[58:61], v[164:167], v[188:191], v[58:61]
	v_mfma_f32_16x16x32_bf16 v[46:49], v[136:139], v[196:199], v[46:49]
	v_mfma_f32_16x16x32_bf16 v[42:45], v[164:167], v[196:199], v[42:45]
	v_mfma_f32_16x16x32_bf16 v[30:33], v[136:139], v[204:207], v[30:33]
	v_mfma_f32_16x16x32_bf16 v[26:29], v[164:167], v[204:207], v[26:29]
	v_mfma_f32_16x16x32_bf16 v[14:17], v[136:139], v[222:225], v[14:17]
	v_mfma_f32_16x16x32_bf16 v[10:13], v[164:167], v[222:225], v[10:13]
	v_mfma_f32_16x16x32_bf16 v[54:57], v[168:171], v[184:187], v[54:57]
	v_mfma_f32_16x16x32_bf16 v[50:53], v[176:179], v[184:187], v[50:53]
	v_mfma_f32_16x16x32_bf16 v[38:41], v[168:171], v[192:195], v[38:41]
	v_mfma_f32_16x16x32_bf16 v[34:37], v[176:179], v[192:195], v[34:37]
	v_mfma_f32_16x16x32_bf16 v[22:25], v[168:171], v[200:203], v[22:25]
	v_mfma_f32_16x16x32_bf16 v[18:21], v[176:179], v[200:203], v[18:21]
	v_mfma_f32_16x16x32_bf16 v[6:9], v[168:171], v[208:211], v[6:9]
	v_mfma_f32_16x16x32_bf16 v[2:5], v[176:179], v[208:211], v[2:5]
	v_mfma_f32_16x16x32_bf16 v[54:57], v[172:175], v[188:191], v[54:57]
	v_mfma_f32_16x16x32_bf16 v[50:53], v[180:183], v[188:191], v[50:53]
	v_mfma_f32_16x16x32_bf16 v[38:41], v[172:175], v[196:199], v[38:41]
	v_mfma_f32_16x16x32_bf16 v[34:37], v[180:183], v[196:199], v[34:37]
	v_mfma_f32_16x16x32_bf16 v[22:25], v[172:175], v[204:207], v[22:25]
	v_mfma_f32_16x16x32_bf16 v[18:21], v[180:183], v[204:207], v[18:21]
	v_mfma_f32_16x16x32_bf16 v[6:9], v[172:175], v[222:225], v[6:9]
	v_mfma_f32_16x16x32_bf16 v[2:5], v[180:183], v[222:225], v[2:5]
	s_setprio 0
	s_barrier
	s_add_i32 s52, s52, 2
	s_add_u32 s48, s48, 0x100
	s_addc_u32 s50, s50, 0
	s_cmp_gt_u32 s52, 29
	s_mov_b64 s[24:25], s[2:3]
	s_cbranch_scc0 .LBB0_842
	s_and_b64 vcc, exec, s[12:13]
	s_cbranch_vccz .LBB0_845
	s_barrier

; #define PG8_STAGE(bufoff, gbase, voff) do { _Pragma("unroll") for (int _i = 0; _i < 2; ++_i) \
;         __builtin_amdgcn_global_load_lds((const unsigned*)((const char*)(gbase) + (voff)[_i]), (LAS unsigned*)(lds + (bufoff) + ldsw + _i * 8192), 16, 0, 0); } while (0)
; #define PG8_LDA(dst, b, h) do { _Pragma("unroll") for (int m = 0; m < 4; ++m) _Pragma("unroll") for (int k = 0; k < 2; ++k) dst[m][k] = *(const LAS bf16x8*)(lds + PG8_SA(b, h) + aoff + m * 2048 + k * 1024); } while (0)
; #define PG8_LDB(dst, b, h) do { _Pragma("unroll") for (int n = 0; n < 2; ++n) _Pragma("unroll") for (int k = 0; k < 2; ++k) dst[n][k] = *(const LAS bf16x8*)(lds + PG8_SB(b, h) + boff + n * 2048 + k * 1024); } while (0)
; #define PG8_MMA(ai, bj, At, Bt) do { __builtin_amdgcn_s_setprio(1); _Pragma("unroll") for (int m = 0; m < 4; ++m) _Pragma("unroll") for (int n = 0; n < 2; ++n) _Pragma("unroll") for (int k = 0; k < 2; ++k) \
;         acc[ai][bj][m][n] = __builtin_amdgcn_mfma_f32_16x16x32_bf16(Bt[n][k], At[m][k], acc[ai][bj][m][n], 0, 0, 0); __builtin_amdgcn_s_setprio(0); } while (0)
; #define PG8_WAIT_V(n) asm volatile("s_waitcnt vmcnt(" #n ")" ::: "memory")
; #define PG8_WAIT_L(n) asm volatile("s_waitcnt lgkmcnt(" #n ")" ::: "memory")
; #define PG8_BAR __builtin_amdgcn_s_barrier()
; #define PG8_SCHED __builtin_amdgcn_sched_barrier(0)
; template <class Epi, class Sched>
; __device__ __forceinline__ void gemm_phase(LAS unsigned char* lds, const Gemm g, const Sched& S, const Epi& E) {
;     ...
;         for (int t = 0; t < nt; t += 2) {
;             const bool last = (t == nt - 2);
;             const char* a1 = cA + (size_t)(t + 1) * kstepA;
;             const char* a2 = last ? nA : cA + (size_t)(t + 2) * kstepA; const char* b2 = last ? nB : cB + (size_t)(t + 2) * kstep;
;             const char* a3 = a2 + kstepA; const char* b3 = b2 + kstep;
;             PG8_LDB(B0, 0, 0); PG8_LDB(B1, 0, 1); PG8_SCHED; PG8_LDA(At, 0, 0); PG8_STAGE(PG8_SA(1, 1), a1 + hA, voffA);
;             PG8_WAIT_V(8); PG8_WAIT_L(0); PG8_BAR; PG8_MMA(0, 0, At, B0); PG8_MMA(0, 1, At, B1); PG8_BAR; PG8_SCHED;
;             PG8_LDA(At, 0, 1); PG8_STAGE(PG8_SB(0, 0), b2, voffB); PG8_STAGE(PG8_SB(0, 1), b2 + hB, voffB); PG8_STAGE(PG8_SA(0, 0), a2, voffA);
;             PG8_WAIT_V(8); PG8_WAIT_L(0); PG8_BAR; PG8_MMA(1, 0, At, B0); PG8_MMA(1, 1, At, B1); PG8_BAR; PG8_SCHED;
.LBB0_978:
	s_add_u32 s18, s16, 0xfff80080
	s_addc_u32 s19, s17, -1
	s_add_i32 s41, 0, 0x10000
	s_cmp_eq_u32 s40, 28
	s_cselect_b32 s21, s9, s19
	s_cselect_b32 s20, s36, s18
	v_add_u32_e32 v145, s41, v147
	s_cselect_b32 s19, s7, s39
	s_cselect_b32 s18, s37, s38
	s_add_i32 s46, 0, 0x14000
	ds_read_b128 v[154:157], v145
	ds_read_b128 v[160:163], v145 offset:1024
	ds_read_b128 v[164:167], v145 offset:2048
	ds_read_b128 v[168:171], v145 offset:3072
	v_add_u32_e32 v145, s46, v147
	ds_read_b128 v[172:175], v145
	ds_read_b128 v[176:179], v145 offset:1024
	ds_read_b128 v[180:183], v145 offset:2048
	ds_read_b128 v[184:187], v145 offset:3072
	v_lshl_add_u64 v[212:213], s[16:17], 0, v[140:141]
	s_add_i32 m0, s25, 0xc000
	ds_read_b128 v[188:191], v158
	ds_read_b128 v[192:195], v158 offset:1024
	ds_read_b128 v[196:199], v158 offset:2048
	ds_read_b128 v[200:203], v158 offset:3072
	ds_read_b128 v[204:207], v158 offset:4096
	ds_read_b128 v[208:211], v158 offset:5120
	ds_read_b128 v[220:223], v158 offset:6144
	ds_read_b128 v[224:227], v158 offset:7168
	global_load_lds_dwordx4 v[212:213], off
	v_lshl_add_u64 v[212:213], s[16:17], 0, v[142:143]
	s_add_i32 m0, s25, 0xe000
	s_nop 0
	global_load_lds_dwordx4 v[212:213], off
	s_waitcnt vmcnt(8)
	s_waitcnt lgkmcnt(0)
	s_barrier
	s_setprio 1
	s_waitcnt lgkmcnt(0)
	v_mfma_f32_16x16x32_bf16 v[128:131], v[154:157], v[188:191], v[128:131]
	v_mfma_f32_16x16x32_bf16 v[124:127], v[164:167], v[188:191], v[124:127]
	v_mfma_f32_16x16x32_bf16 v[112:115], v[154:157], v[196:199], v[112:115]
	v_mfma_f32_16x16x32_bf16 v[108:111], v[164:167], v[196:199], v[108:111]
	v_mfma_f32_16x16x32_bf16 v[94:97], v[154:157], v[204:207], v[94:97]
	v_mfma_f32_16x16x32_bf16 v[90:93], v[164:167], v[204:207], v[90:93]
	v_mfma_f32_16x16x32_bf16 v[78:81], v[154:157], v[220:223], v[78:81]
	v_mfma_f32_16x16x32_bf16 v[74:77], v[164:167], v[220:223], v[74:77]
	v_mfma_f32_16x16x32_bf16 v[128:131], v[160:163], v[192:195], v[128:131]
	v_mfma_f32_16x16x32_bf16 v[124:127], v[168:171], v[192:195], v[124:127]
	v_mfma_f32_16x16x32_bf16 v[112:115], v[160:163], v[200:203], v[112:115]
	v_mfma_f32_16x16x32_bf16 v[108:111], v[168:171], v[200:203], v[108:111]
	v_mfma_f32_16x16x32_bf16 v[94:97], v[160:163], v[208:211], v[94:97]
	v_mfma_f32_16x16x32_bf16 v[90:93], v[168:171], v[208:211], v[90:93]
	v_mfma_f32_16x16x32_bf16 v[78:81], v[160:163], v[224:227], v[78:81]
	v_mfma_f32_16x16x32_bf16 v[74:77], v[168:171], v[224:227], v[74:77]
	v_mfma_f32_16x16x32_bf16 v[120:123], v[172:175], v[188:191], v[120:123]
	v_mfma_f32_16x16x32_bf16 v[116:119], v[180:183], v[188:191], v[116:119]
	v_mfma_f32_16x16x32_bf16 v[104:107], v[172:175], v[196:199], v[104:107]
	v_mfma_f32_16x16x32_bf16 v[100:103], v[180:183], v[196:199], v[100:103]
	v_mfma_f32_16x16x32_bf16 v[86:89], v[172:175], v[204:207], v[86:89]
	v_mfma_f32_16x16x32_bf16 v[82:85], v[180:183], v[204:207], v[82:85]
	v_mfma_f32_16x16x32_bf16 v[70:73], v[172:175], v[220:223], v[70:73]
	v_mfma_f32_16x16x32_bf16 v[66:69], v[180:183], v[220:223], v[66:69]
	v_mfma_f32_16x16x32_bf16 v[120:123], v[176:179], v[192:195], v[120:123]
	v_mfma_f32_16x16x32_bf16 v[116:119], v[184:187], v[192:195], v[116:119]
	v_mfma_f32_16x16x32_bf16 v[104:107], v[176:179], v[200:203], v[104:107]
	v_mfma_f32_16x16x32_bf16 v[100:103], v[184:187], v[200:203], v[100:103]
	v_mfma_f32_16x16x32_bf16 v[86:89], v[176:179], v[208:211], v[86:89]
	v_mfma_f32_16x16x32_bf16 v[82:85], v[184:187], v[208:211], v[82:85]
	v_mfma_f32_16x16x32_bf16 v[70:73], v[176:179], v[224:227], v[70:73]
	v_mfma_f32_16x16x32_bf16 v[66:69], v[184:187], v[224:227], v[66:69]
	s_setprio 0
	s_barrier
	s_add_i32 s41, s41, s24
	v_lshl_add_u64 v[212:213], s[18:19], 0, v[136:137]
	s_mov_b32 m0, s41
	ds_read_b128 v[188:191], v158 offset:16384
	ds_read_b128 v[192:195], v158 offset:17408
	ds_read_b128 v[196:199], v158 offset:18432
	ds_read_b128 v[200:203], v158 offset:19456
	ds_read_b128 v[204:207], v158 offset:20480
	ds_read_b128 v[208:211], v158 offset:21504
	ds_read_b128 v[220:223], v158 offset:22528
	ds_read_b128 v[224:227], v158 offset:23552
	global_load_lds_dwordx4 v[212:213], off
	s_add_i32 m0, s41, 0x2000
	s_add_u32 s42, s18, 0x20000
	v_lshl_add_u64 v[228:229], s[18:19], 0, v[132:133]
	s_addc_u32 s43, s19, 0
	s_add_i32 s41, s46, s24
	global_load_lds_dwordx4 v[228:229], off
	v_lshl_add_u64 v[230:231], s[42:43], 0, v[136:137]
	s_mov_b32 m0, s41
	v_lshl_add_u64 v[232:233], s[20:21], 0, v[134:135]
	global_load_lds_dwordx4 v[230:231], off
	v_lshl_add_u64 v[230:231], s[42:43], 0, v[132:133]
	s_add_i32 m0, s41, 0x2000
	s_nop 0
	global_load_lds_dwordx4 v[230:231], off
	v_lshl_add_u64 v[230:231], s[20:21], 0, v[138:139]
	s_mov_b32 m0, s25
	s_nop 0
	global_load_lds_dwordx4 v[230:231], off
	s_mov_b32 m0, s26
	s_nop 0
	global_load_lds_dwordx4 v[232:233], off
	s_waitcnt vmcnt(8)
	s_waitcnt lgkmcnt(0)
	s_barrier
; #define PG8_STAGE(bufoff, gbase, voff) do { _Pragma("unroll") for (int _i = 0; _i < 2; ++_i) \
;         __builtin_amdgcn_global_load_lds((const unsigned*)((const char*)(gbase) + (voff)[_i]), (LAS unsigned*)(lds + (bufoff) + ldsw + _i * 8192), 16, 0, 0); } while (0)
; #define PG8_LDA(dst, b, h) do { _Pragma("unroll") for (int m = 0; m < 4; ++m) _Pragma("unroll") for (int k = 0; k < 2; ++k) dst[m][k] = *(const LAS bf16x8*)(lds + PG8_SA(b, h) + aoff + m * 2048 + k * 1024); } while (0)
; #define PG8_LDB(dst, b, h) do { _Pragma("unroll") for (int n = 0; n < 2; ++n) _Pragma("unroll") for (int k = 0; k < 2; ++k) dst[n][k] = *(const LAS bf16x8*)(lds + PG8_SB(b, h) + boff + n * 2048 + k * 1024); } while (0)
; #define PG8_MMA(ai, bj, At, Bt) do { __builtin_amdgcn_s_setprio(1); _Pragma("unroll") for (int m = 0; m < 4; ++m) _Pragma("unroll") for (int n = 0; n < 2; ++n) _Pragma("unroll") for (int k = 0; k < 2; ++k) \
;         acc[ai][bj][m][n] = __builtin_amdgcn_mfma_f32_16x16x32_bf16(Bt[n][k], At[m][k], acc[ai][bj][m][n], 0, 0, 0); __builtin_amdgcn_s_setprio(0); } while (0)
; #define PG8_WAIT_V(n) asm volatile("s_waitcnt vmcnt(" #n ")" ::: "memory")
; #define PG8_WAIT_L(n) asm volatile("s_waitcnt lgkmcnt(" #n ")" ::: "memory")
; #define PG8_BAR __builtin_amdgcn_s_barrier()
; #define PG8_SCHED __builtin_amdgcn_sched_barrier(0)
; template <class Epi, class Sched>
; __device__ __forceinline__ void gemm_phase(LAS unsigned char* lds, const Gemm g, const Sched& S, const Epi& E) {
;     ...
;             PG8_WAIT_V(8); PG8_WAIT_L(0); PG8_BAR; PG8_MMA(1, 0, At, B0); PG8_MMA(1, 1, At, B1); PG8_BAR; PG8_SCHED;
;             PG8_LDB(B0, 1, 0); PG8_LDB(B1, 1, 1); PG8_SCHED; PG8_LDA(At, 1, 0); PG8_STAGE(PG8_SA(0, 1), a2 + hA, voffA);
;             PG8_WAIT_V(8); PG8_WAIT_L(0); PG8_BAR; PG8_MMA(0, 0, At, B0); PG8_MMA(0, 1, At, B1); PG8_BAR; PG8_SCHED;
;             PG8_LDA(At, 1, 1); PG8_STAGE(PG8_SB(1, 0), b3, voffB); PG8_STAGE(PG8_SB(1, 1), b3 + hB, voffB); PG8_STAGE(PG8_SA(1, 0), a3, voffA);
;             PG8_WAIT_V(8); PG8_WAIT_L(0); PG8_BAR; PG8_MMA(1, 0, At, B0); PG8_MMA(1, 1, At, B1); PG8_BAR; PG8_SCHED;
	s_setprio 1
	s_waitcnt lgkmcnt(0)
	v_mfma_f32_16x16x32_bf16 v[62:65], v[154:157], v[188:191], v[62:65]
	v_mfma_f32_16x16x32_bf16 v[58:61], v[164:167], v[188:191], v[58:61]
	v_mfma_f32_16x16x32_bf16 v[46:49], v[154:157], v[196:199], v[46:49]
	v_mfma_f32_16x16x32_bf16 v[42:45], v[164:167], v[196:199], v[42:45]
	v_mfma_f32_16x16x32_bf16 v[30:33], v[154:157], v[204:207], v[30:33]
	v_mfma_f32_16x16x32_bf16 v[26:29], v[164:167], v[204:207], v[26:29]
	v_mfma_f32_16x16x32_bf16 v[14:17], v[154:157], v[220:223], v[14:17]
	v_mfma_f32_16x16x32_bf16 v[10:13], v[164:167], v[220:223], v[10:13]
	v_mfma_f32_16x16x32_bf16 v[62:65], v[160:163], v[192:195], v[62:65]
	v_mfma_f32_16x16x32_bf16 v[58:61], v[168:171], v[192:195], v[58:61]
	v_mfma_f32_16x16x32_bf16 v[46:49], v[160:163], v[200:203], v[46:49]
	v_mfma_f32_16x16x32_bf16 v[42:45], v[168:171], v[200:203], v[42:45]
	v_mfma_f32_16x16x32_bf16 v[30:33], v[160:163], v[208:211], v[30:33]
	v_mfma_f32_16x16x32_bf16 v[26:29], v[168:171], v[208:211], v[26:29]
	v_mfma_f32_16x16x32_bf16 v[14:17], v[160:163], v[224:227], v[14:17]
	v_mfma_f32_16x16x32_bf16 v[10:13], v[168:171], v[224:227], v[10:13]
	v_mfma_f32_16x16x32_bf16 v[54:57], v[172:175], v[188:191], v[54:57]
	v_mfma_f32_16x16x32_bf16 v[50:53], v[180:183], v[188:191], v[50:53]
	v_mfma_f32_16x16x32_bf16 v[38:41], v[172:175], v[196:199], v[38:41]
	v_mfma_f32_16x16x32_bf16 v[34:37], v[180:183], v[196:199], v[34:37]
	v_mfma_f32_16x16x32_bf16 v[22:25], v[172:175], v[204:207], v[22:25]
	v_mfma_f32_16x16x32_bf16 v[18:21], v[180:183], v[204:207], v[18:21]
	v_mfma_f32_16x16x32_bf16 v[6:9], v[172:175], v[220:223], v[6:9]
	v_mfma_f32_16x16x32_bf16 v[2:5], v[180:183], v[220:223], v[2:5]
	v_mfma_f32_16x16x32_bf16 v[54:57], v[176:179], v[192:195], v[54:57]
	v_mfma_f32_16x16x32_bf16 v[50:53], v[184:187], v[192:195], v[50:53]
	v_mfma_f32_16x16x32_bf16 v[38:41], v[176:179], v[200:203], v[38:41]
	v_mfma_f32_16x16x32_bf16 v[34:37], v[184:187], v[200:203], v[34:37]
	v_mfma_f32_16x16x32_bf16 v[22:25], v[176:179], v[208:211], v[22:25]
	v_mfma_f32_16x16x32_bf16 v[18:21], v[184:187], v[208:211], v[18:21]
	v_mfma_f32_16x16x32_bf16 v[6:9], v[176:179], v[224:227], v[6:9]
	v_mfma_f32_16x16x32_bf16 v[2:5], v[184:187], v[224:227], v[2:5]
	s_setprio 0
	s_barrier
	s_add_i32 s41, 0, 0x18000
	v_add_u32_e32 v145, s41, v147
	s_add_i32 s42, 0, 0x1c000
	ds_read_b128 v[154:157], v145
	ds_read_b128 v[160:163], v145 offset:1024
	ds_read_b128 v[164:167], v145 offset:2048
	ds_read_b128 v[168:171], v145 offset:3072
	v_add_u32_e32 v145, s42, v147
	ds_read_b128 v[172:175], v145
	ds_read_b128 v[176:179], v145 offset:1024
	ds_read_b128 v[180:183], v145 offset:2048
	ds_read_b128 v[184:187], v145 offset:3072
	s_add_u32 s20, s20, 0x80000
	s_addc_u32 s21, s21, 0
	s_mov_b32 m0, s27
	v_lshl_add_u64 v[234:235], s[20:21], 0, v[138:139]
	ds_read_b128 v[188:191], v158 offset:32768
	ds_read_b128 v[192:195], v158 offset:33792
	ds_read_b128 v[196:199], v158 offset:34816
	ds_read_b128 v[200:203], v158 offset:35840
	ds_read_b128 v[204:207], v158 offset:36864
	ds_read_b128 v[208:211], v158 offset:37888
	ds_read_b128 v[220:223], v158 offset:38912
	ds_read_b128 v[224:227], v158 offset:39936
	global_load_lds_dwordx4 v[234:235], off
	v_lshl_add_u64 v[234:235], s[20:21], 0, v[134:135]
	s_mov_b32 m0, s28
	s_nop 0
	global_load_lds_dwordx4 v[234:235], off
	s_waitcnt vmcnt(8)
	s_waitcnt lgkmcnt(0)
	s_barrier
	s_setprio 1
	s_waitcnt lgkmcnt(0)
	v_mfma_f32_16x16x32_bf16 v[128:131], v[154:157], v[188:191], v[128:131]
	v_mfma_f32_16x16x32_bf16 v[124:127], v[164:167], v[188:191], v[124:127]
	v_mfma_f32_16x16x32_bf16 v[112:115], v[154:157], v[196:199], v[112:115]
	v_mfma_f32_16x16x32_bf16 v[108:111], v[164:167], v[196:199], v[108:111]
	v_mfma_f32_16x16x32_bf16 v[94:97], v[154:157], v[204:207], v[94:97]
	v_mfma_f32_16x16x32_bf16 v[90:93], v[164:167], v[204:207], v[90:93]
	v_mfma_f32_16x16x32_bf16 v[78:81], v[154:157], v[220:223], v[78:81]
	v_mfma_f32_16x16x32_bf16 v[74:77], v[164:167], v[220:223], v[74:77]
	v_mfma_f32_16x16x32_bf16 v[128:131], v[160:163], v[192:195], v[128:131]
	v_mfma_f32_16x16x32_bf16 v[124:127], v[168:171], v[192:195], v[124:127]
	v_mfma_f32_16x16x32_bf16 v[112:115], v[160:163], v[200:203], v[112:115]
	v_mfma_f32_16x16x32_bf16 v[108:111], v[168:171], v[200:203], v[108:111]
	v_mfma_f32_16x16x32_bf16 v[94:97], v[160:163], v[208:211], v[94:97]
	v_mfma_f32_16x16x32_bf16 v[90:93], v[168:171], v[208:211], v[90:93]
	v_mfma_f32_16x16x32_bf16 v[78:81], v[160:163], v[224:227], v[78:81]
	v_mfma_f32_16x16x32_bf16 v[74:77], v[168:171], v[224:227], v[74:77]
	v_mfma_f32_16x16x32_bf16 v[120:123], v[172:175], v[188:191], v[120:123]
	v_mfma_f32_16x16x32_bf16 v[116:119], v[180:183], v[188:191], v[116:119]
	v_mfma_f32_16x16x32_bf16 v[104:107], v[172:175], v[196:199], v[104:107]
	v_mfma_f32_16x16x32_bf16 v[100:103], v[180:183], v[196:199], v[100:103]
	v_mfma_f32_16x16x32_bf16 v[86:89], v[172:175], v[204:207], v[86:89]
	v_mfma_f32_16x16x32_bf16 v[82:85], v[180:183], v[204:207], v[82:85]
	v_mfma_f32_16x16x32_bf16 v[70:73], v[172:175], v[220:223], v[70:73]
	v_mfma_f32_16x16x32_bf16 v[66:69], v[180:183], v[220:223], v[66:69]
	v_mfma_f32_16x16x32_bf16 v[120:123], v[176:179], v[192:195], v[120:123]
	v_mfma_f32_16x16x32_bf16 v[116:119], v[184:187], v[192:195], v[116:119]
	v_mfma_f32_16x16x32_bf16 v[104:107], v[176:179], v[200:203], v[104:107]
	v_mfma_f32_16x16x32_bf16 v[100:103], v[184:187], v[200:203], v[100:103]
	v_mfma_f32_16x16x32_bf16 v[86:89], v[176:179], v[208:211], v[86:89]
	v_mfma_f32_16x16x32_bf16 v[82:85], v[184:187], v[208:211], v[82:85]
	v_mfma_f32_16x16x32_bf16 v[70:73], v[176:179], v[224:227], v[70:73]
	v_mfma_f32_16x16x32_bf16 v[66:69], v[184:187], v[224:227], v[66:69]
	s_setprio 0
	s_barrier
; #define PG8_STAGE(bufoff, gbase, voff) do { _Pragma("unroll") for (int _i = 0; _i < 2; ++_i) \
;         __builtin_amdgcn_global_load_lds((const unsigned*)((const char*)(gbase) + (voff)[_i]), (LAS unsigned*)(lds + (bufoff) + ldsw + _i * 8192), 16, 0, 0); } while (0)
; #define PG8_LDA(dst, b, h) do { _Pragma("unroll") for (int m = 0; m < 4; ++m) _Pragma("unroll") for (int k = 0; k < 2; ++k) dst[m][k] = *(const LAS bf16x8*)(lds + PG8_SA(b, h) + aoff + m * 2048 + k * 1024); } while (0)
; #define PG8_MMA(ai, bj, At, Bt) do { __builtin_amdgcn_s_setprio(1); _Pragma("unroll") for (int m = 0; m < 4; ++m) _Pragma("unroll") for (int n = 0; n < 2; ++n) _Pragma("unroll") for (int k = 0; k < 2; ++k) \
;         acc[ai][bj][m][n] = __builtin_amdgcn_mfma_f32_16x16x32_bf16(Bt[n][k], At[m][k], acc[ai][bj][m][n], 0, 0, 0); __builtin_amdgcn_s_setprio(0); } while (0)
; #define PG8_WAIT_V(n) asm volatile("s_waitcnt vmcnt(" #n ")" ::: "memory")
; #define PG8_WAIT_L(n) asm volatile("s_waitcnt lgkmcnt(" #n ")" ::: "memory")
; #define PG8_BAR __builtin_amdgcn_s_barrier()
; #define PG8_SCHED __builtin_amdgcn_sched_barrier(0)
; template <class Epi, class Sched>
; __device__ __forceinline__ void gemm_phase(LAS unsigned char* lds, const Gemm g, const Sched& S, const Epi& E) {
;     ...
;             PG8_LDA(At, 1, 1); PG8_STAGE(PG8_SB(1, 0), b3, voffB); PG8_STAGE(PG8_SB(1, 1), b3 + hB, voffB); PG8_STAGE(PG8_SA(1, 0), a3, voffA);
;             PG8_WAIT_V(8); PG8_WAIT_L(0); PG8_BAR; PG8_MMA(1, 0, At, B0); PG8_MMA(1, 1, At, B1); PG8_BAR; PG8_SCHED;
;         }
;         if (wr == 0) PG8_BAR;
	s_add_i32 s20, s41, s24
	v_lshl_add_u64 v[212:213], v[212:213], 0, s[76:77]
	s_mov_b32 m0, s20
	ds_read_b128 v[188:191], v158 offset:49152
	ds_read_b128 v[192:195], v158 offset:50176
	ds_read_b128 v[196:199], v158 offset:51200
	ds_read_b128 v[200:203], v158 offset:52224
	ds_read_b128 v[204:207], v158 offset:53248
	ds_read_b128 v[208:211], v158 offset:54272
	ds_read_b128 v[220:223], v158 offset:55296
	ds_read_b128 v[224:227], v158 offset:56320
	global_load_lds_dwordx4 v[212:213], off
	s_add_i32 m0, s20, 0x2000
	s_add_u32 s18, s18, 0x20080
	v_lshl_add_u64 v[212:213], v[228:229], 0, s[76:77]
	s_addc_u32 s19, s19, 0
	s_add_i32 s20, s42, s24
	global_load_lds_dwordx4 v[212:213], off
	v_lshl_add_u64 v[212:213], s[18:19], 0, v[136:137]
	s_mov_b32 m0, s20
	s_nop 0
	global_load_lds_dwordx4 v[212:213], off
	v_lshl_add_u64 v[212:213], s[18:19], 0, v[132:133]
	s_add_i32 m0, s20, 0x2000
	s_nop 0
	global_load_lds_dwordx4 v[212:213], off
	v_lshl_add_u64 v[212:213], v[230:231], 0, s[76:77]
	s_mov_b32 m0, s30
	s_nop 0
	global_load_lds_dwordx4 v[212:213], off
	v_lshl_add_u64 v[212:213], v[232:233], 0, s[76:77]
	s_mov_b32 m0, s31
	s_nop 0
	global_load_lds_dwordx4 v[212:213], off
	s_waitcnt vmcnt(8)
	s_waitcnt lgkmcnt(0)
	s_barrier
	s_setprio 1
	s_waitcnt lgkmcnt(0)
	v_mfma_f32_16x16x32_bf16 v[62:65], v[154:157], v[188:191], v[62:65]
	v_mfma_f32_16x16x32_bf16 v[58:61], v[164:167], v[188:191], v[58:61]
	v_mfma_f32_16x16x32_bf16 v[46:49], v[154:157], v[196:199], v[46:49]
	v_mfma_f32_16x16x32_bf16 v[42:45], v[164:167], v[196:199], v[42:45]
	v_mfma_f32_16x16x32_bf16 v[30:33], v[154:157], v[204:207], v[30:33]
	v_mfma_f32_16x16x32_bf16 v[26:29], v[164:167], v[204:207], v[26:29]
	v_mfma_f32_16x16x32_bf16 v[14:17], v[154:157], v[220:223], v[14:17]
	v_mfma_f32_16x16x32_bf16 v[10:13], v[164:167], v[220:223], v[10:13]
	v_mfma_f32_16x16x32_bf16 v[62:65], v[160:163], v[192:195], v[62:65]
	v_mfma_f32_16x16x32_bf16 v[58:61], v[168:171], v[192:195], v[58:61]
	v_mfma_f32_16x16x32_bf16 v[46:49], v[160:163], v[200:203], v[46:49]
	v_mfma_f32_16x16x32_bf16 v[42:45], v[168:171], v[200:203], v[42:45]
	v_mfma_f32_16x16x32_bf16 v[30:33], v[160:163], v[208:211], v[30:33]
	v_mfma_f32_16x16x32_bf16 v[26:29], v[168:171], v[208:211], v[26:29]
	v_mfma_f32_16x16x32_bf16 v[14:17], v[160:163], v[224:227], v[14:17]
	v_mfma_f32_16x16x32_bf16 v[10:13], v[168:171], v[224:227], v[10:13]
	v_mfma_f32_16x16x32_bf16 v[54:57], v[172:175], v[188:191], v[54:57]
	v_mfma_f32_16x16x32_bf16 v[50:53], v[180:183], v[188:191], v[50:53]
	v_mfma_f32_16x16x32_bf16 v[38:41], v[172:175], v[196:199], v[38:41]
	v_mfma_f32_16x16x32_bf16 v[34:37], v[180:183], v[196:199], v[34:37]
	v_mfma_f32_16x16x32_bf16 v[22:25], v[172:175], v[204:207], v[22:25]
	v_mfma_f32_16x16x32_bf16 v[18:21], v[180:183], v[204:207], v[18:21]
	v_mfma_f32_16x16x32_bf16 v[6:9], v[172:175], v[220:223], v[6:9]
	v_mfma_f32_16x16x32_bf16 v[2:5], v[180:183], v[220:223], v[2:5]
	v_mfma_f32_16x16x32_bf16 v[54:57], v[176:179], v[192:195], v[54:57]
	v_mfma_f32_16x16x32_bf16 v[50:53], v[184:187], v[192:195], v[50:53]
	v_mfma_f32_16x16x32_bf16 v[38:41], v[176:179], v[200:203], v[38:41]
	v_mfma_f32_16x16x32_bf16 v[34:37], v[184:187], v[200:203], v[34:37]
	v_mfma_f32_16x16x32_bf16 v[22:25], v[176:179], v[208:211], v[22:25]
	v_mfma_f32_16x16x32_bf16 v[18:21], v[184:187], v[208:211], v[18:21]
	v_mfma_f32_16x16x32_bf16 v[6:9], v[176:179], v[224:227], v[6:9]
	v_mfma_f32_16x16x32_bf16 v[2:5], v[184:187], v[224:227], v[2:5]
	s_setprio 0
	s_barrier
	s_add_i32 s40, s40, 2
	s_add_u32 s16, s16, 0x100
	s_addc_u32 s17, s17, 0
	s_add_u32 s38, s38, 0x100
	s_addc_u32 s39, s39, 0
	s_cmp_gt_u32 s40, 29
	s_cbranch_scc0 .LBB0_978
	s_and_b64 vcc, exec, s[4:5]
	s_cbranch_vccz .LBB0_981
	s_barrier

; #define PG8_STAGE(bufoff, gbase, voff) do { _Pragma("unroll") for (int _i = 0; _i < 2; ++_i) \
;         __builtin_amdgcn_global_load_lds((const unsigned*)((const char*)(gbase) + (voff)[_i]), (LAS unsigned*)(lds + (bufoff) + ldsw + _i * 8192), 16, 0, 0); } while (0)
; #define PG8_LDA(dst, b, h) do { _Pragma("unroll") for (int m = 0; m < 4; ++m) _Pragma("unroll") for (int k = 0; k < 2; ++k) dst[m][k] = *(const LAS bf16x8*)(lds + PG8_SA(b, h) + aoff + m * 2048 + k * 1024); } while (0)
; #define PG8_LDB(dst, b, h) do { _Pragma("unroll") for (int n = 0; n < 2; ++n) _Pragma("unroll") for (int k = 0; k < 2; ++k) dst[n][k] = *(const LAS bf16x8*)(lds + PG8_SB(b, h) + boff + n * 2048 + k * 1024); } while (0)
; #define PG8_MMA(ai, bj, At, Bt) do { __builtin_amdgcn_s_setprio(1); _Pragma("unroll") for (int m = 0; m < 4; ++m) _Pragma("unroll") for (int n = 0; n < 2; ++n) _Pragma("unroll") for (int k = 0; k < 2; ++k) \
;         acc[ai][bj][m][n] = __builtin_amdgcn_mfma_f32_16x16x32_bf16(Bt[n][k], At[m][k], acc[ai][bj][m][n], 0, 0, 0); __builtin_amdgcn_s_setprio(0); } while (0)
; #define PG8_WAIT_V(n) asm volatile("s_waitcnt vmcnt(" #n ")" ::: "memory")
; #define PG8_WAIT_L(n) asm volatile("s_waitcnt lgkmcnt(" #n ")" ::: "memory")
; #define PG8_BAR __builtin_amdgcn_s_barrier()
; #define PG8_SCHED __builtin_amdgcn_sched_barrier(0)
; template <class Epi, class Sched>
; __device__ __forceinline__ void gemm_phase(LAS unsigned char* lds, const Gemm g, const Sched& S, const Epi& E) {
;     ...
;         for (int t = 0; t < nt; t += 2) {
;             const bool last = (t == nt - 2);
;             const char* a1 = cA + (size_t)(t + 1) * kstepA;
;             const char* a2 = last ? nA : cA + (size_t)(t + 2) * kstepA; const char* b2 = last ? nB : cB + (size_t)(t + 2) * kstep;
;             const char* a3 = a2 + kstepA; const char* b3 = b2 + kstep;
;             PG8_LDB(B0, 0, 0); PG8_LDB(B1, 0, 1); PG8_SCHED; PG8_LDA(At, 0, 0); PG8_STAGE(PG8_SA(1, 1), a1 + hA, voffA);
;             PG8_WAIT_V(8); PG8_WAIT_L(0); PG8_BAR; PG8_MMA(0, 0, At, B0); PG8_MMA(0, 1, At, B1); PG8_BAR; PG8_SCHED;
;             PG8_LDA(At, 0, 1); PG8_STAGE(PG8_SB(0, 0), b2, voffB); PG8_STAGE(PG8_SB(0, 1), b2 + hB, voffB); PG8_STAGE(PG8_SA(0, 0), a2, voffA);
;             PG8_WAIT_V(8); PG8_WAIT_L(0); PG8_BAR; PG8_MMA(1, 0, At, B0); PG8_MMA(1, 1, At, B1); PG8_BAR; PG8_SCHED;
.LBB0_1048:
	s_add_u32 s2, s20, 0x200
	s_addc_u32 s3, s21, 0
	s_add_i32 s47, 0, 0x10000
	s_cmpk_eq_i32 s46, 0x54
	s_cselect_b32 s25, s5, s3
	s_cselect_b32 s24, s4, s2
	s_cselect_b32 s23, s19, s43
	s_cselect_b32 s22, s18, s42
	s_add_i32 s48, 0, 0x14000
	v_add_u32_e32 v154, s47, v221
	v_add_u32_e32 v178, s48, v221
	ds_read_b128 v[132:135], v154
	ds_read_b128 v[136:139], v154 offset:1024
	ds_read_b128 v[140:143], v154 offset:2048
	ds_read_b128 v[154:157], v154 offset:3072
	ds_read_b128 v[166:169], v178
	ds_read_b128 v[170:173], v178 offset:1024
	ds_read_b128 v[174:177], v178 offset:2048
	ds_read_b128 v[178:181], v178 offset:3072
	v_lshl_add_u64 v[226:227], s[20:21], 0, v[162:163]
	s_add_i32 m0, s29, 0xc000
	ds_read_b128 v[182:185], v224
	ds_read_b128 v[186:189], v224 offset:1024
	ds_read_b128 v[190:193], v224 offset:2048
	ds_read_b128 v[194:197], v224 offset:3072
	ds_read_b128 v[198:201], v224 offset:4096
	ds_read_b128 v[202:205], v224 offset:5120
	ds_read_b128 v[206:209], v224 offset:6144
	ds_read_b128 v[210:213], v224 offset:7168
	global_load_lds_dwordx4 v[226:227], off
	v_lshl_add_u64 v[226:227], s[20:21], 0, v[164:165]
	s_add_i32 m0, s29, 0xe000
	s_nop 0
	global_load_lds_dwordx4 v[226:227], off
	s_waitcnt vmcnt(8)
	s_waitcnt lgkmcnt(0)
	s_barrier
	s_setprio 1
	s_waitcnt lgkmcnt(0)
	v_mfma_f32_16x16x32_bf16 v[128:131], v[132:135], v[182:185], v[128:131]
	v_mfma_f32_16x16x32_bf16 v[124:127], v[140:143], v[182:185], v[124:127]
	v_mfma_f32_16x16x32_bf16 v[112:115], v[132:135], v[190:193], v[112:115]
	v_mfma_f32_16x16x32_bf16 v[108:111], v[140:143], v[190:193], v[108:111]
	v_mfma_f32_16x16x32_bf16 v[94:97], v[132:135], v[198:201], v[94:97]
	v_mfma_f32_16x16x32_bf16 v[90:93], v[140:143], v[198:201], v[90:93]
	v_mfma_f32_16x16x32_bf16 v[78:81], v[132:135], v[206:209], v[78:81]
	v_mfma_f32_16x16x32_bf16 v[74:77], v[140:143], v[206:209], v[74:77]
	v_mfma_f32_16x16x32_bf16 v[128:131], v[136:139], v[186:189], v[128:131]
	v_mfma_f32_16x16x32_bf16 v[124:127], v[154:157], v[186:189], v[124:127]
	v_mfma_f32_16x16x32_bf16 v[112:115], v[136:139], v[194:197], v[112:115]
	v_mfma_f32_16x16x32_bf16 v[108:111], v[154:157], v[194:197], v[108:111]
	v_mfma_f32_16x16x32_bf16 v[94:97], v[136:139], v[202:205], v[94:97]
	v_mfma_f32_16x16x32_bf16 v[90:93], v[154:157], v[202:205], v[90:93]
	v_mfma_f32_16x16x32_bf16 v[78:81], v[136:139], v[210:213], v[78:81]
	v_mfma_f32_16x16x32_bf16 v[74:77], v[154:157], v[210:213], v[74:77]
	v_mfma_f32_16x16x32_bf16 v[120:123], v[166:169], v[182:185], v[120:123]
	v_mfma_f32_16x16x32_bf16 v[116:119], v[174:177], v[182:185], v[116:119]
	v_mfma_f32_16x16x32_bf16 v[104:107], v[166:169], v[190:193], v[104:107]
	v_mfma_f32_16x16x32_bf16 v[100:103], v[174:177], v[190:193], v[100:103]
	v_mfma_f32_16x16x32_bf16 v[86:89], v[166:169], v[198:201], v[86:89]
	v_mfma_f32_16x16x32_bf16 v[82:85], v[174:177], v[198:201], v[82:85]
	v_mfma_f32_16x16x32_bf16 v[70:73], v[166:169], v[206:209], v[70:73]
	v_mfma_f32_16x16x32_bf16 v[66:69], v[174:177], v[206:209], v[66:69]
	v_mfma_f32_16x16x32_bf16 v[120:123], v[170:173], v[186:189], v[120:123]
	v_mfma_f32_16x16x32_bf16 v[116:119], v[178:181], v[186:189], v[116:119]
	v_mfma_f32_16x16x32_bf16 v[104:107], v[170:173], v[194:197], v[104:107]
	v_mfma_f32_16x16x32_bf16 v[100:103], v[178:181], v[194:197], v[100:103]
	v_mfma_f32_16x16x32_bf16 v[86:89], v[170:173], v[202:205], v[86:89]
	v_mfma_f32_16x16x32_bf16 v[82:85], v[178:181], v[202:205], v[82:85]
	v_mfma_f32_16x16x32_bf16 v[70:73], v[170:173], v[210:213], v[70:73]
	v_mfma_f32_16x16x32_bf16 v[66:69], v[178:181], v[210:213], v[66:69]
	s_setprio 0
	s_barrier
	s_add_i32 s20, s47, s28
	v_lshl_add_u64 v[226:227], s[22:23], 0, v[158:159]
	s_mov_b32 m0, s20
	ds_read_b128 v[182:185], v224 offset:16384
	ds_read_b128 v[186:189], v224 offset:17408
	ds_read_b128 v[190:193], v224 offset:18432
	ds_read_b128 v[194:197], v224 offset:19456
	ds_read_b128 v[198:201], v224 offset:20480
	ds_read_b128 v[202:205], v224 offset:21504
	ds_read_b128 v[206:209], v224 offset:22528
	ds_read_b128 v[210:213], v224 offset:23552
	global_load_lds_dwordx4 v[226:227], off
	s_add_i32 m0, s20, 0x2000
	s_add_u32 s20, s22, 0x58000
	v_lshl_add_u64 v[228:229], s[22:23], 0, v[144:145]
	s_addc_u32 s21, s23, 0
	s_add_i32 s47, s48, s28
	global_load_lds_dwordx4 v[228:229], off
	v_lshl_add_u64 v[230:231], s[20:21], 0, v[158:159]
	s_mov_b32 m0, s47
	v_lshl_add_u64 v[232:233], s[24:25], 0, v[146:147]
	global_load_lds_dwordx4 v[230:231], off
	v_lshl_add_u64 v[230:231], s[20:21], 0, v[144:145]
	s_add_i32 m0, s47, 0x2000
	s_nop 0
	global_load_lds_dwordx4 v[230:231], off
	v_lshl_add_u64 v[230:231], s[24:25], 0, v[160:161]
	s_mov_b32 m0, s29
	s_nop 0
	global_load_lds_dwordx4 v[230:231], off
	s_mov_b32 m0, s30
	s_nop 0
	global_load_lds_dwordx4 v[232:233], off
	s_waitcnt vmcnt(8)
	s_waitcnt lgkmcnt(0)
	s_barrier
; #define PG8_STAGE(bufoff, gbase, voff) do { _Pragma("unroll") for (int _i = 0; _i < 2; ++_i) \
;         __builtin_amdgcn_global_load_lds((const unsigned*)((const char*)(gbase) + (voff)[_i]), (LAS unsigned*)(lds + (bufoff) + ldsw + _i * 8192), 16, 0, 0); } while (0)
; #define PG8_LDA(dst, b, h) do { _Pragma("unroll") for (int m = 0; m < 4; ++m) _Pragma("unroll") for (int k = 0; k < 2; ++k) dst[m][k] = *(const LAS bf16x8*)(lds + PG8_SA(b, h) + aoff + m * 2048 + k * 1024); } while (0)
; #define PG8_LDB(dst, b, h) do { _Pragma("unroll") for (int n = 0; n < 2; ++n) _Pragma("unroll") for (int k = 0; k < 2; ++k) dst[n][k] = *(const LAS bf16x8*)(lds + PG8_SB(b, h) + boff + n * 2048 + k * 1024); } while (0)
; #define PG8_MMA(ai, bj, At, Bt) do { __builtin_amdgcn_s_setprio(1); _Pragma("unroll") for (int m = 0; m < 4; ++m) _Pragma("unroll") for (int n = 0; n < 2; ++n) _Pragma("unroll") for (int k = 0; k < 2; ++k) \
;         acc[ai][bj][m][n] = __builtin_amdgcn_mfma_f32_16x16x32_bf16(Bt[n][k], At[m][k], acc[ai][bj][m][n], 0, 0, 0); __builtin_amdgcn_s_setprio(0); } while (0)
; #define PG8_WAIT_V(n) asm volatile("s_waitcnt vmcnt(" #n ")" ::: "memory")
; #define PG8_WAIT_L(n) asm volatile("s_waitcnt lgkmcnt(" #n ")" ::: "memory")
; #define PG8_BAR __builtin_amdgcn_s_barrier()
; #define PG8_SCHED __builtin_amdgcn_sched_barrier(0)
; template <class Epi, class Sched>
; __device__ __forceinline__ void gemm_phase(LAS unsigned char* lds, const Gemm g, const Sched& S, const Epi& E) {
;     ...
;             PG8_WAIT_V(8); PG8_WAIT_L(0); PG8_BAR; PG8_MMA(1, 0, At, B0); PG8_MMA(1, 1, At, B1); PG8_BAR; PG8_SCHED;
;             PG8_LDB(B0, 1, 0); PG8_LDB(B1, 1, 1); PG8_SCHED; PG8_LDA(At, 1, 0); PG8_STAGE(PG8_SA(0, 1), a2 + hA, voffA);
;             PG8_WAIT_V(8); PG8_WAIT_L(0); PG8_BAR; PG8_MMA(0, 0, At, B0); PG8_MMA(0, 1, At, B1); PG8_BAR; PG8_SCHED;
;             PG8_LDA(At, 1, 1); PG8_STAGE(PG8_SB(1, 0), b3, voffB); PG8_STAGE(PG8_SB(1, 1), b3 + hB, voffB); PG8_STAGE(PG8_SA(1, 0), a3, voffA);
;             PG8_WAIT_V(8); PG8_WAIT_L(0); PG8_BAR; PG8_MMA(1, 0, At, B0); PG8_MMA(1, 1, At, B1); PG8_BAR; PG8_SCHED;
	s_setprio 1
	s_waitcnt lgkmcnt(0)
	v_mfma_f32_16x16x32_bf16 v[62:65], v[132:135], v[182:185], v[62:65]
	v_mfma_f32_16x16x32_bf16 v[58:61], v[140:143], v[182:185], v[58:61]
	v_mfma_f32_16x16x32_bf16 v[46:49], v[132:135], v[190:193], v[46:49]
	v_mfma_f32_16x16x32_bf16 v[42:45], v[140:143], v[190:193], v[42:45]
	v_mfma_f32_16x16x32_bf16 v[30:33], v[132:135], v[198:201], v[30:33]
	v_mfma_f32_16x16x32_bf16 v[26:29], v[140:143], v[198:201], v[26:29]
	v_mfma_f32_16x16x32_bf16 v[14:17], v[132:135], v[206:209], v[14:17]
	v_mfma_f32_16x16x32_bf16 v[10:13], v[140:143], v[206:209], v[10:13]
	v_mfma_f32_16x16x32_bf16 v[62:65], v[136:139], v[186:189], v[62:65]
	v_mfma_f32_16x16x32_bf16 v[58:61], v[154:157], v[186:189], v[58:61]
	v_mfma_f32_16x16x32_bf16 v[46:49], v[136:139], v[194:197], v[46:49]
	v_mfma_f32_16x16x32_bf16 v[42:45], v[154:157], v[194:197], v[42:45]
	v_mfma_f32_16x16x32_bf16 v[30:33], v[136:139], v[202:205], v[30:33]
	v_mfma_f32_16x16x32_bf16 v[26:29], v[154:157], v[202:205], v[26:29]
	v_mfma_f32_16x16x32_bf16 v[14:17], v[136:139], v[210:213], v[14:17]
	v_mfma_f32_16x16x32_bf16 v[10:13], v[154:157], v[210:213], v[10:13]
	v_mfma_f32_16x16x32_bf16 v[54:57], v[166:169], v[182:185], v[54:57]
	v_mfma_f32_16x16x32_bf16 v[50:53], v[174:177], v[182:185], v[50:53]
	v_mfma_f32_16x16x32_bf16 v[38:41], v[166:169], v[190:193], v[38:41]
	v_mfma_f32_16x16x32_bf16 v[34:37], v[174:177], v[190:193], v[34:37]
	v_mfma_f32_16x16x32_bf16 v[22:25], v[166:169], v[198:201], v[22:25]
	v_mfma_f32_16x16x32_bf16 v[18:21], v[174:177], v[198:201], v[18:21]
	v_mfma_f32_16x16x32_bf16 v[6:9], v[166:169], v[206:209], v[6:9]
	v_mfma_f32_16x16x32_bf16 v[2:5], v[174:177], v[206:209], v[2:5]
	v_mfma_f32_16x16x32_bf16 v[54:57], v[170:173], v[186:189], v[54:57]
	v_mfma_f32_16x16x32_bf16 v[50:53], v[178:181], v[186:189], v[50:53]
	v_mfma_f32_16x16x32_bf16 v[38:41], v[170:173], v[194:197], v[38:41]
	v_mfma_f32_16x16x32_bf16 v[34:37], v[178:181], v[194:197], v[34:37]
	v_mfma_f32_16x16x32_bf16 v[22:25], v[170:173], v[202:205], v[22:25]
	v_mfma_f32_16x16x32_bf16 v[18:21], v[178:181], v[202:205], v[18:21]
	v_mfma_f32_16x16x32_bf16 v[6:9], v[170:173], v[210:213], v[6:9]
	v_mfma_f32_16x16x32_bf16 v[2:5], v[178:181], v[210:213], v[2:5]
	s_setprio 0
	s_barrier
	s_add_i32 s47, 0, 0x18000
	s_add_i32 s48, 0, 0x1c000
	v_add_u32_e32 v154, s47, v221
	v_add_u32_e32 v178, s48, v221
	ds_read_b128 v[132:135], v154
	ds_read_b128 v[136:139], v154 offset:1024
	ds_read_b128 v[140:143], v154 offset:2048
	ds_read_b128 v[154:157], v154 offset:3072
	ds_read_b128 v[166:169], v178
	ds_read_b128 v[170:173], v178 offset:1024
	ds_read_b128 v[174:177], v178 offset:2048
	ds_read_b128 v[178:181], v178 offset:3072
	s_add_u32 s20, s24, 0x160000
	s_addc_u32 s21, s25, 0
	s_mov_b32 m0, s31
	v_lshl_add_u64 v[234:235], s[20:21], 0, v[160:161]
	ds_read_b128 v[182:185], v224 offset:32768
	ds_read_b128 v[186:189], v224 offset:33792
	ds_read_b128 v[190:193], v224 offset:34816
	ds_read_b128 v[194:197], v224 offset:35840
	ds_read_b128 v[198:201], v224 offset:36864
	ds_read_b128 v[202:205], v224 offset:37888
	ds_read_b128 v[206:209], v224 offset:38912
	ds_read_b128 v[210:213], v224 offset:39936
	global_load_lds_dwordx4 v[234:235], off
	v_lshl_add_u64 v[234:235], s[20:21], 0, v[146:147]
	s_mov_b32 m0, s34
	s_nop 0
	global_load_lds_dwordx4 v[234:235], off
	s_waitcnt vmcnt(8)
	s_waitcnt lgkmcnt(0)
	s_barrier
	s_setprio 1
	s_waitcnt lgkmcnt(0)
	v_mfma_f32_16x16x32_bf16 v[128:131], v[132:135], v[182:185], v[128:131]
	v_mfma_f32_16x16x32_bf16 v[124:127], v[140:143], v[182:185], v[124:127]
	v_mfma_f32_16x16x32_bf16 v[112:115], v[132:135], v[190:193], v[112:115]
	v_mfma_f32_16x16x32_bf16 v[108:111], v[140:143], v[190:193], v[108:111]
	v_mfma_f32_16x16x32_bf16 v[94:97], v[132:135], v[198:201], v[94:97]
	v_mfma_f32_16x16x32_bf16 v[90:93], v[140:143], v[198:201], v[90:93]
	v_mfma_f32_16x16x32_bf16 v[78:81], v[132:135], v[206:209], v[78:81]
	v_mfma_f32_16x16x32_bf16 v[74:77], v[140:143], v[206:209], v[74:77]
	v_mfma_f32_16x16x32_bf16 v[128:131], v[136:139], v[186:189], v[128:131]
	v_mfma_f32_16x16x32_bf16 v[124:127], v[154:157], v[186:189], v[124:127]
	v_mfma_f32_16x16x32_bf16 v[112:115], v[136:139], v[194:197], v[112:115]
	v_mfma_f32_16x16x32_bf16 v[108:111], v[154:157], v[194:197], v[108:111]
	v_mfma_f32_16x16x32_bf16 v[94:97], v[136:139], v[202:205], v[94:97]
	v_mfma_f32_16x16x32_bf16 v[90:93], v[154:157], v[202:205], v[90:93]
	v_mfma_f32_16x16x32_bf16 v[78:81], v[136:139], v[210:213], v[78:81]
	v_mfma_f32_16x16x32_bf16 v[74:77], v[154:157], v[210:213], v[74:77]
	v_mfma_f32_16x16x32_bf16 v[120:123], v[166:169], v[182:185], v[120:123]
	v_mfma_f32_16x16x32_bf16 v[116:119], v[174:177], v[182:185], v[116:119]
	v_mfma_f32_16x16x32_bf16 v[104:107], v[166:169], v[190:193], v[104:107]
	v_mfma_f32_16x16x32_bf16 v[100:103], v[174:177], v[190:193], v[100:103]
	v_mfma_f32_16x16x32_bf16 v[86:89], v[166:169], v[198:201], v[86:89]
	v_mfma_f32_16x16x32_bf16 v[82:85], v[174:177], v[198:201], v[82:85]
	v_mfma_f32_16x16x32_bf16 v[70:73], v[166:169], v[206:209], v[70:73]
	v_mfma_f32_16x16x32_bf16 v[66:69], v[174:177], v[206:209], v[66:69]
	v_mfma_f32_16x16x32_bf16 v[120:123], v[170:173], v[186:189], v[120:123]
	v_mfma_f32_16x16x32_bf16 v[116:119], v[178:181], v[186:189], v[116:119]
	v_mfma_f32_16x16x32_bf16 v[104:107], v[170:173], v[194:197], v[104:107]
	v_mfma_f32_16x16x32_bf16 v[100:103], v[178:181], v[194:197], v[100:103]
	v_mfma_f32_16x16x32_bf16 v[86:89], v[170:173], v[202:205], v[86:89]
	v_mfma_f32_16x16x32_bf16 v[82:85], v[178:181], v[202:205], v[82:85]
	v_mfma_f32_16x16x32_bf16 v[70:73], v[170:173], v[210:213], v[70:73]
	v_mfma_f32_16x16x32_bf16 v[66:69], v[178:181], v[210:213], v[66:69]
	s_setprio 0
	s_barrier
; #define PG8_STAGE(bufoff, gbase, voff) do { _Pragma("unroll") for (int _i = 0; _i < 2; ++_i) \
;         __builtin_amdgcn_global_load_lds((const unsigned*)((const char*)(gbase) + (voff)[_i]), (LAS unsigned*)(lds + (bufoff) + ldsw + _i * 8192), 16, 0, 0); } while (0)
; #define PG8_LDA(dst, b, h) do { _Pragma("unroll") for (int m = 0; m < 4; ++m) _Pragma("unroll") for (int k = 0; k < 2; ++k) dst[m][k] = *(const LAS bf16x8*)(lds + PG8_SA(b, h) + aoff + m * 2048 + k * 1024); } while (0)
; #define PG8_MMA(ai, bj, At, Bt) do { __builtin_amdgcn_s_setprio(1); _Pragma("unroll") for (int m = 0; m < 4; ++m) _Pragma("unroll") for (int n = 0; n < 2; ++n) _Pragma("unroll") for (int k = 0; k < 2; ++k) \
;         acc[ai][bj][m][n] = __builtin_amdgcn_mfma_f32_16x16x32_bf16(Bt[n][k], At[m][k], acc[ai][bj][m][n], 0, 0, 0); __builtin_amdgcn_s_setprio(0); } while (0)
; #define PG8_WAIT_V(n) asm volatile("s_waitcnt vmcnt(" #n ")" ::: "memory")
; #define PG8_WAIT_L(n) asm volatile("s_waitcnt lgkmcnt(" #n ")" ::: "memory")
; #define PG8_BAR __builtin_amdgcn_s_barrier()
; #define PG8_SCHED __builtin_amdgcn_sched_barrier(0)
; template <class Epi, class Sched>
; __device__ __forceinline__ void gemm_phase(LAS unsigned char* lds, const Gemm g, const Sched& S, const Epi& E) {
;     ...
;             PG8_LDA(At, 1, 1); PG8_STAGE(PG8_SB(1, 0), b3, voffB); PG8_STAGE(PG8_SB(1, 1), b3 + hB, voffB); PG8_STAGE(PG8_SA(1, 0), a3, voffA);
;             PG8_WAIT_V(8); PG8_WAIT_L(0); PG8_BAR; PG8_MMA(1, 0, At, B0); PG8_MMA(1, 1, At, B1); PG8_BAR; PG8_SCHED;
;         }
;         if (wr == 0) PG8_BAR;
	s_add_i32 s20, s47, s28
	v_lshl_add_u64 v[226:227], v[226:227], 0, s[76:77]
	s_mov_b32 m0, s20
	ds_read_b128 v[182:185], v224 offset:49152
	ds_read_b128 v[186:189], v224 offset:50176
	ds_read_b128 v[190:193], v224 offset:51200
	ds_read_b128 v[194:197], v224 offset:52224
	ds_read_b128 v[198:201], v224 offset:53248
	ds_read_b128 v[202:205], v224 offset:54272
	ds_read_b128 v[206:209], v224 offset:55296
	ds_read_b128 v[210:213], v224 offset:56320
	global_load_lds_dwordx4 v[226:227], off
	s_add_i32 m0, s20, 0x2000
	s_add_u32 s20, s22, 0x58080
	v_lshl_add_u64 v[226:227], v[228:229], 0, s[76:77]
	s_addc_u32 s21, s23, 0
	s_add_i32 s22, s48, s28
	global_load_lds_dwordx4 v[226:227], off
	v_lshl_add_u64 v[226:227], s[20:21], 0, v[158:159]
	s_mov_b32 m0, s22
	s_nop 0
	global_load_lds_dwordx4 v[226:227], off
	v_lshl_add_u64 v[226:227], s[20:21], 0, v[144:145]
	s_add_i32 m0, s22, 0x2000
	s_nop 0
	global_load_lds_dwordx4 v[226:227], off
	v_lshl_add_u64 v[226:227], v[230:231], 0, s[82:83]
	s_mov_b32 m0, s36
	s_nop 0
	global_load_lds_dwordx4 v[226:227], off
	v_lshl_add_u64 v[226:227], v[232:233], 0, s[82:83]
	s_mov_b32 m0, s37
	s_nop 0
	global_load_lds_dwordx4 v[226:227], off
	s_waitcnt vmcnt(8)
	s_waitcnt lgkmcnt(0)
	s_barrier
	s_setprio 1
	s_waitcnt lgkmcnt(0)
	v_mfma_f32_16x16x32_bf16 v[62:65], v[132:135], v[182:185], v[62:65]
	v_mfma_f32_16x16x32_bf16 v[58:61], v[140:143], v[182:185], v[58:61]
	v_mfma_f32_16x16x32_bf16 v[46:49], v[132:135], v[190:193], v[46:49]
	v_mfma_f32_16x16x32_bf16 v[42:45], v[140:143], v[190:193], v[42:45]
	v_mfma_f32_16x16x32_bf16 v[30:33], v[132:135], v[198:201], v[30:33]
	v_mfma_f32_16x16x32_bf16 v[26:29], v[140:143], v[198:201], v[26:29]
	v_mfma_f32_16x16x32_bf16 v[14:17], v[132:135], v[206:209], v[14:17]
	v_mfma_f32_16x16x32_bf16 v[10:13], v[140:143], v[206:209], v[10:13]
	v_mfma_f32_16x16x32_bf16 v[62:65], v[136:139], v[186:189], v[62:65]
	v_mfma_f32_16x16x32_bf16 v[58:61], v[154:157], v[186:189], v[58:61]
	v_mfma_f32_16x16x32_bf16 v[46:49], v[136:139], v[194:197], v[46:49]
	v_mfma_f32_16x16x32_bf16 v[42:45], v[154:157], v[194:197], v[42:45]
	v_mfma_f32_16x16x32_bf16 v[30:33], v[136:139], v[202:205], v[30:33]
	v_mfma_f32_16x16x32_bf16 v[26:29], v[154:157], v[202:205], v[26:29]
	v_mfma_f32_16x16x32_bf16 v[14:17], v[136:139], v[210:213], v[14:17]
	v_mfma_f32_16x16x32_bf16 v[10:13], v[154:157], v[210:213], v[10:13]
	v_mfma_f32_16x16x32_bf16 v[54:57], v[166:169], v[182:185], v[54:57]
	v_mfma_f32_16x16x32_bf16 v[50:53], v[174:177], v[182:185], v[50:53]
	v_mfma_f32_16x16x32_bf16 v[38:41], v[166:169], v[190:193], v[38:41]
	v_mfma_f32_16x16x32_bf16 v[34:37], v[174:177], v[190:193], v[34:37]
	v_mfma_f32_16x16x32_bf16 v[22:25], v[166:169], v[198:201], v[22:25]
	v_mfma_f32_16x16x32_bf16 v[18:21], v[174:177], v[198:201], v[18:21]
	v_mfma_f32_16x16x32_bf16 v[6:9], v[166:169], v[206:209], v[6:9]
	v_mfma_f32_16x16x32_bf16 v[2:5], v[174:177], v[206:209], v[2:5]
	v_mfma_f32_16x16x32_bf16 v[54:57], v[170:173], v[186:189], v[54:57]
	v_mfma_f32_16x16x32_bf16 v[50:53], v[178:181], v[186:189], v[50:53]
	v_mfma_f32_16x16x32_bf16 v[38:41], v[170:173], v[194:197], v[38:41]
	v_mfma_f32_16x16x32_bf16 v[34:37], v[178:181], v[194:197], v[34:37]
	v_mfma_f32_16x16x32_bf16 v[22:25], v[170:173], v[202:205], v[22:25]
	v_mfma_f32_16x16x32_bf16 v[18:21], v[178:181], v[202:205], v[18:21]
	v_mfma_f32_16x16x32_bf16 v[6:9], v[170:173], v[210:213], v[6:9]
	v_mfma_f32_16x16x32_bf16 v[2:5], v[178:181], v[210:213], v[2:5]
	s_setprio 0
	s_barrier
	s_add_i32 s46, s46, 2
	s_add_u32 s42, s42, 0x100
	s_addc_u32 s43, s43, 0
	s_cmpk_gt_u32 s46, 0x55
	s_mov_b64 s[20:21], s[2:3]
	s_cbranch_scc0 .LBB0_1048
	s_and_b64 vcc, exec, s[16:17]
	s_cbranch_vccz .LBB0_1051
	s_barrier
